# K-loop: all load segments at setprio 2
# baseline (speedup 1.0000x reference)
.LBB0_322:
	s_ashr_i32 s43, s42, 31
	s_lshl_b64 s[46:47], s[42:43], 19
	s_add_u32 s46, s12, s46
	s_addc_u32 s47, s13, s47
	s_and_b64 s[48:49], s[4:5], exec
	s_cselect_b32 s18, s47, s7
	s_cselect_b32 s43, s46, s6
	s_ashr_i32 s45, s44, 31
	s_lshl_b64 s[48:49], s[44:45], 19
	s_add_u32 s48, s59, s48
	s_addc_u32 s49, s60, s49
	s_and_b64 s[50:51], s[4:5], exec
	s_cselect_b32 s45, s49, s9
	s_cselect_b32 s55, s48, s8
	s_add_u32 s6, s6, 0x40080
	s_addc_u32 s7, s7, 0
	s_add_u32 s56, s8, 0x100
	s_addc_u32 s57, s9, 0
	s_mov_b32 s78, -2
	ds_read_b128 v[96:99], v209
	ds_read_b128 v[100:103], v209 offset:1024
	ds_read_b128 v[120:123], v209 offset:2048
	ds_read_b128 v[124:127], v209 offset:3072
	ds_read_b128 v[144:147], v210
	ds_read_b128 v[148:151], v210 offset:1024
	ds_read_b128 v[152:155], v210 offset:2048
	ds_read_b128 v[156:159], v210 offset:3072
	s_add_u32 s8, s6, 0xfffc0080
	s_addc_u32 s9, s7, -1
	s_cmp_eq_u32 s78, 12
	s_cselect_b32 s51, s18, s9
	s_cselect_b32 s50, s43, s8
	s_cselect_b32 s9, s45, s57
	s_cselect_b32 s8, s55, s56
	v_lshl_add_u64 v[206:207], s[6:7], 0, v[170:171]
	s_add_i32 m0, s17, 0xc000
	ds_read_b128 v[178:181], v211
	ds_read_b128 v[182:185], v211 offset:1024
	ds_read_b128 v[186:189], v211 offset:2048
	ds_read_b128 v[190:193], v211 offset:3072
	ds_read_b128 v[194:197], v211 offset:4096
	ds_read_b128 v[198:201], v211 offset:5120
	ds_read_b128 v[202:205], v211 offset:6144
	ds_read_b128 v[218:221], v211 offset:7168
	global_load_lds_dwordx4 v[206:207], off
	s_add_i32 m0, s17, 0xe000
	v_lshl_add_u64 v[206:207], s[6:7], 0, v[172:173]
	global_load_lds_dwordx4 v[206:207], off
	s_waitcnt vmcnt(8)
	s_waitcnt lgkmcnt(0)
	s_barrier
	s_setprio 1
	s_waitcnt lgkmcnt(0)
	v_mfma_f32_16x16x32_bf16 v[140:143], v[96:99], v[178:181], 0
	v_mfma_f32_16x16x32_bf16 v[136:139], v[120:123], v[178:181], 0
	v_mfma_f32_16x16x32_bf16 v[116:119], v[96:99], v[186:189], 0
	v_mfma_f32_16x16x32_bf16 v[112:115], v[120:123], v[186:189], 0
	v_mfma_f32_16x16x32_bf16 v[92:95], v[96:99], v[194:197], 0
	v_mfma_f32_16x16x32_bf16 v[88:91], v[120:123], v[194:197], 0
	v_mfma_f32_16x16x32_bf16 v[76:79], v[96:99], v[202:205], 0
	v_mfma_f32_16x16x32_bf16 v[72:75], v[120:123], v[202:205], 0
	v_mfma_f32_16x16x32_bf16 v[140:143], v[100:103], v[182:185], v[140:143]
	v_mfma_f32_16x16x32_bf16 v[136:139], v[124:127], v[182:185], v[136:139]
	v_mfma_f32_16x16x32_bf16 v[116:119], v[100:103], v[190:193], v[116:119]
	v_mfma_f32_16x16x32_bf16 v[112:115], v[124:127], v[190:193], v[112:115]
	v_mfma_f32_16x16x32_bf16 v[92:95], v[100:103], v[198:201], v[92:95]
	v_mfma_f32_16x16x32_bf16 v[88:91], v[124:127], v[198:201], v[88:91]
	v_mfma_f32_16x16x32_bf16 v[76:79], v[100:103], v[218:221], v[76:79]
	v_mfma_f32_16x16x32_bf16 v[72:75], v[124:127], v[218:221], v[72:75]
	s_setprio 0
	s_setprio 1
	v_mfma_f32_16x16x32_bf16 v[132:135], v[144:147], v[178:181], 0
	v_mfma_f32_16x16x32_bf16 v[128:131], v[152:155], v[178:181], 0
	v_mfma_f32_16x16x32_bf16 v[108:111], v[144:147], v[186:189], 0
	v_mfma_f32_16x16x32_bf16 v[104:107], v[152:155], v[186:189], 0
	v_mfma_f32_16x16x32_bf16 v[84:87], v[144:147], v[194:197], 0
	v_mfma_f32_16x16x32_bf16 v[80:83], v[152:155], v[194:197], 0
	v_mfma_f32_16x16x32_bf16 v[68:71], v[144:147], v[202:205], 0
	v_mfma_f32_16x16x32_bf16 v[64:67], v[152:155], v[202:205], 0
	v_mfma_f32_16x16x32_bf16 v[132:135], v[148:151], v[182:185], v[132:135]
	v_mfma_f32_16x16x32_bf16 v[128:131], v[156:159], v[182:185], v[128:131]
	v_mfma_f32_16x16x32_bf16 v[108:111], v[148:151], v[190:193], v[108:111]
	v_mfma_f32_16x16x32_bf16 v[104:107], v[156:159], v[190:193], v[104:107]
	s_setprio 2
	s_barrier
	v_mfma_f32_16x16x32_bf16 v[84:87], v[148:151], v[198:201], v[84:87]
	v_mfma_f32_16x16x32_bf16 v[80:83], v[156:159], v[198:201], v[80:83]
	v_mfma_f32_16x16x32_bf16 v[68:71], v[148:151], v[218:221], v[68:71]
	v_mfma_f32_16x16x32_bf16 v[64:67], v[156:159], v[218:221], v[64:67]
	s_setprio 2
	s_add_i32 s79, s73, s61
	v_lshl_add_u64 v[206:207], s[8:9], 0, v[162:163]
	s_mov_b32 m0, s79
	ds_read_b128 v[178:181], v211 offset:16384
	ds_read_b128 v[182:185], v211 offset:17408
	ds_read_b128 v[186:189], v211 offset:18432
	ds_read_b128 v[190:193], v211 offset:19456
	ds_read_b128 v[194:197], v211 offset:20480
	ds_read_b128 v[198:201], v211 offset:21504
	ds_read_b128 v[202:205], v211 offset:22528
	ds_read_b128 v[218:221], v211 offset:23552
	global_load_lds_dwordx4 v[206:207], off
	s_add_i32 m0, s79, 0x2000
	s_add_u32 s80, s8, 0x40000
	v_lshl_add_u64 v[222:223], s[8:9], 0, v[166:167]
	s_addc_u32 s81, s9, 0
	s_add_i32 s79, s74, s61
	global_load_lds_dwordx4 v[222:223], off
	v_lshl_add_u64 v[224:225], s[80:81], 0, v[162:163]
	s_mov_b32 m0, s79
	v_lshl_add_u64 v[226:227], s[50:51], 0, v[164:165]
	global_load_lds_dwordx4 v[224:225], off
	s_add_i32 m0, s79, 0x2000
	v_lshl_add_u64 v[224:225], s[80:81], 0, v[166:167]
	global_load_lds_dwordx4 v[224:225], off
	s_mov_b32 m0, s17
	v_lshl_add_u64 v[224:225], s[50:51], 0, v[160:161]
	global_load_lds_dwordx4 v[224:225], off
	s_mov_b32 m0, s62
	s_nop 0
	global_load_lds_dwordx4 v[226:227], off
	s_waitcnt vmcnt(8)
	s_waitcnt lgkmcnt(0)
	s_barrier
	s_setprio 1
	s_waitcnt lgkmcnt(0)
	v_mfma_f32_16x16x32_bf16 v[60:63], v[96:99], v[178:181], 0
	v_mfma_f32_16x16x32_bf16 v[56:59], v[120:123], v[178:181], 0
	v_mfma_f32_16x16x32_bf16 v[44:47], v[96:99], v[186:189], 0
	v_mfma_f32_16x16x32_bf16 v[40:43], v[120:123], v[186:189], 0
	v_mfma_f32_16x16x32_bf16 v[28:31], v[96:99], v[194:197], 0
	v_mfma_f32_16x16x32_bf16 v[24:27], v[120:123], v[194:197], 0
	v_mfma_f32_16x16x32_bf16 v[12:15], v[96:99], v[202:205], 0
	v_mfma_f32_16x16x32_bf16 v[8:11], v[120:123], v[202:205], 0
	v_mfma_f32_16x16x32_bf16 v[60:63], v[100:103], v[182:185], v[60:63]
	v_mfma_f32_16x16x32_bf16 v[56:59], v[124:127], v[182:185], v[56:59]
	v_mfma_f32_16x16x32_bf16 v[44:47], v[100:103], v[190:193], v[44:47]
	v_mfma_f32_16x16x32_bf16 v[40:43], v[124:127], v[190:193], v[40:43]
	v_mfma_f32_16x16x32_bf16 v[28:31], v[100:103], v[198:201], v[28:31]
	v_mfma_f32_16x16x32_bf16 v[24:27], v[124:127], v[198:201], v[24:27]
	v_mfma_f32_16x16x32_bf16 v[12:15], v[100:103], v[218:221], v[12:15]
	v_mfma_f32_16x16x32_bf16 v[8:11], v[124:127], v[218:221], v[8:11]
	s_setprio 0
	s_setprio 1
	v_mfma_f32_16x16x32_bf16 v[52:55], v[144:147], v[178:181], 0
	v_mfma_f32_16x16x32_bf16 v[48:51], v[152:155], v[178:181], 0
	v_mfma_f32_16x16x32_bf16 v[36:39], v[144:147], v[186:189], 0
	v_mfma_f32_16x16x32_bf16 v[32:35], v[152:155], v[186:189], 0
	v_mfma_f32_16x16x32_bf16 v[20:23], v[144:147], v[194:197], 0
	v_mfma_f32_16x16x32_bf16 v[16:19], v[152:155], v[194:197], 0
	v_mfma_f32_16x16x32_bf16 v[4:7], v[144:147], v[202:205], 0
	v_mfma_f32_16x16x32_bf16 v[0:3], v[152:155], v[202:205], 0
	v_mfma_f32_16x16x32_bf16 v[52:55], v[148:151], v[182:185], v[52:55]
	v_mfma_f32_16x16x32_bf16 v[48:51], v[156:159], v[182:185], v[48:51]
	v_mfma_f32_16x16x32_bf16 v[36:39], v[148:151], v[190:193], v[36:39]
	v_mfma_f32_16x16x32_bf16 v[32:35], v[156:159], v[190:193], v[32:35]
	s_setprio 2
	s_barrier
	v_mfma_f32_16x16x32_bf16 v[20:23], v[148:151], v[198:201], v[20:23]
	v_mfma_f32_16x16x32_bf16 v[16:19], v[156:159], v[198:201], v[16:19]
	v_mfma_f32_16x16x32_bf16 v[4:7], v[148:151], v[218:221], v[4:7]
	v_mfma_f32_16x16x32_bf16 v[0:3], v[156:159], v[218:221], v[0:3]
	s_setprio 2
	s_add_i32 s79, 0, 0x18000
	s_add_i32 s80, 0, 0x1c000
	v_add_u32_e32 v124, s79, v208
	v_add_u32_e32 v156, s80, v208
	ds_read_b128 v[96:99], v124
	ds_read_b128 v[100:103], v124 offset:1024
	ds_read_b128 v[120:123], v124 offset:2048
	ds_read_b128 v[124:127], v124 offset:3072
	ds_read_b128 v[144:147], v156
	ds_read_b128 v[148:151], v156 offset:1024
	ds_read_b128 v[152:155], v156 offset:2048
	ds_read_b128 v[156:159], v156 offset:3072
	s_add_u32 s50, s50, 0x40000
	s_addc_u32 s51, s51, 0
	s_mov_b32 m0, s63
	v_lshl_add_u64 v[228:229], s[50:51], 0, v[160:161]
	ds_read_b128 v[178:181], v211 offset:32768
	ds_read_b128 v[182:185], v211 offset:33792
	ds_read_b128 v[186:189], v211 offset:34816
	ds_read_b128 v[190:193], v211 offset:35840
	ds_read_b128 v[194:197], v211 offset:36864
	ds_read_b128 v[198:201], v211 offset:37888
	ds_read_b128 v[202:205], v211 offset:38912
	ds_read_b128 v[218:221], v211 offset:39936
	global_load_lds_dwordx4 v[228:229], off
	s_mov_b32 m0, s64
	v_lshl_add_u64 v[228:229], s[50:51], 0, v[164:165]
	global_load_lds_dwordx4 v[228:229], off
	s_waitcnt vmcnt(8)
	s_waitcnt lgkmcnt(0)
	s_barrier
	s_setprio 1
	s_waitcnt lgkmcnt(0)
	v_mfma_f32_16x16x32_bf16 v[140:143], v[96:99], v[178:181], v[140:143]
	v_mfma_f32_16x16x32_bf16 v[136:139], v[120:123], v[178:181], v[136:139]
	v_mfma_f32_16x16x32_bf16 v[116:119], v[96:99], v[186:189], v[116:119]
	v_mfma_f32_16x16x32_bf16 v[112:115], v[120:123], v[186:189], v[112:115]
	v_mfma_f32_16x16x32_bf16 v[92:95], v[96:99], v[194:197], v[92:95]
	v_mfma_f32_16x16x32_bf16 v[88:91], v[120:123], v[194:197], v[88:91]
	v_mfma_f32_16x16x32_bf16 v[76:79], v[96:99], v[202:205], v[76:79]
	v_mfma_f32_16x16x32_bf16 v[72:75], v[120:123], v[202:205], v[72:75]
	v_mfma_f32_16x16x32_bf16 v[140:143], v[100:103], v[182:185], v[140:143]
	v_mfma_f32_16x16x32_bf16 v[136:139], v[124:127], v[182:185], v[136:139]
	v_mfma_f32_16x16x32_bf16 v[116:119], v[100:103], v[190:193], v[116:119]
	v_mfma_f32_16x16x32_bf16 v[112:115], v[124:127], v[190:193], v[112:115]
	v_mfma_f32_16x16x32_bf16 v[92:95], v[100:103], v[198:201], v[92:95]
	v_mfma_f32_16x16x32_bf16 v[88:91], v[124:127], v[198:201], v[88:91]
	v_mfma_f32_16x16x32_bf16 v[76:79], v[100:103], v[218:221], v[76:79]
	v_mfma_f32_16x16x32_bf16 v[72:75], v[124:127], v[218:221], v[72:75]
	s_setprio 0
	s_setprio 1
	v_mfma_f32_16x16x32_bf16 v[132:135], v[144:147], v[178:181], v[132:135]
	v_mfma_f32_16x16x32_bf16 v[128:131], v[152:155], v[178:181], v[128:131]
	v_mfma_f32_16x16x32_bf16 v[108:111], v[144:147], v[186:189], v[108:111]
	v_mfma_f32_16x16x32_bf16 v[104:107], v[152:155], v[186:189], v[104:107]
	v_mfma_f32_16x16x32_bf16 v[84:87], v[144:147], v[194:197], v[84:87]
	v_mfma_f32_16x16x32_bf16 v[80:83], v[152:155], v[194:197], v[80:83]
	v_mfma_f32_16x16x32_bf16 v[68:71], v[144:147], v[202:205], v[68:71]
	v_mfma_f32_16x16x32_bf16 v[64:67], v[152:155], v[202:205], v[64:67]
	v_mfma_f32_16x16x32_bf16 v[132:135], v[148:151], v[182:185], v[132:135]
	v_mfma_f32_16x16x32_bf16 v[128:131], v[156:159], v[182:185], v[128:131]
	v_mfma_f32_16x16x32_bf16 v[108:111], v[148:151], v[190:193], v[108:111]
	v_mfma_f32_16x16x32_bf16 v[104:107], v[156:159], v[190:193], v[104:107]
	s_setprio 2
	s_barrier
	v_mfma_f32_16x16x32_bf16 v[84:87], v[148:151], v[198:201], v[84:87]
	v_mfma_f32_16x16x32_bf16 v[80:83], v[156:159], v[198:201], v[80:83]
	v_mfma_f32_16x16x32_bf16 v[68:71], v[148:151], v[218:221], v[68:71]
	v_mfma_f32_16x16x32_bf16 v[64:67], v[156:159], v[218:221], v[64:67]
	s_setprio 2
	s_add_i32 s50, s79, s61
	v_lshl_add_u64 v[206:207], v[206:207], 0, s[36:37]
	s_mov_b32 m0, s50
	ds_read_b128 v[178:181], v211 offset:49152
	ds_read_b128 v[182:185], v211 offset:50176
	ds_read_b128 v[186:189], v211 offset:51200
	ds_read_b128 v[190:193], v211 offset:52224
	ds_read_b128 v[194:197], v211 offset:53248
	ds_read_b128 v[198:201], v211 offset:54272
	ds_read_b128 v[202:205], v211 offset:55296
	ds_read_b128 v[218:221], v211 offset:56320
	global_load_lds_dwordx4 v[206:207], off
	s_add_i32 m0, s50, 0x2000
	s_add_u32 s8, s8, 0x40080
	v_lshl_add_u64 v[206:207], v[222:223], 0, s[36:37]
	s_addc_u32 s9, s9, 0
	s_add_i32 s50, s80, s61
	global_load_lds_dwordx4 v[206:207], off
	s_mov_b32 m0, s50
	v_lshl_add_u64 v[206:207], s[8:9], 0, v[162:163]
	global_load_lds_dwordx4 v[206:207], off
	s_add_i32 m0, s50, 0x2000
	v_lshl_add_u64 v[206:207], s[8:9], 0, v[166:167]
	global_load_lds_dwordx4 v[206:207], off
	s_mov_b32 m0, s68
	v_lshl_add_u64 v[206:207], v[224:225], 0, s[36:37]
	global_load_lds_dwordx4 v[206:207], off
	s_mov_b32 m0, s69
	v_lshl_add_u64 v[206:207], v[226:227], 0, s[36:37]
	global_load_lds_dwordx4 v[206:207], off
	s_waitcnt vmcnt(8)
	s_waitcnt lgkmcnt(0)
	s_barrier
	s_setprio 1
	s_waitcnt lgkmcnt(0)
	v_mfma_f32_16x16x32_bf16 v[60:63], v[96:99], v[178:181], v[60:63]
	v_mfma_f32_16x16x32_bf16 v[56:59], v[120:123], v[178:181], v[56:59]
	v_mfma_f32_16x16x32_bf16 v[44:47], v[96:99], v[186:189], v[44:47]
	v_mfma_f32_16x16x32_bf16 v[40:43], v[120:123], v[186:189], v[40:43]
	v_mfma_f32_16x16x32_bf16 v[28:31], v[96:99], v[194:197], v[28:31]
	v_mfma_f32_16x16x32_bf16 v[24:27], v[120:123], v[194:197], v[24:27]
	v_mfma_f32_16x16x32_bf16 v[12:15], v[96:99], v[202:205], v[12:15]
	v_mfma_f32_16x16x32_bf16 v[8:11], v[120:123], v[202:205], v[8:11]
	v_mfma_f32_16x16x32_bf16 v[60:63], v[100:103], v[182:185], v[60:63]
	v_mfma_f32_16x16x32_bf16 v[56:59], v[124:127], v[182:185], v[56:59]
	v_mfma_f32_16x16x32_bf16 v[44:47], v[100:103], v[190:193], v[44:47]
	v_mfma_f32_16x16x32_bf16 v[40:43], v[124:127], v[190:193], v[40:43]
	v_mfma_f32_16x16x32_bf16 v[28:31], v[100:103], v[198:201], v[28:31]
	v_mfma_f32_16x16x32_bf16 v[24:27], v[124:127], v[198:201], v[24:27]
	v_mfma_f32_16x16x32_bf16 v[12:15], v[100:103], v[218:221], v[12:15]
	v_mfma_f32_16x16x32_bf16 v[8:11], v[124:127], v[218:221], v[8:11]
	s_setprio 0
	s_setprio 1
	v_mfma_f32_16x16x32_bf16 v[52:55], v[144:147], v[178:181], v[52:55]
	v_mfma_f32_16x16x32_bf16 v[48:51], v[152:155], v[178:181], v[48:51]
	v_mfma_f32_16x16x32_bf16 v[36:39], v[144:147], v[186:189], v[36:39]
	v_mfma_f32_16x16x32_bf16 v[32:35], v[152:155], v[186:189], v[32:35]
	v_mfma_f32_16x16x32_bf16 v[20:23], v[144:147], v[194:197], v[20:23]
	v_mfma_f32_16x16x32_bf16 v[16:19], v[152:155], v[194:197], v[16:19]
	v_mfma_f32_16x16x32_bf16 v[4:7], v[144:147], v[202:205], v[4:7]
	v_mfma_f32_16x16x32_bf16 v[0:3], v[152:155], v[202:205], v[0:3]
	v_mfma_f32_16x16x32_bf16 v[52:55], v[148:151], v[182:185], v[52:55]
	v_mfma_f32_16x16x32_bf16 v[48:51], v[156:159], v[182:185], v[48:51]
	v_mfma_f32_16x16x32_bf16 v[36:39], v[148:151], v[190:193], v[36:39]
	v_mfma_f32_16x16x32_bf16 v[32:35], v[156:159], v[190:193], v[32:35]
	s_setprio 2
	s_barrier
	v_mfma_f32_16x16x32_bf16 v[20:23], v[148:151], v[198:201], v[20:23]
	v_mfma_f32_16x16x32_bf16 v[16:19], v[156:159], v[198:201], v[16:19]
	v_mfma_f32_16x16x32_bf16 v[4:7], v[148:151], v[218:221], v[4:7]
	v_mfma_f32_16x16x32_bf16 v[0:3], v[156:159], v[218:221], v[0:3]
	s_setprio 2
	s_add_i32 s78, s78, 2
	s_add_u32 s6, s6, 0x100
	s_addc_u32 s7, s7, 0
	s_add_u32 s56, s56, 0x100
	s_addc_u32 s57, s57, 0
	s_cmp_gt_u32 s78, 13
.LBB0_323:
	ds_read_b128 v[96:99], v209
	ds_read_b128 v[100:103], v209 offset:1024
	ds_read_b128 v[120:123], v209 offset:2048
	ds_read_b128 v[124:127], v209 offset:3072
	ds_read_b128 v[144:147], v210
	ds_read_b128 v[148:151], v210 offset:1024
	ds_read_b128 v[152:155], v210 offset:2048
	ds_read_b128 v[156:159], v210 offset:3072
	s_add_u32 s8, s6, 0xfffc0080
	s_addc_u32 s9, s7, -1
	s_cmp_eq_u32 s78, 12
	s_cselect_b32 s51, s18, s9
	s_cselect_b32 s50, s43, s8
	s_cselect_b32 s9, s45, s57
	s_cselect_b32 s8, s55, s56
	v_lshl_add_u64 v[206:207], s[6:7], 0, v[170:171]
	s_add_i32 m0, s17, 0xc000
	ds_read_b128 v[178:181], v211
	ds_read_b128 v[182:185], v211 offset:1024
	ds_read_b128 v[186:189], v211 offset:2048
	ds_read_b128 v[190:193], v211 offset:3072
	ds_read_b128 v[194:197], v211 offset:4096
	ds_read_b128 v[198:201], v211 offset:5120
	ds_read_b128 v[202:205], v211 offset:6144
	ds_read_b128 v[218:221], v211 offset:7168
	global_load_lds_dwordx4 v[206:207], off
	s_add_i32 m0, s17, 0xe000
	v_lshl_add_u64 v[206:207], s[6:7], 0, v[172:173]
	global_load_lds_dwordx4 v[206:207], off
	s_waitcnt vmcnt(8)
	s_waitcnt lgkmcnt(0)
	s_barrier
	s_setprio 1
	s_waitcnt lgkmcnt(0)
	v_mfma_f32_16x16x32_bf16 v[140:143], v[96:99], v[178:181], v[140:143]
	v_mfma_f32_16x16x32_bf16 v[136:139], v[120:123], v[178:181], v[136:139]
	v_mfma_f32_16x16x32_bf16 v[116:119], v[96:99], v[186:189], v[116:119]
	v_mfma_f32_16x16x32_bf16 v[112:115], v[120:123], v[186:189], v[112:115]
	v_mfma_f32_16x16x32_bf16 v[92:95], v[96:99], v[194:197], v[92:95]
	v_mfma_f32_16x16x32_bf16 v[88:91], v[120:123], v[194:197], v[88:91]
	v_mfma_f32_16x16x32_bf16 v[76:79], v[96:99], v[202:205], v[76:79]
	v_mfma_f32_16x16x32_bf16 v[72:75], v[120:123], v[202:205], v[72:75]
	v_mfma_f32_16x16x32_bf16 v[140:143], v[100:103], v[182:185], v[140:143]
	v_mfma_f32_16x16x32_bf16 v[136:139], v[124:127], v[182:185], v[136:139]
	v_mfma_f32_16x16x32_bf16 v[116:119], v[100:103], v[190:193], v[116:119]
	v_mfma_f32_16x16x32_bf16 v[112:115], v[124:127], v[190:193], v[112:115]
	v_mfma_f32_16x16x32_bf16 v[92:95], v[100:103], v[198:201], v[92:95]
	v_mfma_f32_16x16x32_bf16 v[88:91], v[124:127], v[198:201], v[88:91]
	v_mfma_f32_16x16x32_bf16 v[76:79], v[100:103], v[218:221], v[76:79]
	v_mfma_f32_16x16x32_bf16 v[72:75], v[124:127], v[218:221], v[72:75]
	s_setprio 0
	s_setprio 1
	v_mfma_f32_16x16x32_bf16 v[132:135], v[144:147], v[178:181], v[132:135]
	v_mfma_f32_16x16x32_bf16 v[128:131], v[152:155], v[178:181], v[128:131]
	v_mfma_f32_16x16x32_bf16 v[108:111], v[144:147], v[186:189], v[108:111]
	v_mfma_f32_16x16x32_bf16 v[104:107], v[152:155], v[186:189], v[104:107]
	v_mfma_f32_16x16x32_bf16 v[84:87], v[144:147], v[194:197], v[84:87]
	v_mfma_f32_16x16x32_bf16 v[80:83], v[152:155], v[194:197], v[80:83]
	v_mfma_f32_16x16x32_bf16 v[68:71], v[144:147], v[202:205], v[68:71]
	v_mfma_f32_16x16x32_bf16 v[64:67], v[152:155], v[202:205], v[64:67]
	v_mfma_f32_16x16x32_bf16 v[132:135], v[148:151], v[182:185], v[132:135]
	v_mfma_f32_16x16x32_bf16 v[128:131], v[156:159], v[182:185], v[128:131]
	v_mfma_f32_16x16x32_bf16 v[108:111], v[148:151], v[190:193], v[108:111]
	v_mfma_f32_16x16x32_bf16 v[104:107], v[156:159], v[190:193], v[104:107]
	s_setprio 2
	s_barrier
	v_mfma_f32_16x16x32_bf16 v[84:87], v[148:151], v[198:201], v[84:87]
	v_mfma_f32_16x16x32_bf16 v[80:83], v[156:159], v[198:201], v[80:83]
	v_mfma_f32_16x16x32_bf16 v[68:71], v[148:151], v[218:221], v[68:71]
	v_mfma_f32_16x16x32_bf16 v[64:67], v[156:159], v[218:221], v[64:67]
	s_setprio 2
	s_add_i32 s79, s73, s61
	v_lshl_add_u64 v[206:207], s[8:9], 0, v[162:163]
	s_mov_b32 m0, s79
	ds_read_b128 v[178:181], v211 offset:16384
	ds_read_b128 v[182:185], v211 offset:17408
	ds_read_b128 v[186:189], v211 offset:18432
	ds_read_b128 v[190:193], v211 offset:19456
	ds_read_b128 v[194:197], v211 offset:20480
	ds_read_b128 v[198:201], v211 offset:21504
	ds_read_b128 v[202:205], v211 offset:22528
	ds_read_b128 v[218:221], v211 offset:23552
	global_load_lds_dwordx4 v[206:207], off
	s_add_i32 m0, s79, 0x2000
	s_add_u32 s80, s8, 0x40000
	v_lshl_add_u64 v[222:223], s[8:9], 0, v[166:167]
	s_addc_u32 s81, s9, 0
	s_add_i32 s79, s74, s61
	global_load_lds_dwordx4 v[222:223], off
	v_lshl_add_u64 v[224:225], s[80:81], 0, v[162:163]
	s_mov_b32 m0, s79
	v_lshl_add_u64 v[226:227], s[50:51], 0, v[164:165]
	global_load_lds_dwordx4 v[224:225], off
	s_add_i32 m0, s79, 0x2000
	v_lshl_add_u64 v[224:225], s[80:81], 0, v[166:167]
	global_load_lds_dwordx4 v[224:225], off
	s_mov_b32 m0, s17
	v_lshl_add_u64 v[224:225], s[50:51], 0, v[160:161]
	global_load_lds_dwordx4 v[224:225], off
	s_mov_b32 m0, s62
	s_nop 0
	global_load_lds_dwordx4 v[226:227], off
	s_waitcnt vmcnt(8)
	s_waitcnt lgkmcnt(0)
	s_barrier
	s_setprio 1
	s_waitcnt lgkmcnt(0)
	v_mfma_f32_16x16x32_bf16 v[60:63], v[96:99], v[178:181], v[60:63]
	v_mfma_f32_16x16x32_bf16 v[56:59], v[120:123], v[178:181], v[56:59]
	v_mfma_f32_16x16x32_bf16 v[44:47], v[96:99], v[186:189], v[44:47]
	v_mfma_f32_16x16x32_bf16 v[40:43], v[120:123], v[186:189], v[40:43]
	v_mfma_f32_16x16x32_bf16 v[28:31], v[96:99], v[194:197], v[28:31]
	v_mfma_f32_16x16x32_bf16 v[24:27], v[120:123], v[194:197], v[24:27]
	v_mfma_f32_16x16x32_bf16 v[12:15], v[96:99], v[202:205], v[12:15]
	v_mfma_f32_16x16x32_bf16 v[8:11], v[120:123], v[202:205], v[8:11]
	v_mfma_f32_16x16x32_bf16 v[60:63], v[100:103], v[182:185], v[60:63]
	v_mfma_f32_16x16x32_bf16 v[56:59], v[124:127], v[182:185], v[56:59]
	v_mfma_f32_16x16x32_bf16 v[44:47], v[100:103], v[190:193], v[44:47]
	v_mfma_f32_16x16x32_bf16 v[40:43], v[124:127], v[190:193], v[40:43]
	v_mfma_f32_16x16x32_bf16 v[28:31], v[100:103], v[198:201], v[28:31]
	v_mfma_f32_16x16x32_bf16 v[24:27], v[124:127], v[198:201], v[24:27]
	v_mfma_f32_16x16x32_bf16 v[12:15], v[100:103], v[218:221], v[12:15]
	v_mfma_f32_16x16x32_bf16 v[8:11], v[124:127], v[218:221], v[8:11]
	s_setprio 0
	s_setprio 1
	v_mfma_f32_16x16x32_bf16 v[52:55], v[144:147], v[178:181], v[52:55]
	v_mfma_f32_16x16x32_bf16 v[48:51], v[152:155], v[178:181], v[48:51]
	v_mfma_f32_16x16x32_bf16 v[36:39], v[144:147], v[186:189], v[36:39]
	v_mfma_f32_16x16x32_bf16 v[32:35], v[152:155], v[186:189], v[32:35]
	v_mfma_f32_16x16x32_bf16 v[20:23], v[144:147], v[194:197], v[20:23]
	v_mfma_f32_16x16x32_bf16 v[16:19], v[152:155], v[194:197], v[16:19]
	v_mfma_f32_16x16x32_bf16 v[4:7], v[144:147], v[202:205], v[4:7]
	v_mfma_f32_16x16x32_bf16 v[0:3], v[152:155], v[202:205], v[0:3]
	v_mfma_f32_16x16x32_bf16 v[52:55], v[148:151], v[182:185], v[52:55]
	v_mfma_f32_16x16x32_bf16 v[48:51], v[156:159], v[182:185], v[48:51]
	v_mfma_f32_16x16x32_bf16 v[36:39], v[148:151], v[190:193], v[36:39]
	v_mfma_f32_16x16x32_bf16 v[32:35], v[156:159], v[190:193], v[32:35]
	s_setprio 2
	s_barrier
	v_mfma_f32_16x16x32_bf16 v[20:23], v[148:151], v[198:201], v[20:23]
	v_mfma_f32_16x16x32_bf16 v[16:19], v[156:159], v[198:201], v[16:19]
	v_mfma_f32_16x16x32_bf16 v[4:7], v[148:151], v[218:221], v[4:7]
	v_mfma_f32_16x16x32_bf16 v[0:3], v[156:159], v[218:221], v[0:3]
	s_setprio 2
	s_add_i32 s79, 0, 0x18000
	s_add_i32 s80, 0, 0x1c000
	v_add_u32_e32 v124, s79, v208
	v_add_u32_e32 v156, s80, v208
	ds_read_b128 v[96:99], v124
	ds_read_b128 v[100:103], v124 offset:1024
	ds_read_b128 v[120:123], v124 offset:2048
	ds_read_b128 v[124:127], v124 offset:3072
	ds_read_b128 v[144:147], v156
	ds_read_b128 v[148:151], v156 offset:1024
	ds_read_b128 v[152:155], v156 offset:2048
	ds_read_b128 v[156:159], v156 offset:3072
	s_add_u32 s50, s50, 0x40000
	s_addc_u32 s51, s51, 0
	s_mov_b32 m0, s63
	v_lshl_add_u64 v[228:229], s[50:51], 0, v[160:161]
	ds_read_b128 v[178:181], v211 offset:32768
	ds_read_b128 v[182:185], v211 offset:33792
	ds_read_b128 v[186:189], v211 offset:34816
	ds_read_b128 v[190:193], v211 offset:35840
	ds_read_b128 v[194:197], v211 offset:36864
	ds_read_b128 v[198:201], v211 offset:37888
	ds_read_b128 v[202:205], v211 offset:38912
	ds_read_b128 v[218:221], v211 offset:39936
	global_load_lds_dwordx4 v[228:229], off
	s_mov_b32 m0, s64
	v_lshl_add_u64 v[228:229], s[50:51], 0, v[164:165]
	global_load_lds_dwordx4 v[228:229], off
	s_waitcnt vmcnt(8)
	s_waitcnt lgkmcnt(0)
	s_barrier
	s_setprio 1
	s_waitcnt lgkmcnt(0)
	v_mfma_f32_16x16x32_bf16 v[140:143], v[96:99], v[178:181], v[140:143]
	v_mfma_f32_16x16x32_bf16 v[136:139], v[120:123], v[178:181], v[136:139]
	v_mfma_f32_16x16x32_bf16 v[116:119], v[96:99], v[186:189], v[116:119]
	v_mfma_f32_16x16x32_bf16 v[112:115], v[120:123], v[186:189], v[112:115]
	v_mfma_f32_16x16x32_bf16 v[92:95], v[96:99], v[194:197], v[92:95]
	v_mfma_f32_16x16x32_bf16 v[88:91], v[120:123], v[194:197], v[88:91]
	v_mfma_f32_16x16x32_bf16 v[76:79], v[96:99], v[202:205], v[76:79]
	v_mfma_f32_16x16x32_bf16 v[72:75], v[120:123], v[202:205], v[72:75]
	v_mfma_f32_16x16x32_bf16 v[140:143], v[100:103], v[182:185], v[140:143]
	v_mfma_f32_16x16x32_bf16 v[136:139], v[124:127], v[182:185], v[136:139]
	v_mfma_f32_16x16x32_bf16 v[116:119], v[100:103], v[190:193], v[116:119]
	v_mfma_f32_16x16x32_bf16 v[112:115], v[124:127], v[190:193], v[112:115]
	v_mfma_f32_16x16x32_bf16 v[92:95], v[100:103], v[198:201], v[92:95]
	v_mfma_f32_16x16x32_bf16 v[88:91], v[124:127], v[198:201], v[88:91]
	v_mfma_f32_16x16x32_bf16 v[76:79], v[100:103], v[218:221], v[76:79]
	v_mfma_f32_16x16x32_bf16 v[72:75], v[124:127], v[218:221], v[72:75]
	s_setprio 0
	s_setprio 1
	v_mfma_f32_16x16x32_bf16 v[132:135], v[144:147], v[178:181], v[132:135]
	v_mfma_f32_16x16x32_bf16 v[128:131], v[152:155], v[178:181], v[128:131]
	v_mfma_f32_16x16x32_bf16 v[108:111], v[144:147], v[186:189], v[108:111]
	v_mfma_f32_16x16x32_bf16 v[104:107], v[152:155], v[186:189], v[104:107]
	v_mfma_f32_16x16x32_bf16 v[84:87], v[144:147], v[194:197], v[84:87]
	v_mfma_f32_16x16x32_bf16 v[80:83], v[152:155], v[194:197], v[80:83]
	v_mfma_f32_16x16x32_bf16 v[68:71], v[144:147], v[202:205], v[68:71]
	v_mfma_f32_16x16x32_bf16 v[64:67], v[152:155], v[202:205], v[64:67]
	v_mfma_f32_16x16x32_bf16 v[132:135], v[148:151], v[182:185], v[132:135]
	v_mfma_f32_16x16x32_bf16 v[128:131], v[156:159], v[182:185], v[128:131]
	v_mfma_f32_16x16x32_bf16 v[108:111], v[148:151], v[190:193], v[108:111]
	v_mfma_f32_16x16x32_bf16 v[104:107], v[156:159], v[190:193], v[104:107]
	s_setprio 2
	s_barrier
	v_mfma_f32_16x16x32_bf16 v[84:87], v[148:151], v[198:201], v[84:87]
	v_mfma_f32_16x16x32_bf16 v[80:83], v[156:159], v[198:201], v[80:83]
	v_mfma_f32_16x16x32_bf16 v[68:71], v[148:151], v[218:221], v[68:71]
	v_mfma_f32_16x16x32_bf16 v[64:67], v[156:159], v[218:221], v[64:67]
	s_setprio 2
	s_add_i32 s50, s79, s61
	v_lshl_add_u64 v[206:207], v[206:207], 0, s[36:37]
	s_mov_b32 m0, s50
	ds_read_b128 v[178:181], v211 offset:49152
	ds_read_b128 v[182:185], v211 offset:50176
	ds_read_b128 v[186:189], v211 offset:51200
	ds_read_b128 v[190:193], v211 offset:52224
	ds_read_b128 v[194:197], v211 offset:53248
	ds_read_b128 v[198:201], v211 offset:54272
	ds_read_b128 v[202:205], v211 offset:55296
	ds_read_b128 v[218:221], v211 offset:56320
	global_load_lds_dwordx4 v[206:207], off
	s_add_i32 m0, s50, 0x2000
	s_add_u32 s8, s8, 0x40080
	v_lshl_add_u64 v[206:207], v[222:223], 0, s[36:37]
	s_addc_u32 s9, s9, 0
	s_add_i32 s50, s80, s61
	global_load_lds_dwordx4 v[206:207], off
	s_mov_b32 m0, s50
	v_lshl_add_u64 v[206:207], s[8:9], 0, v[162:163]
	global_load_lds_dwordx4 v[206:207], off
	s_add_i32 m0, s50, 0x2000
	v_lshl_add_u64 v[206:207], s[8:9], 0, v[166:167]
	global_load_lds_dwordx4 v[206:207], off
	s_mov_b32 m0, s68
	v_lshl_add_u64 v[206:207], v[224:225], 0, s[36:37]
	global_load_lds_dwordx4 v[206:207], off
	s_mov_b32 m0, s69
	v_lshl_add_u64 v[206:207], v[226:227], 0, s[36:37]
	global_load_lds_dwordx4 v[206:207], off
	s_waitcnt vmcnt(8)
	s_waitcnt lgkmcnt(0)
	s_barrier
	s_setprio 1
	s_waitcnt lgkmcnt(0)
	v_mfma_f32_16x16x32_bf16 v[60:63], v[96:99], v[178:181], v[60:63]
	v_mfma_f32_16x16x32_bf16 v[56:59], v[120:123], v[178:181], v[56:59]
	v_mfma_f32_16x16x32_bf16 v[44:47], v[96:99], v[186:189], v[44:47]
	v_mfma_f32_16x16x32_bf16 v[40:43], v[120:123], v[186:189], v[40:43]
	v_mfma_f32_16x16x32_bf16 v[28:31], v[96:99], v[194:197], v[28:31]
	v_mfma_f32_16x16x32_bf16 v[24:27], v[120:123], v[194:197], v[24:27]
	v_mfma_f32_16x16x32_bf16 v[12:15], v[96:99], v[202:205], v[12:15]
	v_mfma_f32_16x16x32_bf16 v[8:11], v[120:123], v[202:205], v[8:11]
	v_mfma_f32_16x16x32_bf16 v[60:63], v[100:103], v[182:185], v[60:63]
	v_mfma_f32_16x16x32_bf16 v[56:59], v[124:127], v[182:185], v[56:59]
	v_mfma_f32_16x16x32_bf16 v[44:47], v[100:103], v[190:193], v[44:47]
	v_mfma_f32_16x16x32_bf16 v[40:43], v[124:127], v[190:193], v[40:43]
	v_mfma_f32_16x16x32_bf16 v[28:31], v[100:103], v[198:201], v[28:31]
	v_mfma_f32_16x16x32_bf16 v[24:27], v[124:127], v[198:201], v[24:27]
	v_mfma_f32_16x16x32_bf16 v[12:15], v[100:103], v[218:221], v[12:15]
	v_mfma_f32_16x16x32_bf16 v[8:11], v[124:127], v[218:221], v[8:11]
	s_setprio 0
	s_setprio 1
	v_mfma_f32_16x16x32_bf16 v[52:55], v[144:147], v[178:181], v[52:55]
	v_mfma_f32_16x16x32_bf16 v[48:51], v[152:155], v[178:181], v[48:51]
	v_mfma_f32_16x16x32_bf16 v[36:39], v[144:147], v[186:189], v[36:39]
	v_mfma_f32_16x16x32_bf16 v[32:35], v[152:155], v[186:189], v[32:35]
	v_mfma_f32_16x16x32_bf16 v[20:23], v[144:147], v[194:197], v[20:23]
	v_mfma_f32_16x16x32_bf16 v[16:19], v[152:155], v[194:197], v[16:19]
	v_mfma_f32_16x16x32_bf16 v[4:7], v[144:147], v[202:205], v[4:7]
	v_mfma_f32_16x16x32_bf16 v[0:3], v[152:155], v[202:205], v[0:3]
	v_mfma_f32_16x16x32_bf16 v[52:55], v[148:151], v[182:185], v[52:55]
	v_mfma_f32_16x16x32_bf16 v[48:51], v[156:159], v[182:185], v[48:51]
	v_mfma_f32_16x16x32_bf16 v[36:39], v[148:151], v[190:193], v[36:39]
	v_mfma_f32_16x16x32_bf16 v[32:35], v[156:159], v[190:193], v[32:35]
	s_setprio 2
	s_barrier
	v_mfma_f32_16x16x32_bf16 v[20:23], v[148:151], v[198:201], v[20:23]
	v_mfma_f32_16x16x32_bf16 v[16:19], v[156:159], v[198:201], v[16:19]
	v_mfma_f32_16x16x32_bf16 v[4:7], v[148:151], v[218:221], v[4:7]
	v_mfma_f32_16x16x32_bf16 v[0:3], v[156:159], v[218:221], v[0:3]
	s_setprio 0
	s_add_i32 s78, s78, 2
	s_add_u32 s6, s6, 0x100
	s_addc_u32 s7, s7, 0
	s_add_u32 s56, s56, 0x100
	s_addc_u32 s57, s57, 0
	s_cmp_gt_u32 s78, 13
	s_cbranch_scc0 .LBB0_323

.LBB0_697:
	s_and_b32 s29, s69, 0x1000
	s_add_i32 s70, s66, s29
	s_ashr_i32 s29, s28, 31
	ds_read_b128 v[0:3], v195 offset:3072
	ds_read_b128 v[4:7], v195 offset:2048
	ds_read_b128 v[8:11], v195 offset:1024
	ds_read_b128 v[12:15], v195
	ds_read_b128 v[16:19], v203 offset:3072
	ds_read_b128 v[20:23], v203 offset:2048
	ds_read_b128 v[24:27], v203 offset:1024
	ds_read_b128 v[28:31], v203
	s_lshl_b64 s[36:37], s[28:29], 20
	s_add_u32 s36, s50, s36
	s_addc_u32 s37, s51, s37
	s_and_b64 s[38:39], s[4:5], exec
	s_cselect_b32 s29, s37, s45
	s_cselect_b32 s71, s36, s44
	s_ashr_i32 s31, s30, 31
	s_lshl_b64 s[38:39], s[30:31], 20
	s_add_u32 s38, s54, s38
	s_addc_u32 s39, s55, s39
	s_and_b64 s[48:49], s[4:5], exec
	s_cselect_b32 s31, s39, s47
	s_cselect_b32 s72, s38, s46
	s_add_u32 s48, s44, 0x80080
	s_addc_u32 s49, s45, 0
	s_add_i32 s73, s56, 0xc000
	v_lshl_add_u64 v[64:65], s[48:49], 0, v[176:177]
	s_mov_b32 m0, s73
	s_add_i32 s74, s56, 0xe000
	ds_read_b128 v[32:35], v211
	ds_read_b128 v[36:39], v211 offset:1024
	ds_read_b128 v[40:43], v211 offset:2048
	ds_read_b128 v[44:47], v211 offset:3072
	ds_read_b128 v[48:51], v211 offset:4096
	ds_read_b128 v[52:55], v211 offset:5120
	ds_read_b128 v[56:59], v211 offset:6144
	ds_read_b128 v[60:63], v211 offset:7168
	global_load_lds_dwordx4 v[64:65], off
	s_mov_b32 m0, s74
	v_lshl_add_u64 v[64:65], s[48:49], 0, v[178:179]
	global_load_lds_dwordx4 v[64:65], off
	s_waitcnt vmcnt(8)
	s_waitcnt lgkmcnt(0)
	s_barrier
	s_setprio 1
	s_waitcnt lgkmcnt(0)
	v_mfma_f32_16x16x32_bf16 v[88:91], v[28:31], v[56:59], 0
	v_mfma_f32_16x16x32_bf16 v[64:67], v[28:31], v[32:35], 0
	v_mfma_f32_16x16x32_bf16 v[68:71], v[20:23], v[32:35], 0
	v_mfma_f32_16x16x32_bf16 v[72:75], v[28:31], v[40:43], 0
	v_mfma_f32_16x16x32_bf16 v[76:79], v[20:23], v[40:43], 0
	v_mfma_f32_16x16x32_bf16 v[80:83], v[28:31], v[48:51], 0
	v_mfma_f32_16x16x32_bf16 v[84:87], v[20:23], v[48:51], 0
	v_mfma_f32_16x16x32_bf16 v[96:99], v[24:27], v[60:63], v[88:91]
	v_mfma_f32_16x16x32_bf16 v[88:91], v[20:23], v[56:59], 0
	v_mfma_f32_16x16x32_bf16 v[64:67], v[24:27], v[36:39], v[64:67]
	v_mfma_f32_16x16x32_bf16 v[68:71], v[16:19], v[36:39], v[68:71]
	v_mfma_f32_16x16x32_bf16 v[72:75], v[24:27], v[44:47], v[72:75]
	v_mfma_f32_16x16x32_bf16 v[76:79], v[16:19], v[44:47], v[76:79]
	v_mfma_f32_16x16x32_bf16 v[80:83], v[24:27], v[52:55], v[80:83]
	v_mfma_f32_16x16x32_bf16 v[84:87], v[16:19], v[52:55], v[84:87]
	v_mfma_f32_16x16x32_bf16 v[100:103], v[16:19], v[60:63], v[88:91]
	s_setprio 0
	s_setprio 1
	v_mfma_f32_16x16x32_bf16 v[88:91], v[12:15], v[32:35], 0
	v_mfma_f32_16x16x32_bf16 v[32:35], v[4:7], v[32:35], 0
	v_mfma_f32_16x16x32_bf16 v[112:115], v[8:11], v[36:39], v[88:91]
	v_mfma_f32_16x16x32_bf16 v[32:35], v[0:3], v[36:39], v[32:35]
	v_mfma_f32_16x16x32_bf16 v[36:39], v[12:15], v[40:43], 0
	v_mfma_f32_16x16x32_bf16 v[40:43], v[4:7], v[40:43], 0
	v_mfma_f32_16x16x32_bf16 v[36:39], v[8:11], v[44:47], v[36:39]
	v_mfma_f32_16x16x32_bf16 v[40:43], v[0:3], v[44:47], v[40:43]
	v_mfma_f32_16x16x32_bf16 v[44:47], v[12:15], v[48:51], 0
	v_mfma_f32_16x16x32_bf16 v[48:51], v[4:7], v[48:51], 0
	v_mfma_f32_16x16x32_bf16 v[44:47], v[8:11], v[52:55], v[44:47]
	v_mfma_f32_16x16x32_bf16 v[48:51], v[0:3], v[52:55], v[48:51]
	s_setprio 2
	s_barrier
	v_mfma_f32_16x16x32_bf16 v[52:55], v[12:15], v[56:59], 0
	v_mfma_f32_16x16x32_bf16 v[56:59], v[4:7], v[56:59], 0
	v_mfma_f32_16x16x32_bf16 v[52:55], v[8:11], v[60:63], v[52:55]
	v_mfma_f32_16x16x32_bf16 v[56:59], v[0:3], v[60:63], v[56:59]
	s_setprio 2
	s_add_i32 s75, s68, s43
	v_lshl_add_u64 v[174:175], s[46:47], 0, v[176:177]
	s_add_i32 s76, s75, 0x2000
	v_lshl_add_u64 v[128:129], v[174:175], 0, s[24:25]
	s_mov_b32 m0, s75
	v_lshl_add_u64 v[200:201], s[46:47], 0, v[178:179]
	s_add_u32 s48, s46, 0x80100
	ds_read_b128 v[60:63], v211 offset:16384
	ds_read_b128 v[88:91], v211 offset:17408
	ds_read_b128 v[92:95], v211 offset:18432
	ds_read_b128 v[104:107], v211 offset:19456
	ds_read_b128 v[108:111], v211 offset:20480
	ds_read_b128 v[116:119], v211 offset:21504
	ds_read_b128 v[120:123], v211 offset:22528
	ds_read_b128 v[124:127], v211 offset:23552
	global_load_lds_dwordx4 v[128:129], off
	v_lshl_add_u64 v[128:129], v[200:201], 0, s[24:25]
	s_mov_b32 m0, s76
	s_addc_u32 s49, s47, 0
	s_add_i32 s77, s67, s43
	global_load_lds_dwordx4 v[128:129], off
	v_lshl_add_u64 v[128:129], s[48:49], 0, v[176:177]
	s_mov_b32 m0, s77
	s_add_i32 s78, s77, 0x2000
	global_load_lds_dwordx4 v[128:129], off
	v_lshl_add_u64 v[128:129], s[48:49], 0, v[178:179]
	s_mov_b32 m0, s78
	v_lshl_add_u64 v[208:209], s[44:45], 0, v[176:177]
	global_load_lds_dwordx4 v[128:129], off
	v_lshl_add_u64 v[128:129], v[208:209], 0, s[24:25]
	s_mov_b32 m0, s56
	v_lshl_add_u64 v[252:253], s[44:45], 0, v[178:179]
	global_load_lds_dwordx4 v[128:129], off
	s_mov_b32 m0, s57
	v_lshl_add_u64 v[128:129], v[252:253], 0, s[24:25]
	global_load_lds_dwordx4 v[128:129], off
	s_waitcnt vmcnt(8)
	s_waitcnt lgkmcnt(0)
	s_barrier
	s_setprio 1
	s_waitcnt lgkmcnt(0)
	v_mfma_f32_16x16x32_bf16 v[134:137], v[20:23], v[60:63], 0
	v_mfma_f32_16x16x32_bf16 v[142:145], v[20:23], v[92:95], 0
	v_mfma_f32_16x16x32_bf16 v[150:153], v[20:23], v[108:111], 0
	v_mfma_f32_16x16x32_bf16 v[20:23], v[20:23], v[120:123], 0
	v_mfma_f32_16x16x32_bf16 v[128:131], v[28:31], v[60:63], 0
	v_mfma_f32_16x16x32_bf16 v[134:137], v[16:19], v[88:91], v[134:137]
	v_mfma_f32_16x16x32_bf16 v[138:141], v[28:31], v[92:95], 0
	v_mfma_f32_16x16x32_bf16 v[142:145], v[16:19], v[104:107], v[142:145]
	v_mfma_f32_16x16x32_bf16 v[146:149], v[28:31], v[108:111], 0
	v_mfma_f32_16x16x32_bf16 v[150:153], v[16:19], v[116:119], v[150:153]
	v_mfma_f32_16x16x32_bf16 v[28:31], v[28:31], v[120:123], 0
	v_mfma_f32_16x16x32_bf16 v[16:19], v[16:19], v[124:127], v[20:23]
	v_mfma_f32_16x16x32_bf16 v[130:133], v[24:27], v[88:91], v[128:131]
	v_mfma_f32_16x16x32_bf16 v[138:141], v[24:27], v[104:107], v[138:141]
	v_mfma_f32_16x16x32_bf16 v[146:149], v[24:27], v[116:119], v[146:149]
	v_mfma_f32_16x16x32_bf16 v[154:157], v[24:27], v[124:127], v[28:31]
	s_setprio 0
	s_setprio 1
	v_mfma_f32_16x16x32_bf16 v[24:27], v[4:7], v[60:63], 0
	v_mfma_f32_16x16x32_bf16 v[158:161], v[0:3], v[88:91], v[24:27]
	v_mfma_f32_16x16x32_bf16 v[24:27], v[12:15], v[92:95], 0
	v_mfma_f32_16x16x32_bf16 v[162:165], v[8:11], v[104:107], v[24:27]
	v_mfma_f32_16x16x32_bf16 v[24:27], v[4:7], v[92:95], 0
	v_mfma_f32_16x16x32_bf16 v[166:169], v[0:3], v[104:107], v[24:27]
	v_mfma_f32_16x16x32_bf16 v[24:27], v[12:15], v[108:111], 0
	v_mfma_f32_16x16x32_bf16 v[20:23], v[12:15], v[60:63], 0
	v_mfma_f32_16x16x32_bf16 v[170:173], v[8:11], v[116:119], v[24:27]
	v_mfma_f32_16x16x32_bf16 v[24:27], v[4:7], v[108:111], 0
	v_mfma_f32_16x16x32_bf16 v[4:7], v[4:7], v[120:123], 0
	v_mfma_f32_16x16x32_bf16 v[20:23], v[8:11], v[88:91], v[20:23]
	s_setprio 2
	s_barrier
	v_mfma_f32_16x16x32_bf16 v[190:193], v[0:3], v[116:119], v[24:27]
	v_mfma_f32_16x16x32_bf16 v[12:15], v[12:15], v[120:123], 0
	v_mfma_f32_16x16x32_bf16 v[0:3], v[0:3], v[124:127], v[4:7]
	v_mfma_f32_16x16x32_bf16 v[196:199], v[8:11], v[124:127], v[12:15]
	s_setprio 2
	s_add_i32 s79, 0, 0x18000
	s_add_i32 s81, 0, 0x1c000
	v_add_u32_e32 v128, s79, v189
	v_add_u32_e32 v129, s81, v189
	ds_read_b128 v[4:7], v128
	ds_read_b128 v[8:11], v128 offset:1024
	ds_read_b128 v[204:207], v128 offset:2048
	ds_read_b128 v[212:215], v128 offset:3072
	ds_read_b128 v[216:219], v129
	ds_read_b128 v[220:223], v129 offset:1024
	ds_read_b128 v[224:227], v129 offset:2048
	ds_read_b128 v[228:231], v129 offset:3072
	s_add_u32 s48, s44, 0x80100
	s_addc_u32 s49, s45, 0
	s_mov_b32 m0, s58
	v_lshl_add_u64 v[88:89], s[48:49], 0, v[176:177]
	ds_read_b128 v[12:15], v211 offset:32768
	ds_read_b128 v[24:27], v211 offset:33792
	ds_read_b128 v[28:31], v211 offset:34816
	ds_read_b128 v[60:63], v211 offset:35840
	ds_read_b128 v[232:235], v211 offset:36864
	ds_read_b128 v[236:239], v211 offset:37888
	ds_read_b128 v[240:243], v211 offset:38912
	ds_read_b128 v[244:247], v211 offset:39936
	global_load_lds_dwordx4 v[88:89], off
	s_mov_b32 m0, s59
	v_lshl_add_u64 v[88:89], s[48:49], 0, v[178:179]
	global_load_lds_dwordx4 v[88:89], off
	s_waitcnt vmcnt(8)
	s_waitcnt lgkmcnt(0)
	s_barrier
	s_setprio 1
	s_waitcnt lgkmcnt(0)
	v_mfma_f32_16x16x32_bf16 v[64:67], v[4:7], v[12:15], v[64:67]
	v_mfma_f32_16x16x32_bf16 v[124:127], v[8:11], v[24:27], v[64:67]
	v_mfma_f32_16x16x32_bf16 v[64:67], v[204:207], v[12:15], v[68:71]
	v_mfma_f32_16x16x32_bf16 v[120:123], v[212:215], v[24:27], v[64:67]
	v_mfma_f32_16x16x32_bf16 v[64:67], v[4:7], v[28:31], v[72:75]
	v_mfma_f32_16x16x32_bf16 v[108:111], v[8:11], v[60:63], v[64:67]
	v_mfma_f32_16x16x32_bf16 v[64:67], v[204:207], v[28:31], v[76:79]
	v_mfma_f32_16x16x32_bf16 v[104:107], v[212:215], v[60:63], v[64:67]
	v_mfma_f32_16x16x32_bf16 v[64:67], v[4:7], v[232:235], v[80:83]
	v_mfma_f32_16x16x32_bf16 v[92:95], v[8:11], v[236:239], v[64:67]
	v_mfma_f32_16x16x32_bf16 v[64:67], v[204:207], v[232:235], v[84:87]
	v_mfma_f32_16x16x32_bf16 v[88:91], v[212:215], v[236:239], v[64:67]
	v_mfma_f32_16x16x32_bf16 v[64:67], v[4:7], v[240:243], v[96:99]
	v_mfma_f32_16x16x32_bf16 v[76:79], v[8:11], v[244:247], v[64:67]
	v_mfma_f32_16x16x32_bf16 v[64:67], v[204:207], v[240:243], v[100:103]
	v_mfma_f32_16x16x32_bf16 v[72:75], v[212:215], v[244:247], v[64:67]
	s_setprio 0
	s_setprio 1
	v_mfma_f32_16x16x32_bf16 v[64:67], v[216:219], v[12:15], v[112:115]
	v_mfma_f32_16x16x32_bf16 v[12:15], v[224:227], v[12:15], v[32:35]
	v_mfma_f32_16x16x32_bf16 v[112:115], v[228:231], v[24:27], v[12:15]
	v_mfma_f32_16x16x32_bf16 v[12:15], v[216:219], v[28:31], v[36:39]
	v_mfma_f32_16x16x32_bf16 v[100:103], v[220:223], v[60:63], v[12:15]
	v_mfma_f32_16x16x32_bf16 v[12:15], v[224:227], v[28:31], v[40:43]
	v_mfma_f32_16x16x32_bf16 v[96:99], v[228:231], v[60:63], v[12:15]
	v_mfma_f32_16x16x32_bf16 v[12:15], v[216:219], v[232:235], v[44:47]
	v_mfma_f32_16x16x32_bf16 v[84:87], v[220:223], v[236:239], v[12:15]
	v_mfma_f32_16x16x32_bf16 v[12:15], v[224:227], v[232:235], v[48:51]
	v_mfma_f32_16x16x32_bf16 v[80:83], v[228:231], v[236:239], v[12:15]
	v_mfma_f32_16x16x32_bf16 v[12:15], v[216:219], v[240:243], v[52:55]
	s_setprio 2
	s_barrier
	v_mfma_f32_16x16x32_bf16 v[68:71], v[220:223], v[244:247], v[12:15]
	v_mfma_f32_16x16x32_bf16 v[12:15], v[224:227], v[240:243], v[56:59]
	v_mfma_f32_16x16x32_bf16 v[116:119], v[220:223], v[24:27], v[64:67]
	v_mfma_f32_16x16x32_bf16 v[64:67], v[228:231], v[244:247], v[12:15]
	s_setprio 2
	s_add_i32 s79, s79, s43
	s_add_i32 s80, s79, 0x2000
	s_nop 1
	v_lshl_add_u64 v[12:13], v[174:175], 0, s[26:27]
	s_mov_b32 m0, s79
	s_add_u32 s48, s46, 0x80180
	ds_read_b128 v[32:35], v211 offset:49152
	ds_read_b128 v[36:39], v211 offset:50176
	ds_read_b128 v[232:235], v211 offset:51200
	ds_read_b128 v[236:239], v211 offset:52224
	ds_read_b128 v[240:243], v211 offset:53248
	ds_read_b128 v[244:247], v211 offset:54272
	ds_read_b128 v[248:251], v211 offset:55296
	ds_read_b128 v[184:187], v211 offset:56320
	global_load_lds_dwordx4 v[12:13], off
	v_lshl_add_u64 v[12:13], v[200:201], 0, s[26:27]
	s_mov_b32 m0, s80
	s_addc_u32 s49, s47, 0
	s_add_i32 s81, s81, s43
	global_load_lds_dwordx4 v[12:13], off
	v_lshl_add_u64 v[12:13], s[48:49], 0, v[176:177]
	s_mov_b32 m0, s81
	s_add_i32 s82, s81, 0x2000
	global_load_lds_dwordx4 v[12:13], off
	s_mov_b32 m0, s82
	v_lshl_add_u64 v[12:13], s[48:49], 0, v[178:179]
	global_load_lds_dwordx4 v[12:13], off
	s_mov_b32 m0, s61
	v_lshl_add_u64 v[12:13], v[208:209], 0, s[26:27]
	global_load_lds_dwordx4 v[12:13], off
	s_mov_b32 m0, s62
	v_lshl_add_u64 v[12:13], v[252:253], 0, s[26:27]
	global_load_lds_dwordx4 v[12:13], off
	s_waitcnt vmcnt(8)
	s_waitcnt lgkmcnt(0)
	s_barrier
	s_setprio 1
	s_waitcnt lgkmcnt(0)
	v_mfma_f32_16x16x32_bf16 v[12:15], v[4:7], v[32:35], v[130:133]
	v_mfma_f32_16x16x32_bf16 v[60:63], v[8:11], v[36:39], v[12:15]
	v_mfma_f32_16x16x32_bf16 v[12:15], v[204:207], v[32:35], v[134:137]
	v_mfma_f32_16x16x32_bf16 v[56:59], v[212:215], v[36:39], v[12:15]
	v_mfma_f32_16x16x32_bf16 v[12:15], v[4:7], v[232:235], v[138:141]
	v_mfma_f32_16x16x32_bf16 v[44:47], v[8:11], v[236:239], v[12:15]
	v_mfma_f32_16x16x32_bf16 v[12:15], v[204:207], v[232:235], v[142:145]
	v_mfma_f32_16x16x32_bf16 v[40:43], v[212:215], v[236:239], v[12:15]
	v_mfma_f32_16x16x32_bf16 v[12:15], v[4:7], v[240:243], v[146:149]
	v_mfma_f32_16x16x32_bf16 v[28:31], v[8:11], v[244:247], v[12:15]
	v_mfma_f32_16x16x32_bf16 v[12:15], v[204:207], v[240:243], v[150:153]
	v_mfma_f32_16x16x32_bf16 v[4:7], v[4:7], v[248:251], v[154:157]
	v_mfma_f32_16x16x32_bf16 v[24:27], v[212:215], v[244:247], v[12:15]
	v_mfma_f32_16x16x32_bf16 v[12:15], v[8:11], v[184:187], v[4:7]
	v_mfma_f32_16x16x32_bf16 v[4:7], v[204:207], v[248:251], v[16:19]
	v_mfma_f32_16x16x32_bf16 v[8:11], v[212:215], v[184:187], v[4:7]
	s_setprio 0
	s_setprio 1
	v_mfma_f32_16x16x32_bf16 v[4:7], v[216:219], v[32:35], v[20:23]
	v_mfma_f32_16x16x32_bf16 v[52:55], v[220:223], v[36:39], v[4:7]
	v_mfma_f32_16x16x32_bf16 v[4:7], v[224:227], v[32:35], v[158:161]
	v_mfma_f32_16x16x32_bf16 v[48:51], v[228:231], v[36:39], v[4:7]
	v_mfma_f32_16x16x32_bf16 v[4:7], v[216:219], v[232:235], v[162:165]
	v_mfma_f32_16x16x32_bf16 v[36:39], v[220:223], v[236:239], v[4:7]
	v_mfma_f32_16x16x32_bf16 v[4:7], v[224:227], v[232:235], v[166:169]
	v_mfma_f32_16x16x32_bf16 v[32:35], v[228:231], v[236:239], v[4:7]
	v_mfma_f32_16x16x32_bf16 v[4:7], v[216:219], v[240:243], v[170:173]
	v_mfma_f32_16x16x32_bf16 v[20:23], v[220:223], v[244:247], v[4:7]
	v_mfma_f32_16x16x32_bf16 v[4:7], v[224:227], v[240:243], v[190:193]
	v_mfma_f32_16x16x32_bf16 v[16:19], v[228:231], v[244:247], v[4:7]
	s_setprio 2
	s_barrier
	v_mfma_f32_16x16x32_bf16 v[4:7], v[216:219], v[248:251], v[196:199]
	v_mfma_f32_16x16x32_bf16 v[0:3], v[224:227], v[248:251], v[0:3]
	v_mfma_f32_16x16x32_bf16 v[4:7], v[220:223], v[184:187], v[4:7]
	v_mfma_f32_16x16x32_bf16 v[0:3], v[228:231], v[184:187], v[0:3]
	s_setprio 2
	s_add_u32 s44, s44, 0x80180
	s_addc_u32 s45, s45, 0
	s_add_u32 s83, s46, 0x200
	s_addc_u32 s84, s47, 0
	s_mov_b32 s46, 0
	s_add_i32 s85, s46, 2
	s_and_b32 s47, s85, 6
	s_cmp_lg_u32 s47, 0
	s_cbranch_scc1 .LBB0_700
	s_branch .LBB0_699

.LBB0_700:
	ds_read_b128 v[130:133], v203
	ds_read_b128 v[134:137], v203 offset:1024
	ds_read_b128 v[138:141], v203 offset:2048
	ds_read_b128 v[142:145], v203 offset:3072
	ds_read_b128 v[146:149], v195
	ds_read_b128 v[150:153], v195 offset:1024
	ds_read_b128 v[154:157], v195 offset:2048
	ds_read_b128 v[158:161], v195 offset:3072
	s_add_u32 s47, s44, 0xfff80080
	s_addc_u32 s48, s45, -1
	s_cmp_eq_u32 s46, 28
	s_cselect_b32 s49, s29, s48
	s_cselect_b32 s48, s71, s47
	s_cselect_b32 s47, s31, s84
	s_cselect_b32 s46, s72, s83
	s_mov_b32 m0, s73
	v_lshl_add_u64 v[174:175], s[44:45], 0, v[180:181]
	ds_read_b128 v[162:165], v211
	ds_read_b128 v[166:169], v211 offset:1024
	ds_read_b128 v[170:173], v211 offset:2048
	ds_read_b128 v[184:187], v211 offset:3072
	ds_read_b128 v[190:193], v211 offset:4096
	ds_read_b128 v[196:199], v211 offset:5120
	ds_read_b128 v[204:207], v211 offset:6144
	ds_read_b128 v[212:215], v211 offset:7168
	global_load_lds_dwordx4 v[174:175], off
	s_mov_b32 m0, s74
	v_lshl_add_u64 v[174:175], s[44:45], 0, v[182:183]
	global_load_lds_dwordx4 v[174:175], off
	s_waitcnt vmcnt(8)
	s_waitcnt lgkmcnt(0)
	s_barrier
	s_setprio 1
	s_waitcnt lgkmcnt(0)
	v_mfma_f32_16x16x32_bf16 v[124:127], v[130:133], v[162:165], v[124:127]
	v_mfma_f32_16x16x32_bf16 v[120:123], v[138:141], v[162:165], v[120:123]
	v_mfma_f32_16x16x32_bf16 v[108:111], v[130:133], v[170:173], v[108:111]
	v_mfma_f32_16x16x32_bf16 v[104:107], v[138:141], v[170:173], v[104:107]
	v_mfma_f32_16x16x32_bf16 v[92:95], v[130:133], v[190:193], v[92:95]
	v_mfma_f32_16x16x32_bf16 v[88:91], v[138:141], v[190:193], v[88:91]
	v_mfma_f32_16x16x32_bf16 v[76:79], v[130:133], v[204:207], v[76:79]
	v_mfma_f32_16x16x32_bf16 v[72:75], v[138:141], v[204:207], v[72:75]
	v_mfma_f32_16x16x32_bf16 v[124:127], v[134:137], v[166:169], v[124:127]
	v_mfma_f32_16x16x32_bf16 v[120:123], v[142:145], v[166:169], v[120:123]
	v_mfma_f32_16x16x32_bf16 v[108:111], v[134:137], v[184:187], v[108:111]
	v_mfma_f32_16x16x32_bf16 v[104:107], v[142:145], v[184:187], v[104:107]
	v_mfma_f32_16x16x32_bf16 v[92:95], v[134:137], v[196:199], v[92:95]
	v_mfma_f32_16x16x32_bf16 v[88:91], v[142:145], v[196:199], v[88:91]
	v_mfma_f32_16x16x32_bf16 v[76:79], v[134:137], v[212:215], v[76:79]
	v_mfma_f32_16x16x32_bf16 v[72:75], v[142:145], v[212:215], v[72:75]
	s_setprio 0
	s_setprio 1
	v_mfma_f32_16x16x32_bf16 v[116:119], v[146:149], v[162:165], v[116:119]
	v_mfma_f32_16x16x32_bf16 v[112:115], v[154:157], v[162:165], v[112:115]
	v_mfma_f32_16x16x32_bf16 v[100:103], v[146:149], v[170:173], v[100:103]
	v_mfma_f32_16x16x32_bf16 v[96:99], v[154:157], v[170:173], v[96:99]
	v_mfma_f32_16x16x32_bf16 v[84:87], v[146:149], v[190:193], v[84:87]
	v_mfma_f32_16x16x32_bf16 v[80:83], v[154:157], v[190:193], v[80:83]
	v_mfma_f32_16x16x32_bf16 v[68:71], v[146:149], v[204:207], v[68:71]
	v_mfma_f32_16x16x32_bf16 v[64:67], v[154:157], v[204:207], v[64:67]
	v_mfma_f32_16x16x32_bf16 v[116:119], v[150:153], v[166:169], v[116:119]
	v_mfma_f32_16x16x32_bf16 v[112:115], v[158:161], v[166:169], v[112:115]
	v_mfma_f32_16x16x32_bf16 v[100:103], v[150:153], v[184:187], v[100:103]
	v_mfma_f32_16x16x32_bf16 v[96:99], v[158:161], v[184:187], v[96:99]
	s_setprio 2
	s_barrier
	v_mfma_f32_16x16x32_bf16 v[84:87], v[150:153], v[196:199], v[84:87]
	v_mfma_f32_16x16x32_bf16 v[80:83], v[158:161], v[196:199], v[80:83]
	v_mfma_f32_16x16x32_bf16 v[68:71], v[150:153], v[212:215], v[68:71]
	v_mfma_f32_16x16x32_bf16 v[64:67], v[158:161], v[212:215], v[64:67]
	s_setprio 2
	s_mov_b32 m0, s75
	v_lshl_add_u64 v[174:175], s[46:47], 0, v[176:177]
	s_add_u32 s86, s46, 0x80000
	ds_read_b128 v[162:165], v211 offset:16384
	ds_read_b128 v[166:169], v211 offset:17408
	ds_read_b128 v[170:173], v211 offset:18432
	ds_read_b128 v[184:187], v211 offset:19456
	ds_read_b128 v[190:193], v211 offset:20480
	ds_read_b128 v[196:199], v211 offset:21504
	ds_read_b128 v[204:207], v211 offset:22528
	ds_read_b128 v[212:215], v211 offset:23552
	global_load_lds_dwordx4 v[174:175], off
	v_lshl_add_u64 v[200:201], s[46:47], 0, v[178:179]
	s_mov_b32 m0, s76
	s_addc_u32 s87, s47, 0
	global_load_lds_dwordx4 v[200:201], off
	v_lshl_add_u64 v[208:209], s[86:87], 0, v[176:177]
	s_mov_b32 m0, s77
	v_lshl_add_u64 v[216:217], s[48:49], 0, v[178:179]
	global_load_lds_dwordx4 v[208:209], off
	s_mov_b32 m0, s78
	v_lshl_add_u64 v[208:209], s[86:87], 0, v[178:179]
	global_load_lds_dwordx4 v[208:209], off
	s_mov_b32 m0, s56
	v_lshl_add_u64 v[208:209], s[48:49], 0, v[176:177]
	global_load_lds_dwordx4 v[208:209], off
	s_mov_b32 m0, s57
	s_nop 0
	global_load_lds_dwordx4 v[216:217], off
	s_waitcnt vmcnt(8)
	s_waitcnt lgkmcnt(0)
	s_barrier
	s_setprio 1
	s_waitcnt lgkmcnt(0)
	v_mfma_f32_16x16x32_bf16 v[60:63], v[130:133], v[162:165], v[60:63]
	v_mfma_f32_16x16x32_bf16 v[56:59], v[138:141], v[162:165], v[56:59]
	v_mfma_f32_16x16x32_bf16 v[44:47], v[130:133], v[170:173], v[44:47]
	v_mfma_f32_16x16x32_bf16 v[40:43], v[138:141], v[170:173], v[40:43]
	v_mfma_f32_16x16x32_bf16 v[28:31], v[130:133], v[190:193], v[28:31]
	v_mfma_f32_16x16x32_bf16 v[24:27], v[138:141], v[190:193], v[24:27]
	v_mfma_f32_16x16x32_bf16 v[12:15], v[130:133], v[204:207], v[12:15]
	v_mfma_f32_16x16x32_bf16 v[8:11], v[138:141], v[204:207], v[8:11]
	v_mfma_f32_16x16x32_bf16 v[60:63], v[134:137], v[166:169], v[60:63]
	v_mfma_f32_16x16x32_bf16 v[56:59], v[142:145], v[166:169], v[56:59]
	v_mfma_f32_16x16x32_bf16 v[44:47], v[134:137], v[184:187], v[44:47]
	v_mfma_f32_16x16x32_bf16 v[40:43], v[142:145], v[184:187], v[40:43]
	v_mfma_f32_16x16x32_bf16 v[28:31], v[134:137], v[196:199], v[28:31]
	v_mfma_f32_16x16x32_bf16 v[24:27], v[142:145], v[196:199], v[24:27]
	v_mfma_f32_16x16x32_bf16 v[12:15], v[134:137], v[212:215], v[12:15]
	v_mfma_f32_16x16x32_bf16 v[8:11], v[142:145], v[212:215], v[8:11]
	s_setprio 0
	s_setprio 1
	v_mfma_f32_16x16x32_bf16 v[52:55], v[146:149], v[162:165], v[52:55]
	v_mfma_f32_16x16x32_bf16 v[48:51], v[154:157], v[162:165], v[48:51]
	v_mfma_f32_16x16x32_bf16 v[36:39], v[146:149], v[170:173], v[36:39]
	v_mfma_f32_16x16x32_bf16 v[32:35], v[154:157], v[170:173], v[32:35]
	v_mfma_f32_16x16x32_bf16 v[20:23], v[146:149], v[190:193], v[20:23]
	v_mfma_f32_16x16x32_bf16 v[16:19], v[154:157], v[190:193], v[16:19]
	v_mfma_f32_16x16x32_bf16 v[4:7], v[146:149], v[204:207], v[4:7]
	v_mfma_f32_16x16x32_bf16 v[0:3], v[154:157], v[204:207], v[0:3]
	v_mfma_f32_16x16x32_bf16 v[52:55], v[150:153], v[166:169], v[52:55]
	v_mfma_f32_16x16x32_bf16 v[48:51], v[158:161], v[166:169], v[48:51]
	v_mfma_f32_16x16x32_bf16 v[36:39], v[150:153], v[184:187], v[36:39]
	v_mfma_f32_16x16x32_bf16 v[32:35], v[158:161], v[184:187], v[32:35]
	s_setprio 2
	s_barrier
	v_mfma_f32_16x16x32_bf16 v[20:23], v[150:153], v[196:199], v[20:23]
	v_mfma_f32_16x16x32_bf16 v[16:19], v[158:161], v[196:199], v[16:19]
	v_mfma_f32_16x16x32_bf16 v[4:7], v[150:153], v[212:215], v[4:7]
	v_mfma_f32_16x16x32_bf16 v[0:3], v[158:161], v[212:215], v[0:3]
	s_setprio 2
	ds_read_b128 v[130:133], v128
	ds_read_b128 v[134:137], v128 offset:1024
	ds_read_b128 v[138:141], v128 offset:2048
	ds_read_b128 v[142:145], v128 offset:3072
	ds_read_b128 v[146:149], v129
	ds_read_b128 v[150:153], v129 offset:1024
	ds_read_b128 v[154:157], v129 offset:2048
	ds_read_b128 v[158:161], v129 offset:3072
	s_add_u32 s48, s48, 0x80000
	s_addc_u32 s49, s49, 0
	s_mov_b32 m0, s58
	v_lshl_add_u64 v[218:219], s[48:49], 0, v[176:177]
	ds_read_b128 v[162:165], v211 offset:32768
	ds_read_b128 v[166:169], v211 offset:33792
	ds_read_b128 v[170:173], v211 offset:34816
	ds_read_b128 v[184:187], v211 offset:35840
	ds_read_b128 v[190:193], v211 offset:36864
	ds_read_b128 v[196:199], v211 offset:37888
	ds_read_b128 v[204:207], v211 offset:38912
	ds_read_b128 v[212:215], v211 offset:39936
	global_load_lds_dwordx4 v[218:219], off
	s_mov_b32 m0, s59
	v_lshl_add_u64 v[218:219], s[48:49], 0, v[178:179]
	global_load_lds_dwordx4 v[218:219], off
	s_waitcnt vmcnt(8)
	s_waitcnt lgkmcnt(0)
	s_barrier
	s_setprio 1
	s_waitcnt lgkmcnt(0)
	v_mfma_f32_16x16x32_bf16 v[124:127], v[130:133], v[162:165], v[124:127]
	v_mfma_f32_16x16x32_bf16 v[120:123], v[138:141], v[162:165], v[120:123]
	v_mfma_f32_16x16x32_bf16 v[108:111], v[130:133], v[170:173], v[108:111]
	v_mfma_f32_16x16x32_bf16 v[104:107], v[138:141], v[170:173], v[104:107]
	v_mfma_f32_16x16x32_bf16 v[92:95], v[130:133], v[190:193], v[92:95]
	v_mfma_f32_16x16x32_bf16 v[88:91], v[138:141], v[190:193], v[88:91]
	v_mfma_f32_16x16x32_bf16 v[76:79], v[130:133], v[204:207], v[76:79]
	v_mfma_f32_16x16x32_bf16 v[72:75], v[138:141], v[204:207], v[72:75]
	v_mfma_f32_16x16x32_bf16 v[124:127], v[134:137], v[166:169], v[124:127]
	v_mfma_f32_16x16x32_bf16 v[120:123], v[142:145], v[166:169], v[120:123]
	v_mfma_f32_16x16x32_bf16 v[108:111], v[134:137], v[184:187], v[108:111]
	v_mfma_f32_16x16x32_bf16 v[104:107], v[142:145], v[184:187], v[104:107]
	v_mfma_f32_16x16x32_bf16 v[92:95], v[134:137], v[196:199], v[92:95]
	v_mfma_f32_16x16x32_bf16 v[88:91], v[142:145], v[196:199], v[88:91]
	v_mfma_f32_16x16x32_bf16 v[76:79], v[134:137], v[212:215], v[76:79]
	v_mfma_f32_16x16x32_bf16 v[72:75], v[142:145], v[212:215], v[72:75]
	s_setprio 0
	s_setprio 1
	v_mfma_f32_16x16x32_bf16 v[116:119], v[146:149], v[162:165], v[116:119]
	v_mfma_f32_16x16x32_bf16 v[112:115], v[154:157], v[162:165], v[112:115]
	v_mfma_f32_16x16x32_bf16 v[100:103], v[146:149], v[170:173], v[100:103]
	v_mfma_f32_16x16x32_bf16 v[96:99], v[154:157], v[170:173], v[96:99]
	v_mfma_f32_16x16x32_bf16 v[84:87], v[146:149], v[190:193], v[84:87]
	v_mfma_f32_16x16x32_bf16 v[80:83], v[154:157], v[190:193], v[80:83]
	v_mfma_f32_16x16x32_bf16 v[68:71], v[146:149], v[204:207], v[68:71]
	v_mfma_f32_16x16x32_bf16 v[64:67], v[154:157], v[204:207], v[64:67]
	v_mfma_f32_16x16x32_bf16 v[116:119], v[150:153], v[166:169], v[116:119]
	v_mfma_f32_16x16x32_bf16 v[112:115], v[158:161], v[166:169], v[112:115]
	v_mfma_f32_16x16x32_bf16 v[100:103], v[150:153], v[184:187], v[100:103]
	v_mfma_f32_16x16x32_bf16 v[96:99], v[158:161], v[184:187], v[96:99]
	s_setprio 2
	s_barrier
	v_mfma_f32_16x16x32_bf16 v[84:87], v[150:153], v[196:199], v[84:87]
	v_mfma_f32_16x16x32_bf16 v[80:83], v[158:161], v[196:199], v[80:83]
	v_mfma_f32_16x16x32_bf16 v[68:71], v[150:153], v[212:215], v[68:71]
	v_mfma_f32_16x16x32_bf16 v[64:67], v[158:161], v[212:215], v[64:67]
	s_setprio 2
	s_mov_b32 m0, s79
	v_lshl_add_u64 v[174:175], v[174:175], 0, s[20:21]
	s_add_u32 s46, s46, 0x80080
	ds_read_b128 v[162:165], v211 offset:49152
	ds_read_b128 v[166:169], v211 offset:50176
	ds_read_b128 v[170:173], v211 offset:51200
	ds_read_b128 v[184:187], v211 offset:52224
	ds_read_b128 v[190:193], v211 offset:53248
	ds_read_b128 v[196:199], v211 offset:54272
	ds_read_b128 v[204:207], v211 offset:55296
	ds_read_b128 v[212:215], v211 offset:56320
	global_load_lds_dwordx4 v[174:175], off
	v_lshl_add_u64 v[174:175], v[200:201], 0, s[20:21]
	s_mov_b32 m0, s80
	s_addc_u32 s47, s47, 0
	global_load_lds_dwordx4 v[174:175], off
	s_mov_b32 m0, s81
	v_lshl_add_u64 v[174:175], s[46:47], 0, v[176:177]
	global_load_lds_dwordx4 v[174:175], off
	s_mov_b32 m0, s82
	v_lshl_add_u64 v[174:175], s[46:47], 0, v[178:179]
	global_load_lds_dwordx4 v[174:175], off
	s_mov_b32 m0, s61
	v_lshl_add_u64 v[174:175], v[208:209], 0, s[20:21]
	global_load_lds_dwordx4 v[174:175], off
	s_mov_b32 m0, s62
	v_lshl_add_u64 v[174:175], v[216:217], 0, s[20:21]
	global_load_lds_dwordx4 v[174:175], off
	s_waitcnt vmcnt(8)
	s_waitcnt lgkmcnt(0)
	s_barrier
	s_setprio 1
	s_waitcnt lgkmcnt(0)
	v_mfma_f32_16x16x32_bf16 v[60:63], v[130:133], v[162:165], v[60:63]
	v_mfma_f32_16x16x32_bf16 v[56:59], v[138:141], v[162:165], v[56:59]
	v_mfma_f32_16x16x32_bf16 v[44:47], v[130:133], v[170:173], v[44:47]
	v_mfma_f32_16x16x32_bf16 v[40:43], v[138:141], v[170:173], v[40:43]
	v_mfma_f32_16x16x32_bf16 v[28:31], v[130:133], v[190:193], v[28:31]
	v_mfma_f32_16x16x32_bf16 v[24:27], v[138:141], v[190:193], v[24:27]
	v_mfma_f32_16x16x32_bf16 v[12:15], v[130:133], v[204:207], v[12:15]
	v_mfma_f32_16x16x32_bf16 v[8:11], v[138:141], v[204:207], v[8:11]
	v_mfma_f32_16x16x32_bf16 v[60:63], v[134:137], v[166:169], v[60:63]
	v_mfma_f32_16x16x32_bf16 v[56:59], v[142:145], v[166:169], v[56:59]
	v_mfma_f32_16x16x32_bf16 v[44:47], v[134:137], v[184:187], v[44:47]
	v_mfma_f32_16x16x32_bf16 v[40:43], v[142:145], v[184:187], v[40:43]
	v_mfma_f32_16x16x32_bf16 v[28:31], v[134:137], v[196:199], v[28:31]
	v_mfma_f32_16x16x32_bf16 v[24:27], v[142:145], v[196:199], v[24:27]
	v_mfma_f32_16x16x32_bf16 v[12:15], v[134:137], v[212:215], v[12:15]
	v_mfma_f32_16x16x32_bf16 v[8:11], v[142:145], v[212:215], v[8:11]
	s_setprio 0
	s_setprio 1
	v_mfma_f32_16x16x32_bf16 v[52:55], v[146:149], v[162:165], v[52:55]
	v_mfma_f32_16x16x32_bf16 v[48:51], v[154:157], v[162:165], v[48:51]
	v_mfma_f32_16x16x32_bf16 v[36:39], v[146:149], v[170:173], v[36:39]
	v_mfma_f32_16x16x32_bf16 v[32:35], v[154:157], v[170:173], v[32:35]
	v_mfma_f32_16x16x32_bf16 v[20:23], v[146:149], v[190:193], v[20:23]
	v_mfma_f32_16x16x32_bf16 v[16:19], v[154:157], v[190:193], v[16:19]
	v_mfma_f32_16x16x32_bf16 v[4:7], v[146:149], v[204:207], v[4:7]
	v_mfma_f32_16x16x32_bf16 v[0:3], v[154:157], v[204:207], v[0:3]
	v_mfma_f32_16x16x32_bf16 v[52:55], v[150:153], v[166:169], v[52:55]
	v_mfma_f32_16x16x32_bf16 v[48:51], v[158:161], v[166:169], v[48:51]
	v_mfma_f32_16x16x32_bf16 v[36:39], v[150:153], v[184:187], v[36:39]
	v_mfma_f32_16x16x32_bf16 v[32:35], v[158:161], v[184:187], v[32:35]
	s_setprio 2
	s_barrier
	v_mfma_f32_16x16x32_bf16 v[20:23], v[150:153], v[196:199], v[20:23]
	v_mfma_f32_16x16x32_bf16 v[16:19], v[158:161], v[196:199], v[16:19]
	v_mfma_f32_16x16x32_bf16 v[4:7], v[150:153], v[212:215], v[4:7]
	v_mfma_f32_16x16x32_bf16 v[0:3], v[158:161], v[212:215], v[0:3]
	s_setprio 0
	s_add_i32 s70, s70, 1
	s_add_u32 s44, s44, 0x100
	s_addc_u32 s45, s45, 0
	s_add_u32 s83, s83, 0x100
	s_addc_u32 s84, s84, 0
	s_cmp_gt_u32 s85, 29
	s_cbranch_scc0 .LBB0_698
	s_lshl_b32 s29, s41, 12
	s_and_b32 s29, s29, 0x1000
	s_add_i32 s29, s29, 0
	v_mbcnt_lo_u32_b32 v128, -1, 0
	v_mbcnt_hi_u32_b32 v128, -1, v128
	s_add_i32 s29, s29, s63
	v_lshlrev_b32_e32 v128, 4, v128
	s_add_i32 s29, s29, 0x20400
	v_and_b32_e32 v128, 0xf0, v128
	v_add_u32_e32 v128, s29, v128
	ds_read2_b32 v[214:215], v128 offset0:3 offset1:67
	ds_read2_b32 v[206:207], v128 offset0:131 offset1:195
	v_add_u32_e32 v128, 12, v128
	ds_read2st64_b32 v[196:197], v128 offset0:8 offset1:9
	ds_read2st64_b32 v[190:191], v128 offset0:10 offset1:11
	s_and_b64 vcc, exec, s[22:23]
	s_waitcnt lgkmcnt(0)
	v_mov_b32_e32 v210, v215
	v_mov_b32_e32 v202, v207
	v_mov_b32_e32 v194, v197
	v_mov_b32_e32 v188, v191
	s_cbranch_vccz .LBB0_703
	s_barrier

.LBB0_783:
	s_ashr_i32 s23, s22, 31
	s_lshl_b64 s[26:27], s[22:23], 19
	s_add_u32 s26, s43, s26
	s_addc_u32 s27, s44, s27
	s_and_b64 s[28:29], s[4:5], exec
	s_cselect_b32 s23, s27, s37
	s_cselect_b32 s31, s26, s36
	s_ashr_i32 s25, s24, 31
	s_lshl_b64 s[28:29], s[24:25], 19
	s_add_u32 s28, s45, s28
	s_addc_u32 s29, s46, s29
	s_and_b64 s[40:41], s[4:5], exec
	s_cselect_b32 s25, s29, s39
	s_cselect_b32 s62, s28, s38
	s_add_u32 s36, s36, 0x40080
	s_addc_u32 s37, s37, 0
	s_add_u32 s63, s38, 0x100
	s_addc_u32 s64, s39, 0
	s_mov_b32 s65, -2
	ds_read_b128 v[144:147], v163
	ds_read_b128 v[148:151], v163 offset:1024
	ds_read_b128 v[152:155], v163 offset:2048
	ds_read_b128 v[156:159], v163 offset:3072
	ds_read_b128 v[168:171], v164
	ds_read_b128 v[172:175], v164 offset:1024
	ds_read_b128 v[176:179], v164 offset:2048
	ds_read_b128 v[180:183], v164 offset:3072
	s_add_u32 s38, s36, 0xfffc0080
	s_addc_u32 s39, s37, -1
	s_cmp_eq_u32 s65, 12
	s_cselect_b32 s41, s23, s39
	s_cselect_b32 s40, s31, s38
	s_cselect_b32 s39, s25, s64
	s_cselect_b32 s38, s62, s63
	v_lshl_add_u64 v[160:161], s[36:37], 0, v[136:137]
	s_add_i32 m0, s50, 0xc000
	ds_read_b128 v[184:187], v165
	ds_read_b128 v[188:191], v165 offset:1024
	ds_read_b128 v[192:195], v165 offset:2048
	ds_read_b128 v[196:199], v165 offset:3072
	ds_read_b128 v[200:203], v165 offset:4096
	ds_read_b128 v[204:207], v165 offset:5120
	ds_read_b128 v[208:211], v165 offset:6144
	ds_read_b128 v[212:215], v165 offset:7168
	global_load_lds_dwordx4 v[160:161], off
	s_add_i32 m0, s50, 0xe000
	v_lshl_add_u64 v[160:161], s[36:37], 0, v[138:139]
	global_load_lds_dwordx4 v[160:161], off
	s_waitcnt vmcnt(8)
	s_waitcnt lgkmcnt(0)
	s_barrier
	s_setprio 1
	s_waitcnt lgkmcnt(0)
	v_mfma_f32_16x16x32_bf16 v[124:127], v[144:147], v[184:187], 0
	v_mfma_f32_16x16x32_bf16 v[120:123], v[152:155], v[184:187], 0
	v_mfma_f32_16x16x32_bf16 v[108:111], v[144:147], v[192:195], 0
	v_mfma_f32_16x16x32_bf16 v[104:107], v[152:155], v[192:195], 0
	v_mfma_f32_16x16x32_bf16 v[92:95], v[144:147], v[200:203], 0
	v_mfma_f32_16x16x32_bf16 v[88:91], v[152:155], v[200:203], 0
	v_mfma_f32_16x16x32_bf16 v[76:79], v[144:147], v[208:211], 0
	v_mfma_f32_16x16x32_bf16 v[72:75], v[152:155], v[208:211], 0
	v_mfma_f32_16x16x32_bf16 v[124:127], v[148:151], v[188:191], v[124:127]
	v_mfma_f32_16x16x32_bf16 v[120:123], v[156:159], v[188:191], v[120:123]
	v_mfma_f32_16x16x32_bf16 v[108:111], v[148:151], v[196:199], v[108:111]
	v_mfma_f32_16x16x32_bf16 v[104:107], v[156:159], v[196:199], v[104:107]
	v_mfma_f32_16x16x32_bf16 v[92:95], v[148:151], v[204:207], v[92:95]
	v_mfma_f32_16x16x32_bf16 v[88:91], v[156:159], v[204:207], v[88:91]
	v_mfma_f32_16x16x32_bf16 v[76:79], v[148:151], v[212:215], v[76:79]
	v_mfma_f32_16x16x32_bf16 v[72:75], v[156:159], v[212:215], v[72:75]
	s_setprio 0
	s_setprio 1
	v_mfma_f32_16x16x32_bf16 v[116:119], v[168:171], v[184:187], 0
	v_mfma_f32_16x16x32_bf16 v[112:115], v[176:179], v[184:187], 0
	v_mfma_f32_16x16x32_bf16 v[100:103], v[168:171], v[192:195], 0
	v_mfma_f32_16x16x32_bf16 v[96:99], v[176:179], v[192:195], 0
	v_mfma_f32_16x16x32_bf16 v[84:87], v[168:171], v[200:203], 0
	v_mfma_f32_16x16x32_bf16 v[80:83], v[176:179], v[200:203], 0
	v_mfma_f32_16x16x32_bf16 v[68:71], v[168:171], v[208:211], 0
	v_mfma_f32_16x16x32_bf16 v[64:67], v[176:179], v[208:211], 0
	v_mfma_f32_16x16x32_bf16 v[116:119], v[172:175], v[188:191], v[116:119]
	v_mfma_f32_16x16x32_bf16 v[112:115], v[180:183], v[188:191], v[112:115]
	v_mfma_f32_16x16x32_bf16 v[100:103], v[172:175], v[196:199], v[100:103]
	v_mfma_f32_16x16x32_bf16 v[96:99], v[180:183], v[196:199], v[96:99]
	s_setprio 2
	s_barrier
	v_mfma_f32_16x16x32_bf16 v[84:87], v[172:175], v[204:207], v[84:87]
	v_mfma_f32_16x16x32_bf16 v[80:83], v[180:183], v[204:207], v[80:83]
	v_mfma_f32_16x16x32_bf16 v[68:71], v[172:175], v[212:215], v[68:71]
	v_mfma_f32_16x16x32_bf16 v[64:67], v[180:183], v[212:215], v[64:67]
	s_setprio 2
	s_add_i32 s66, s59, s47
	v_lshl_add_u64 v[160:161], s[38:39], 0, v[132:133]
	s_mov_b32 m0, s66
	ds_read_b128 v[184:187], v165 offset:16384
	ds_read_b128 v[188:191], v165 offset:17408
	ds_read_b128 v[192:195], v165 offset:18432
	ds_read_b128 v[196:199], v165 offset:19456
	ds_read_b128 v[200:203], v165 offset:20480
	ds_read_b128 v[204:207], v165 offset:21504
	ds_read_b128 v[208:211], v165 offset:22528
	ds_read_b128 v[212:215], v165 offset:23552
	global_load_lds_dwordx4 v[160:161], off
	s_add_i32 m0, s66, 0x2000
	s_add_u32 s66, s38, 0x40000
	v_lshl_add_u64 v[216:217], s[38:39], 0, v[128:129]
	s_addc_u32 s67, s39, 0
	s_add_i32 s68, s60, s47
	global_load_lds_dwordx4 v[216:217], off
	v_lshl_add_u64 v[218:219], s[66:67], 0, v[132:133]
	s_mov_b32 m0, s68
	v_lshl_add_u64 v[220:221], s[40:41], 0, v[130:131]
	global_load_lds_dwordx4 v[218:219], off
	s_add_i32 m0, s68, 0x2000
	v_lshl_add_u64 v[218:219], s[66:67], 0, v[128:129]
	global_load_lds_dwordx4 v[218:219], off
	s_mov_b32 m0, s50
	v_lshl_add_u64 v[218:219], s[40:41], 0, v[134:135]
	global_load_lds_dwordx4 v[218:219], off
	s_mov_b32 m0, s51
	s_nop 0
	global_load_lds_dwordx4 v[220:221], off
	s_waitcnt vmcnt(8)
	s_waitcnt lgkmcnt(0)
	s_barrier
	s_setprio 1
	s_waitcnt lgkmcnt(0)
	v_mfma_f32_16x16x32_bf16 v[60:63], v[144:147], v[184:187], 0
	v_mfma_f32_16x16x32_bf16 v[56:59], v[152:155], v[184:187], 0
	v_mfma_f32_16x16x32_bf16 v[44:47], v[144:147], v[192:195], 0
	v_mfma_f32_16x16x32_bf16 v[40:43], v[152:155], v[192:195], 0
	v_mfma_f32_16x16x32_bf16 v[28:31], v[144:147], v[200:203], 0
	v_mfma_f32_16x16x32_bf16 v[24:27], v[152:155], v[200:203], 0
	v_mfma_f32_16x16x32_bf16 v[12:15], v[144:147], v[208:211], 0
	v_mfma_f32_16x16x32_bf16 v[8:11], v[152:155], v[208:211], 0
	v_mfma_f32_16x16x32_bf16 v[60:63], v[148:151], v[188:191], v[60:63]
	v_mfma_f32_16x16x32_bf16 v[56:59], v[156:159], v[188:191], v[56:59]
	v_mfma_f32_16x16x32_bf16 v[44:47], v[148:151], v[196:199], v[44:47]
	v_mfma_f32_16x16x32_bf16 v[40:43], v[156:159], v[196:199], v[40:43]
	v_mfma_f32_16x16x32_bf16 v[28:31], v[148:151], v[204:207], v[28:31]
	v_mfma_f32_16x16x32_bf16 v[24:27], v[156:159], v[204:207], v[24:27]
	v_mfma_f32_16x16x32_bf16 v[12:15], v[148:151], v[212:215], v[12:15]
	v_mfma_f32_16x16x32_bf16 v[8:11], v[156:159], v[212:215], v[8:11]
	s_setprio 0
	s_setprio 1
	v_mfma_f32_16x16x32_bf16 v[52:55], v[168:171], v[184:187], 0
	v_mfma_f32_16x16x32_bf16 v[48:51], v[176:179], v[184:187], 0
	v_mfma_f32_16x16x32_bf16 v[36:39], v[168:171], v[192:195], 0
	v_mfma_f32_16x16x32_bf16 v[32:35], v[176:179], v[192:195], 0
	v_mfma_f32_16x16x32_bf16 v[20:23], v[168:171], v[200:203], 0
	v_mfma_f32_16x16x32_bf16 v[16:19], v[176:179], v[200:203], 0
	v_mfma_f32_16x16x32_bf16 v[4:7], v[168:171], v[208:211], 0
	v_mfma_f32_16x16x32_bf16 v[0:3], v[176:179], v[208:211], 0
	v_mfma_f32_16x16x32_bf16 v[52:55], v[172:175], v[188:191], v[52:55]
	v_mfma_f32_16x16x32_bf16 v[48:51], v[180:183], v[188:191], v[48:51]
	v_mfma_f32_16x16x32_bf16 v[36:39], v[172:175], v[196:199], v[36:39]
	v_mfma_f32_16x16x32_bf16 v[32:35], v[180:183], v[196:199], v[32:35]
	s_setprio 2
	s_barrier
	v_mfma_f32_16x16x32_bf16 v[20:23], v[172:175], v[204:207], v[20:23]
	v_mfma_f32_16x16x32_bf16 v[16:19], v[180:183], v[204:207], v[16:19]
	v_mfma_f32_16x16x32_bf16 v[4:7], v[172:175], v[212:215], v[4:7]
	v_mfma_f32_16x16x32_bf16 v[0:3], v[180:183], v[212:215], v[0:3]
	s_setprio 2
	s_add_i32 s66, 0, 0x18000
	s_add_i32 s67, 0, 0x1c000
	v_add_u32_e32 v156, s66, v162
	v_add_u32_e32 v167, s67, v162
	ds_read_b128 v[144:147], v156
	ds_read_b128 v[148:151], v156 offset:1024
	ds_read_b128 v[152:155], v156 offset:2048
	ds_read_b128 v[156:159], v156 offset:3072
	ds_read_b128 v[168:171], v167
	ds_read_b128 v[172:175], v167 offset:1024
	ds_read_b128 v[176:179], v167 offset:2048
	ds_read_b128 v[180:183], v167 offset:3072
	s_add_u32 s40, s40, 0x40000
	s_addc_u32 s41, s41, 0
	s_mov_b32 m0, s54
	v_lshl_add_u64 v[222:223], s[40:41], 0, v[134:135]
	ds_read_b128 v[184:187], v165 offset:32768
	ds_read_b128 v[188:191], v165 offset:33792
	ds_read_b128 v[192:195], v165 offset:34816
	ds_read_b128 v[196:199], v165 offset:35840
	ds_read_b128 v[200:203], v165 offset:36864
	ds_read_b128 v[204:207], v165 offset:37888
	ds_read_b128 v[208:211], v165 offset:38912
	ds_read_b128 v[212:215], v165 offset:39936
	global_load_lds_dwordx4 v[222:223], off
	s_mov_b32 m0, s55
	v_lshl_add_u64 v[222:223], s[40:41], 0, v[130:131]
	global_load_lds_dwordx4 v[222:223], off
	s_waitcnt vmcnt(8)
	s_waitcnt lgkmcnt(0)
	s_barrier
	s_setprio 1
	s_waitcnt lgkmcnt(0)
	v_mfma_f32_16x16x32_bf16 v[124:127], v[144:147], v[184:187], v[124:127]
	v_mfma_f32_16x16x32_bf16 v[120:123], v[152:155], v[184:187], v[120:123]
	v_mfma_f32_16x16x32_bf16 v[108:111], v[144:147], v[192:195], v[108:111]
	v_mfma_f32_16x16x32_bf16 v[104:107], v[152:155], v[192:195], v[104:107]
	v_mfma_f32_16x16x32_bf16 v[92:95], v[144:147], v[200:203], v[92:95]
	v_mfma_f32_16x16x32_bf16 v[88:91], v[152:155], v[200:203], v[88:91]
	v_mfma_f32_16x16x32_bf16 v[76:79], v[144:147], v[208:211], v[76:79]
	v_mfma_f32_16x16x32_bf16 v[72:75], v[152:155], v[208:211], v[72:75]
	v_mfma_f32_16x16x32_bf16 v[124:127], v[148:151], v[188:191], v[124:127]
	v_mfma_f32_16x16x32_bf16 v[120:123], v[156:159], v[188:191], v[120:123]
	v_mfma_f32_16x16x32_bf16 v[108:111], v[148:151], v[196:199], v[108:111]
	v_mfma_f32_16x16x32_bf16 v[104:107], v[156:159], v[196:199], v[104:107]
	v_mfma_f32_16x16x32_bf16 v[92:95], v[148:151], v[204:207], v[92:95]
	v_mfma_f32_16x16x32_bf16 v[88:91], v[156:159], v[204:207], v[88:91]
	v_mfma_f32_16x16x32_bf16 v[76:79], v[148:151], v[212:215], v[76:79]
	v_mfma_f32_16x16x32_bf16 v[72:75], v[156:159], v[212:215], v[72:75]
	s_setprio 0
	s_setprio 1
	v_mfma_f32_16x16x32_bf16 v[116:119], v[168:171], v[184:187], v[116:119]
	v_mfma_f32_16x16x32_bf16 v[112:115], v[176:179], v[184:187], v[112:115]
	v_mfma_f32_16x16x32_bf16 v[100:103], v[168:171], v[192:195], v[100:103]
	v_mfma_f32_16x16x32_bf16 v[96:99], v[176:179], v[192:195], v[96:99]
	v_mfma_f32_16x16x32_bf16 v[84:87], v[168:171], v[200:203], v[84:87]
	v_mfma_f32_16x16x32_bf16 v[80:83], v[176:179], v[200:203], v[80:83]
	v_mfma_f32_16x16x32_bf16 v[68:71], v[168:171], v[208:211], v[68:71]
	v_mfma_f32_16x16x32_bf16 v[64:67], v[176:179], v[208:211], v[64:67]
	v_mfma_f32_16x16x32_bf16 v[116:119], v[172:175], v[188:191], v[116:119]
	v_mfma_f32_16x16x32_bf16 v[112:115], v[180:183], v[188:191], v[112:115]
	v_mfma_f32_16x16x32_bf16 v[100:103], v[172:175], v[196:199], v[100:103]
	v_mfma_f32_16x16x32_bf16 v[96:99], v[180:183], v[196:199], v[96:99]
	s_setprio 2
	s_barrier
	v_mfma_f32_16x16x32_bf16 v[84:87], v[172:175], v[204:207], v[84:87]
	v_mfma_f32_16x16x32_bf16 v[80:83], v[180:183], v[204:207], v[80:83]
	v_mfma_f32_16x16x32_bf16 v[68:71], v[172:175], v[212:215], v[68:71]
	v_mfma_f32_16x16x32_bf16 v[64:67], v[180:183], v[212:215], v[64:67]
	s_setprio 2
	s_add_i32 s40, s66, s47
	v_lshl_add_u64 v[160:161], v[160:161], 0, s[16:17]
	s_mov_b32 m0, s40
	ds_read_b128 v[184:187], v165 offset:49152
	ds_read_b128 v[188:191], v165 offset:50176
	ds_read_b128 v[192:195], v165 offset:51200
	ds_read_b128 v[196:199], v165 offset:52224
	ds_read_b128 v[200:203], v165 offset:53248
	ds_read_b128 v[204:207], v165 offset:54272
	ds_read_b128 v[208:211], v165 offset:55296
	ds_read_b128 v[212:215], v165 offset:56320
	global_load_lds_dwordx4 v[160:161], off
	s_add_i32 m0, s40, 0x2000
	s_add_u32 s38, s38, 0x40080
	v_lshl_add_u64 v[160:161], v[216:217], 0, s[16:17]
	s_addc_u32 s39, s39, 0
	s_add_i32 s40, s67, s47
	global_load_lds_dwordx4 v[160:161], off
	s_mov_b32 m0, s40
	v_lshl_add_u64 v[160:161], s[38:39], 0, v[132:133]
	global_load_lds_dwordx4 v[160:161], off
	s_add_i32 m0, s40, 0x2000
	v_lshl_add_u64 v[160:161], s[38:39], 0, v[128:129]
	global_load_lds_dwordx4 v[160:161], off
	s_mov_b32 m0, s57
	v_lshl_add_u64 v[160:161], v[218:219], 0, s[16:17]
	global_load_lds_dwordx4 v[160:161], off
	s_mov_b32 m0, s58
	v_lshl_add_u64 v[160:161], v[220:221], 0, s[16:17]
	global_load_lds_dwordx4 v[160:161], off
	s_waitcnt vmcnt(8)
	s_waitcnt lgkmcnt(0)
	s_barrier
	s_setprio 1
	s_waitcnt lgkmcnt(0)
	v_mfma_f32_16x16x32_bf16 v[60:63], v[144:147], v[184:187], v[60:63]
	v_mfma_f32_16x16x32_bf16 v[56:59], v[152:155], v[184:187], v[56:59]
	v_mfma_f32_16x16x32_bf16 v[44:47], v[144:147], v[192:195], v[44:47]
	v_mfma_f32_16x16x32_bf16 v[40:43], v[152:155], v[192:195], v[40:43]
	v_mfma_f32_16x16x32_bf16 v[28:31], v[144:147], v[200:203], v[28:31]
	v_mfma_f32_16x16x32_bf16 v[24:27], v[152:155], v[200:203], v[24:27]
	v_mfma_f32_16x16x32_bf16 v[12:15], v[144:147], v[208:211], v[12:15]
	v_mfma_f32_16x16x32_bf16 v[8:11], v[152:155], v[208:211], v[8:11]
	v_mfma_f32_16x16x32_bf16 v[60:63], v[148:151], v[188:191], v[60:63]
	v_mfma_f32_16x16x32_bf16 v[56:59], v[156:159], v[188:191], v[56:59]
	v_mfma_f32_16x16x32_bf16 v[44:47], v[148:151], v[196:199], v[44:47]
	v_mfma_f32_16x16x32_bf16 v[40:43], v[156:159], v[196:199], v[40:43]
	v_mfma_f32_16x16x32_bf16 v[28:31], v[148:151], v[204:207], v[28:31]
	v_mfma_f32_16x16x32_bf16 v[24:27], v[156:159], v[204:207], v[24:27]
	v_mfma_f32_16x16x32_bf16 v[12:15], v[148:151], v[212:215], v[12:15]
	v_mfma_f32_16x16x32_bf16 v[8:11], v[156:159], v[212:215], v[8:11]
	s_setprio 0
	s_setprio 1
	v_mfma_f32_16x16x32_bf16 v[52:55], v[168:171], v[184:187], v[52:55]
	v_mfma_f32_16x16x32_bf16 v[48:51], v[176:179], v[184:187], v[48:51]
	v_mfma_f32_16x16x32_bf16 v[36:39], v[168:171], v[192:195], v[36:39]
	v_mfma_f32_16x16x32_bf16 v[32:35], v[176:179], v[192:195], v[32:35]
	v_mfma_f32_16x16x32_bf16 v[20:23], v[168:171], v[200:203], v[20:23]
	v_mfma_f32_16x16x32_bf16 v[16:19], v[176:179], v[200:203], v[16:19]
	v_mfma_f32_16x16x32_bf16 v[4:7], v[168:171], v[208:211], v[4:7]
	v_mfma_f32_16x16x32_bf16 v[0:3], v[176:179], v[208:211], v[0:3]
	v_mfma_f32_16x16x32_bf16 v[52:55], v[172:175], v[188:191], v[52:55]
	v_mfma_f32_16x16x32_bf16 v[48:51], v[180:183], v[188:191], v[48:51]
	v_mfma_f32_16x16x32_bf16 v[36:39], v[172:175], v[196:199], v[36:39]
	v_mfma_f32_16x16x32_bf16 v[32:35], v[180:183], v[196:199], v[32:35]
	s_setprio 2
	s_barrier
	v_mfma_f32_16x16x32_bf16 v[20:23], v[172:175], v[204:207], v[20:23]
	v_mfma_f32_16x16x32_bf16 v[16:19], v[180:183], v[204:207], v[16:19]
	v_mfma_f32_16x16x32_bf16 v[4:7], v[172:175], v[212:215], v[4:7]
	v_mfma_f32_16x16x32_bf16 v[0:3], v[180:183], v[212:215], v[0:3]
	s_setprio 2
	s_add_i32 s65, s65, 2
	s_add_u32 s36, s36, 0x100
	s_addc_u32 s37, s37, 0
	s_add_u32 s63, s63, 0x100
	s_addc_u32 s64, s64, 0
	s_cmp_gt_u32 s65, 13
.LBB0_784:
	ds_read_b128 v[144:147], v163
	ds_read_b128 v[148:151], v163 offset:1024
	ds_read_b128 v[152:155], v163 offset:2048
	ds_read_b128 v[156:159], v163 offset:3072
	ds_read_b128 v[168:171], v164
	ds_read_b128 v[172:175], v164 offset:1024
	ds_read_b128 v[176:179], v164 offset:2048
	ds_read_b128 v[180:183], v164 offset:3072
	s_add_u32 s38, s36, 0xfffc0080
	s_addc_u32 s39, s37, -1
	s_cmp_eq_u32 s65, 12
	s_cselect_b32 s41, s23, s39
	s_cselect_b32 s40, s31, s38
	s_cselect_b32 s39, s25, s64
	s_cselect_b32 s38, s62, s63
	v_lshl_add_u64 v[160:161], s[36:37], 0, v[136:137]
	s_add_i32 m0, s50, 0xc000
	ds_read_b128 v[184:187], v165
	ds_read_b128 v[188:191], v165 offset:1024
	ds_read_b128 v[192:195], v165 offset:2048
	ds_read_b128 v[196:199], v165 offset:3072
	ds_read_b128 v[200:203], v165 offset:4096
	ds_read_b128 v[204:207], v165 offset:5120
	ds_read_b128 v[208:211], v165 offset:6144
	ds_read_b128 v[212:215], v165 offset:7168
	global_load_lds_dwordx4 v[160:161], off
	s_add_i32 m0, s50, 0xe000
	v_lshl_add_u64 v[160:161], s[36:37], 0, v[138:139]
	global_load_lds_dwordx4 v[160:161], off
	s_waitcnt vmcnt(8)
	s_waitcnt lgkmcnt(0)
	s_barrier
	s_setprio 1
	s_waitcnt lgkmcnt(0)
	v_mfma_f32_16x16x32_bf16 v[124:127], v[144:147], v[184:187], v[124:127]
	v_mfma_f32_16x16x32_bf16 v[120:123], v[152:155], v[184:187], v[120:123]
	v_mfma_f32_16x16x32_bf16 v[108:111], v[144:147], v[192:195], v[108:111]
	v_mfma_f32_16x16x32_bf16 v[104:107], v[152:155], v[192:195], v[104:107]
	v_mfma_f32_16x16x32_bf16 v[92:95], v[144:147], v[200:203], v[92:95]
	v_mfma_f32_16x16x32_bf16 v[88:91], v[152:155], v[200:203], v[88:91]
	v_mfma_f32_16x16x32_bf16 v[76:79], v[144:147], v[208:211], v[76:79]
	v_mfma_f32_16x16x32_bf16 v[72:75], v[152:155], v[208:211], v[72:75]
	v_mfma_f32_16x16x32_bf16 v[124:127], v[148:151], v[188:191], v[124:127]
	v_mfma_f32_16x16x32_bf16 v[120:123], v[156:159], v[188:191], v[120:123]
	v_mfma_f32_16x16x32_bf16 v[108:111], v[148:151], v[196:199], v[108:111]
	v_mfma_f32_16x16x32_bf16 v[104:107], v[156:159], v[196:199], v[104:107]
	v_mfma_f32_16x16x32_bf16 v[92:95], v[148:151], v[204:207], v[92:95]
	v_mfma_f32_16x16x32_bf16 v[88:91], v[156:159], v[204:207], v[88:91]
	v_mfma_f32_16x16x32_bf16 v[76:79], v[148:151], v[212:215], v[76:79]
	v_mfma_f32_16x16x32_bf16 v[72:75], v[156:159], v[212:215], v[72:75]
	s_setprio 0
	s_setprio 1
	v_mfma_f32_16x16x32_bf16 v[116:119], v[168:171], v[184:187], v[116:119]
	v_mfma_f32_16x16x32_bf16 v[112:115], v[176:179], v[184:187], v[112:115]
	v_mfma_f32_16x16x32_bf16 v[100:103], v[168:171], v[192:195], v[100:103]
	v_mfma_f32_16x16x32_bf16 v[96:99], v[176:179], v[192:195], v[96:99]
	v_mfma_f32_16x16x32_bf16 v[84:87], v[168:171], v[200:203], v[84:87]
	v_mfma_f32_16x16x32_bf16 v[80:83], v[176:179], v[200:203], v[80:83]
	v_mfma_f32_16x16x32_bf16 v[68:71], v[168:171], v[208:211], v[68:71]
	v_mfma_f32_16x16x32_bf16 v[64:67], v[176:179], v[208:211], v[64:67]
	v_mfma_f32_16x16x32_bf16 v[116:119], v[172:175], v[188:191], v[116:119]
	v_mfma_f32_16x16x32_bf16 v[112:115], v[180:183], v[188:191], v[112:115]
	v_mfma_f32_16x16x32_bf16 v[100:103], v[172:175], v[196:199], v[100:103]
	v_mfma_f32_16x16x32_bf16 v[96:99], v[180:183], v[196:199], v[96:99]
	s_setprio 2
	s_barrier
	v_mfma_f32_16x16x32_bf16 v[84:87], v[172:175], v[204:207], v[84:87]
	v_mfma_f32_16x16x32_bf16 v[80:83], v[180:183], v[204:207], v[80:83]
	v_mfma_f32_16x16x32_bf16 v[68:71], v[172:175], v[212:215], v[68:71]
	v_mfma_f32_16x16x32_bf16 v[64:67], v[180:183], v[212:215], v[64:67]
	s_setprio 2
	s_add_i32 s66, s59, s47
	v_lshl_add_u64 v[160:161], s[38:39], 0, v[132:133]
	s_mov_b32 m0, s66
	ds_read_b128 v[184:187], v165 offset:16384
	ds_read_b128 v[188:191], v165 offset:17408
	ds_read_b128 v[192:195], v165 offset:18432
	ds_read_b128 v[196:199], v165 offset:19456
	ds_read_b128 v[200:203], v165 offset:20480
	ds_read_b128 v[204:207], v165 offset:21504
	ds_read_b128 v[208:211], v165 offset:22528
	ds_read_b128 v[212:215], v165 offset:23552
	global_load_lds_dwordx4 v[160:161], off
	s_add_i32 m0, s66, 0x2000
	s_add_u32 s66, s38, 0x40000
	v_lshl_add_u64 v[216:217], s[38:39], 0, v[128:129]
	s_addc_u32 s67, s39, 0
	s_add_i32 s68, s60, s47
	global_load_lds_dwordx4 v[216:217], off
	v_lshl_add_u64 v[218:219], s[66:67], 0, v[132:133]
	s_mov_b32 m0, s68
	v_lshl_add_u64 v[220:221], s[40:41], 0, v[130:131]
	global_load_lds_dwordx4 v[218:219], off
	s_add_i32 m0, s68, 0x2000
	v_lshl_add_u64 v[218:219], s[66:67], 0, v[128:129]
	global_load_lds_dwordx4 v[218:219], off
	s_mov_b32 m0, s50
	v_lshl_add_u64 v[218:219], s[40:41], 0, v[134:135]
	global_load_lds_dwordx4 v[218:219], off
	s_mov_b32 m0, s51
	s_nop 0
	global_load_lds_dwordx4 v[220:221], off
	s_waitcnt vmcnt(8)
	s_waitcnt lgkmcnt(0)
	s_barrier
	s_setprio 1
	s_waitcnt lgkmcnt(0)
	v_mfma_f32_16x16x32_bf16 v[60:63], v[144:147], v[184:187], v[60:63]
	v_mfma_f32_16x16x32_bf16 v[56:59], v[152:155], v[184:187], v[56:59]
	v_mfma_f32_16x16x32_bf16 v[44:47], v[144:147], v[192:195], v[44:47]
	v_mfma_f32_16x16x32_bf16 v[40:43], v[152:155], v[192:195], v[40:43]
	v_mfma_f32_16x16x32_bf16 v[28:31], v[144:147], v[200:203], v[28:31]
	v_mfma_f32_16x16x32_bf16 v[24:27], v[152:155], v[200:203], v[24:27]
	v_mfma_f32_16x16x32_bf16 v[12:15], v[144:147], v[208:211], v[12:15]
	v_mfma_f32_16x16x32_bf16 v[8:11], v[152:155], v[208:211], v[8:11]
	v_mfma_f32_16x16x32_bf16 v[60:63], v[148:151], v[188:191], v[60:63]
	v_mfma_f32_16x16x32_bf16 v[56:59], v[156:159], v[188:191], v[56:59]
	v_mfma_f32_16x16x32_bf16 v[44:47], v[148:151], v[196:199], v[44:47]
	v_mfma_f32_16x16x32_bf16 v[40:43], v[156:159], v[196:199], v[40:43]
	v_mfma_f32_16x16x32_bf16 v[28:31], v[148:151], v[204:207], v[28:31]
	v_mfma_f32_16x16x32_bf16 v[24:27], v[156:159], v[204:207], v[24:27]
	v_mfma_f32_16x16x32_bf16 v[12:15], v[148:151], v[212:215], v[12:15]
	v_mfma_f32_16x16x32_bf16 v[8:11], v[156:159], v[212:215], v[8:11]
	s_setprio 0
	s_setprio 1
	v_mfma_f32_16x16x32_bf16 v[52:55], v[168:171], v[184:187], v[52:55]
	v_mfma_f32_16x16x32_bf16 v[48:51], v[176:179], v[184:187], v[48:51]
	v_mfma_f32_16x16x32_bf16 v[36:39], v[168:171], v[192:195], v[36:39]
	v_mfma_f32_16x16x32_bf16 v[32:35], v[176:179], v[192:195], v[32:35]
	v_mfma_f32_16x16x32_bf16 v[20:23], v[168:171], v[200:203], v[20:23]
	v_mfma_f32_16x16x32_bf16 v[16:19], v[176:179], v[200:203], v[16:19]
	v_mfma_f32_16x16x32_bf16 v[4:7], v[168:171], v[208:211], v[4:7]
	v_mfma_f32_16x16x32_bf16 v[0:3], v[176:179], v[208:211], v[0:3]
	v_mfma_f32_16x16x32_bf16 v[52:55], v[172:175], v[188:191], v[52:55]
	v_mfma_f32_16x16x32_bf16 v[48:51], v[180:183], v[188:191], v[48:51]
	v_mfma_f32_16x16x32_bf16 v[36:39], v[172:175], v[196:199], v[36:39]
	v_mfma_f32_16x16x32_bf16 v[32:35], v[180:183], v[196:199], v[32:35]
	s_setprio 2
	s_barrier
	v_mfma_f32_16x16x32_bf16 v[20:23], v[172:175], v[204:207], v[20:23]
	v_mfma_f32_16x16x32_bf16 v[16:19], v[180:183], v[204:207], v[16:19]
	v_mfma_f32_16x16x32_bf16 v[4:7], v[172:175], v[212:215], v[4:7]
	v_mfma_f32_16x16x32_bf16 v[0:3], v[180:183], v[212:215], v[0:3]
	s_setprio 2
	s_add_i32 s66, 0, 0x18000
	s_add_i32 s67, 0, 0x1c000
	v_add_u32_e32 v156, s66, v162
	v_add_u32_e32 v167, s67, v162
	ds_read_b128 v[144:147], v156
	ds_read_b128 v[148:151], v156 offset:1024
	ds_read_b128 v[152:155], v156 offset:2048
	ds_read_b128 v[156:159], v156 offset:3072
	ds_read_b128 v[168:171], v167
	ds_read_b128 v[172:175], v167 offset:1024
	ds_read_b128 v[176:179], v167 offset:2048
	ds_read_b128 v[180:183], v167 offset:3072
	s_add_u32 s40, s40, 0x40000
	s_addc_u32 s41, s41, 0
	s_mov_b32 m0, s54
	v_lshl_add_u64 v[222:223], s[40:41], 0, v[134:135]
	ds_read_b128 v[184:187], v165 offset:32768
	ds_read_b128 v[188:191], v165 offset:33792
	ds_read_b128 v[192:195], v165 offset:34816
	ds_read_b128 v[196:199], v165 offset:35840
	ds_read_b128 v[200:203], v165 offset:36864
	ds_read_b128 v[204:207], v165 offset:37888
	ds_read_b128 v[208:211], v165 offset:38912
	ds_read_b128 v[212:215], v165 offset:39936
	global_load_lds_dwordx4 v[222:223], off
	s_mov_b32 m0, s55
	v_lshl_add_u64 v[222:223], s[40:41], 0, v[130:131]
	global_load_lds_dwordx4 v[222:223], off
	s_waitcnt vmcnt(8)
	s_waitcnt lgkmcnt(0)
	s_barrier
	s_setprio 1
	s_waitcnt lgkmcnt(0)
	v_mfma_f32_16x16x32_bf16 v[124:127], v[144:147], v[184:187], v[124:127]
	v_mfma_f32_16x16x32_bf16 v[120:123], v[152:155], v[184:187], v[120:123]
	v_mfma_f32_16x16x32_bf16 v[108:111], v[144:147], v[192:195], v[108:111]
	v_mfma_f32_16x16x32_bf16 v[104:107], v[152:155], v[192:195], v[104:107]
	v_mfma_f32_16x16x32_bf16 v[92:95], v[144:147], v[200:203], v[92:95]
	v_mfma_f32_16x16x32_bf16 v[88:91], v[152:155], v[200:203], v[88:91]
	v_mfma_f32_16x16x32_bf16 v[76:79], v[144:147], v[208:211], v[76:79]
	v_mfma_f32_16x16x32_bf16 v[72:75], v[152:155], v[208:211], v[72:75]
	v_mfma_f32_16x16x32_bf16 v[124:127], v[148:151], v[188:191], v[124:127]
	v_mfma_f32_16x16x32_bf16 v[120:123], v[156:159], v[188:191], v[120:123]
	v_mfma_f32_16x16x32_bf16 v[108:111], v[148:151], v[196:199], v[108:111]
	v_mfma_f32_16x16x32_bf16 v[104:107], v[156:159], v[196:199], v[104:107]
	v_mfma_f32_16x16x32_bf16 v[92:95], v[148:151], v[204:207], v[92:95]
	v_mfma_f32_16x16x32_bf16 v[88:91], v[156:159], v[204:207], v[88:91]
	v_mfma_f32_16x16x32_bf16 v[76:79], v[148:151], v[212:215], v[76:79]
	v_mfma_f32_16x16x32_bf16 v[72:75], v[156:159], v[212:215], v[72:75]
	s_setprio 0
	s_setprio 1
	v_mfma_f32_16x16x32_bf16 v[116:119], v[168:171], v[184:187], v[116:119]
	v_mfma_f32_16x16x32_bf16 v[112:115], v[176:179], v[184:187], v[112:115]
	v_mfma_f32_16x16x32_bf16 v[100:103], v[168:171], v[192:195], v[100:103]
	v_mfma_f32_16x16x32_bf16 v[96:99], v[176:179], v[192:195], v[96:99]
	v_mfma_f32_16x16x32_bf16 v[84:87], v[168:171], v[200:203], v[84:87]
	v_mfma_f32_16x16x32_bf16 v[80:83], v[176:179], v[200:203], v[80:83]
	v_mfma_f32_16x16x32_bf16 v[68:71], v[168:171], v[208:211], v[68:71]
	v_mfma_f32_16x16x32_bf16 v[64:67], v[176:179], v[208:211], v[64:67]
	v_mfma_f32_16x16x32_bf16 v[116:119], v[172:175], v[188:191], v[116:119]
	v_mfma_f32_16x16x32_bf16 v[112:115], v[180:183], v[188:191], v[112:115]
	v_mfma_f32_16x16x32_bf16 v[100:103], v[172:175], v[196:199], v[100:103]
	v_mfma_f32_16x16x32_bf16 v[96:99], v[180:183], v[196:199], v[96:99]
	s_setprio 2
	s_barrier
	v_mfma_f32_16x16x32_bf16 v[84:87], v[172:175], v[204:207], v[84:87]
	v_mfma_f32_16x16x32_bf16 v[80:83], v[180:183], v[204:207], v[80:83]
	v_mfma_f32_16x16x32_bf16 v[68:71], v[172:175], v[212:215], v[68:71]
	v_mfma_f32_16x16x32_bf16 v[64:67], v[180:183], v[212:215], v[64:67]
	s_setprio 2
	s_add_i32 s40, s66, s47
	v_lshl_add_u64 v[160:161], v[160:161], 0, s[16:17]
	s_mov_b32 m0, s40
	ds_read_b128 v[184:187], v165 offset:49152
	ds_read_b128 v[188:191], v165 offset:50176
	ds_read_b128 v[192:195], v165 offset:51200
	ds_read_b128 v[196:199], v165 offset:52224
	ds_read_b128 v[200:203], v165 offset:53248
	ds_read_b128 v[204:207], v165 offset:54272
	ds_read_b128 v[208:211], v165 offset:55296
	ds_read_b128 v[212:215], v165 offset:56320
	global_load_lds_dwordx4 v[160:161], off
	s_add_i32 m0, s40, 0x2000
	s_add_u32 s38, s38, 0x40080
	v_lshl_add_u64 v[160:161], v[216:217], 0, s[16:17]
	s_addc_u32 s39, s39, 0
	s_add_i32 s40, s67, s47
	global_load_lds_dwordx4 v[160:161], off
	s_mov_b32 m0, s40
	v_lshl_add_u64 v[160:161], s[38:39], 0, v[132:133]
	global_load_lds_dwordx4 v[160:161], off
	s_add_i32 m0, s40, 0x2000
	v_lshl_add_u64 v[160:161], s[38:39], 0, v[128:129]
	global_load_lds_dwordx4 v[160:161], off
	s_mov_b32 m0, s57
	v_lshl_add_u64 v[160:161], v[218:219], 0, s[16:17]
	global_load_lds_dwordx4 v[160:161], off
	s_mov_b32 m0, s58
	v_lshl_add_u64 v[160:161], v[220:221], 0, s[16:17]
	global_load_lds_dwordx4 v[160:161], off
	s_waitcnt vmcnt(8)
	s_waitcnt lgkmcnt(0)
	s_barrier
	s_setprio 1
	s_waitcnt lgkmcnt(0)
	v_mfma_f32_16x16x32_bf16 v[60:63], v[144:147], v[184:187], v[60:63]
	v_mfma_f32_16x16x32_bf16 v[56:59], v[152:155], v[184:187], v[56:59]
	v_mfma_f32_16x16x32_bf16 v[44:47], v[144:147], v[192:195], v[44:47]
	v_mfma_f32_16x16x32_bf16 v[40:43], v[152:155], v[192:195], v[40:43]
	v_mfma_f32_16x16x32_bf16 v[28:31], v[144:147], v[200:203], v[28:31]
	v_mfma_f32_16x16x32_bf16 v[24:27], v[152:155], v[200:203], v[24:27]
	v_mfma_f32_16x16x32_bf16 v[12:15], v[144:147], v[208:211], v[12:15]
	v_mfma_f32_16x16x32_bf16 v[8:11], v[152:155], v[208:211], v[8:11]
	v_mfma_f32_16x16x32_bf16 v[60:63], v[148:151], v[188:191], v[60:63]
	v_mfma_f32_16x16x32_bf16 v[56:59], v[156:159], v[188:191], v[56:59]
	v_mfma_f32_16x16x32_bf16 v[44:47], v[148:151], v[196:199], v[44:47]
	v_mfma_f32_16x16x32_bf16 v[40:43], v[156:159], v[196:199], v[40:43]
	v_mfma_f32_16x16x32_bf16 v[28:31], v[148:151], v[204:207], v[28:31]
	v_mfma_f32_16x16x32_bf16 v[24:27], v[156:159], v[204:207], v[24:27]
	v_mfma_f32_16x16x32_bf16 v[12:15], v[148:151], v[212:215], v[12:15]
	v_mfma_f32_16x16x32_bf16 v[8:11], v[156:159], v[212:215], v[8:11]
	s_setprio 0
	s_setprio 1
	v_mfma_f32_16x16x32_bf16 v[52:55], v[168:171], v[184:187], v[52:55]
	v_mfma_f32_16x16x32_bf16 v[48:51], v[176:179], v[184:187], v[48:51]
	v_mfma_f32_16x16x32_bf16 v[36:39], v[168:171], v[192:195], v[36:39]
	v_mfma_f32_16x16x32_bf16 v[32:35], v[176:179], v[192:195], v[32:35]
	v_mfma_f32_16x16x32_bf16 v[20:23], v[168:171], v[200:203], v[20:23]
	v_mfma_f32_16x16x32_bf16 v[16:19], v[176:179], v[200:203], v[16:19]
	v_mfma_f32_16x16x32_bf16 v[4:7], v[168:171], v[208:211], v[4:7]
	v_mfma_f32_16x16x32_bf16 v[0:3], v[176:179], v[208:211], v[0:3]
	v_mfma_f32_16x16x32_bf16 v[52:55], v[172:175], v[188:191], v[52:55]
	v_mfma_f32_16x16x32_bf16 v[48:51], v[180:183], v[188:191], v[48:51]
	v_mfma_f32_16x16x32_bf16 v[36:39], v[172:175], v[196:199], v[36:39]
	v_mfma_f32_16x16x32_bf16 v[32:35], v[180:183], v[196:199], v[32:35]
	s_setprio 2
	s_barrier
	v_mfma_f32_16x16x32_bf16 v[20:23], v[172:175], v[204:207], v[20:23]
	v_mfma_f32_16x16x32_bf16 v[16:19], v[180:183], v[204:207], v[16:19]
	v_mfma_f32_16x16x32_bf16 v[4:7], v[172:175], v[212:215], v[4:7]
	v_mfma_f32_16x16x32_bf16 v[0:3], v[180:183], v[212:215], v[0:3]
	s_setprio 0
	s_add_i32 s65, s65, 2
	s_add_u32 s36, s36, 0x100
	s_addc_u32 s37, s37, 0
	s_add_u32 s63, s63, 0x100
	s_addc_u32 s64, s64, 0
	s_cmp_gt_u32 s65, 13
	s_cbranch_scc0 .LBB0_784

.LBB0_865:
	s_add_u32 s62, s28, 0x100
	s_addc_u32 s63, s29, 0
	s_mov_b32 s64, -2
	ds_read_b128 v[120:123], v233
	ds_read_b128 v[124:127], v233 offset:1024
	ds_read_b128 v[136:139], v233 offset:2048
	ds_read_b128 v[140:143], v233 offset:3072
	ds_read_b128 v[144:147], v234
	ds_read_b128 v[148:151], v234 offset:1024
	ds_read_b128 v[152:155], v234 offset:2048
	ds_read_b128 v[156:159], v234 offset:3072
	s_add_u32 s28, s26, 0x100
	s_addc_u32 s29, s27, 0
	s_cmp_eq_u32 s64, 40
	s_cselect_b32 s37, s7, s29
	s_cselect_b32 s36, s6, s28
	s_cselect_b32 s31, s25, s63
	s_cselect_b32 s30, s24, s62
	v_lshl_add_u64 v[208:209], s[26:27], 0, v[192:193]
	s_add_i32 m0, s44, 0xc000
	ds_read_b128 v[160:163], v235
	ds_read_b128 v[164:167], v235 offset:1024
	ds_read_b128 v[168:171], v235 offset:2048
	ds_read_b128 v[172:175], v235 offset:3072
	ds_read_b128 v[176:179], v235 offset:4096
	ds_read_b128 v[180:183], v235 offset:5120
	ds_read_b128 v[200:203], v235 offset:6144
	ds_read_b128 v[204:207], v235 offset:7168
	global_load_lds_dwordx4 v[208:209], off
	s_add_i32 m0, s44, 0xe000
	v_lshl_add_u64 v[208:209], s[26:27], 0, v[194:195]
	global_load_lds_dwordx4 v[208:209], off
	s_waitcnt vmcnt(8)
	s_waitcnt lgkmcnt(0)
	s_barrier
	s_setprio 1
	s_waitcnt lgkmcnt(0)
	v_mfma_f32_16x16x32_bf16 v[132:135], v[120:123], v[160:163], 0
	v_mfma_f32_16x16x32_bf16 v[128:131], v[136:139], v[160:163], 0
	v_mfma_f32_16x16x32_bf16 v[108:111], v[120:123], v[168:171], 0
	v_mfma_f32_16x16x32_bf16 v[104:107], v[136:139], v[168:171], 0
	v_mfma_f32_16x16x32_bf16 v[92:95], v[120:123], v[176:179], 0
	v_mfma_f32_16x16x32_bf16 v[88:91], v[136:139], v[176:179], 0
	v_mfma_f32_16x16x32_bf16 v[76:79], v[120:123], v[200:203], 0
	v_mfma_f32_16x16x32_bf16 v[72:75], v[136:139], v[200:203], 0
	v_mfma_f32_16x16x32_bf16 v[132:135], v[124:127], v[164:167], v[132:135]
	v_mfma_f32_16x16x32_bf16 v[128:131], v[140:143], v[164:167], v[128:131]
	v_mfma_f32_16x16x32_bf16 v[108:111], v[124:127], v[172:175], v[108:111]
	v_mfma_f32_16x16x32_bf16 v[104:107], v[140:143], v[172:175], v[104:107]
	v_mfma_f32_16x16x32_bf16 v[92:95], v[124:127], v[180:183], v[92:95]
	v_mfma_f32_16x16x32_bf16 v[88:91], v[140:143], v[180:183], v[88:91]
	v_mfma_f32_16x16x32_bf16 v[76:79], v[124:127], v[204:207], v[76:79]
	v_mfma_f32_16x16x32_bf16 v[72:75], v[140:143], v[204:207], v[72:75]
	s_setprio 0
	s_setprio 1
	v_mfma_f32_16x16x32_bf16 v[116:119], v[144:147], v[160:163], 0
	v_mfma_f32_16x16x32_bf16 v[112:115], v[152:155], v[160:163], 0
	v_mfma_f32_16x16x32_bf16 v[100:103], v[144:147], v[168:171], 0
	v_mfma_f32_16x16x32_bf16 v[96:99], v[152:155], v[168:171], 0
	v_mfma_f32_16x16x32_bf16 v[84:87], v[144:147], v[176:179], 0
	v_mfma_f32_16x16x32_bf16 v[80:83], v[152:155], v[176:179], 0
	v_mfma_f32_16x16x32_bf16 v[68:71], v[144:147], v[200:203], 0
	v_mfma_f32_16x16x32_bf16 v[64:67], v[152:155], v[200:203], 0
	v_mfma_f32_16x16x32_bf16 v[116:119], v[148:151], v[164:167], v[116:119]
	v_mfma_f32_16x16x32_bf16 v[112:115], v[156:159], v[164:167], v[112:115]
	v_mfma_f32_16x16x32_bf16 v[100:103], v[148:151], v[172:175], v[100:103]
	v_mfma_f32_16x16x32_bf16 v[96:99], v[156:159], v[172:175], v[96:99]
	s_setprio 2
	s_barrier
	v_mfma_f32_16x16x32_bf16 v[84:87], v[148:151], v[180:183], v[84:87]
	v_mfma_f32_16x16x32_bf16 v[80:83], v[156:159], v[180:183], v[80:83]
	v_mfma_f32_16x16x32_bf16 v[68:71], v[148:151], v[204:207], v[68:71]
	v_mfma_f32_16x16x32_bf16 v[64:67], v[156:159], v[204:207], v[64:67]
	s_setprio 2
	s_add_i32 s26, s56, s43
	v_lshl_add_u64 v[208:209], s[30:31], 0, v[186:187]
	s_mov_b32 m0, s26
	ds_read_b128 v[160:163], v235 offset:16384
	ds_read_b128 v[164:167], v235 offset:17408
	ds_read_b128 v[168:171], v235 offset:18432
	ds_read_b128 v[172:175], v235 offset:19456
	ds_read_b128 v[176:179], v235 offset:20480
	ds_read_b128 v[180:183], v235 offset:21504
	ds_read_b128 v[200:203], v235 offset:22528
	ds_read_b128 v[204:207], v235 offset:23552
	global_load_lds_dwordx4 v[208:209], off
	s_add_i32 m0, s26, 0x2000
	s_add_u32 s26, s30, 0xb0000
	v_lshl_add_u64 v[210:211], s[30:31], 0, v[190:191]
	s_addc_u32 s27, s31, 0
	s_add_i32 s65, s57, s43
	global_load_lds_dwordx4 v[210:211], off
	v_lshl_add_u64 v[212:213], s[26:27], 0, v[186:187]
	s_mov_b32 m0, s65
	v_lshl_add_u64 v[214:215], s[36:37], 0, v[188:189]
	global_load_lds_dwordx4 v[212:213], off
	s_add_i32 m0, s65, 0x2000
	v_lshl_add_u64 v[212:213], s[26:27], 0, v[190:191]
	global_load_lds_dwordx4 v[212:213], off
	s_mov_b32 m0, s44
	v_lshl_add_u64 v[212:213], s[36:37], 0, v[184:185]
	global_load_lds_dwordx4 v[212:213], off
	s_mov_b32 m0, s45
	s_nop 0
	global_load_lds_dwordx4 v[214:215], off
	s_waitcnt vmcnt(8)
	s_waitcnt lgkmcnt(0)
	s_barrier
	s_setprio 1
	s_waitcnt lgkmcnt(0)
	v_mfma_f32_16x16x32_bf16 v[60:63], v[120:123], v[160:163], 0
	v_mfma_f32_16x16x32_bf16 v[56:59], v[136:139], v[160:163], 0
	v_mfma_f32_16x16x32_bf16 v[44:47], v[120:123], v[168:171], 0
	v_mfma_f32_16x16x32_bf16 v[40:43], v[136:139], v[168:171], 0
	v_mfma_f32_16x16x32_bf16 v[28:31], v[120:123], v[176:179], 0
	v_mfma_f32_16x16x32_bf16 v[24:27], v[136:139], v[176:179], 0
	v_mfma_f32_16x16x32_bf16 v[12:15], v[120:123], v[200:203], 0
	v_mfma_f32_16x16x32_bf16 v[8:11], v[136:139], v[200:203], 0
	v_mfma_f32_16x16x32_bf16 v[60:63], v[124:127], v[164:167], v[60:63]
	v_mfma_f32_16x16x32_bf16 v[56:59], v[140:143], v[164:167], v[56:59]
	v_mfma_f32_16x16x32_bf16 v[44:47], v[124:127], v[172:175], v[44:47]
	v_mfma_f32_16x16x32_bf16 v[40:43], v[140:143], v[172:175], v[40:43]
	v_mfma_f32_16x16x32_bf16 v[28:31], v[124:127], v[180:183], v[28:31]
	v_mfma_f32_16x16x32_bf16 v[24:27], v[140:143], v[180:183], v[24:27]
	v_mfma_f32_16x16x32_bf16 v[12:15], v[124:127], v[204:207], v[12:15]
	v_mfma_f32_16x16x32_bf16 v[8:11], v[140:143], v[204:207], v[8:11]
	s_setprio 0
	s_setprio 1
	v_mfma_f32_16x16x32_bf16 v[52:55], v[144:147], v[160:163], 0
	v_mfma_f32_16x16x32_bf16 v[48:51], v[152:155], v[160:163], 0
	v_mfma_f32_16x16x32_bf16 v[36:39], v[144:147], v[168:171], 0
	v_mfma_f32_16x16x32_bf16 v[32:35], v[152:155], v[168:171], 0
	v_mfma_f32_16x16x32_bf16 v[20:23], v[144:147], v[176:179], 0
	v_mfma_f32_16x16x32_bf16 v[16:19], v[152:155], v[176:179], 0
	v_mfma_f32_16x16x32_bf16 v[4:7], v[144:147], v[200:203], 0
	v_mfma_f32_16x16x32_bf16 v[0:3], v[152:155], v[200:203], 0
	v_mfma_f32_16x16x32_bf16 v[52:55], v[148:151], v[164:167], v[52:55]
	v_mfma_f32_16x16x32_bf16 v[48:51], v[156:159], v[164:167], v[48:51]
	v_mfma_f32_16x16x32_bf16 v[36:39], v[148:151], v[172:175], v[36:39]
	v_mfma_f32_16x16x32_bf16 v[32:35], v[156:159], v[172:175], v[32:35]
	s_setprio 2
	s_barrier
	v_mfma_f32_16x16x32_bf16 v[20:23], v[148:151], v[180:183], v[20:23]
	v_mfma_f32_16x16x32_bf16 v[16:19], v[156:159], v[180:183], v[16:19]
	v_mfma_f32_16x16x32_bf16 v[4:7], v[148:151], v[204:207], v[4:7]
	v_mfma_f32_16x16x32_bf16 v[0:3], v[156:159], v[204:207], v[0:3]
	s_setprio 2
	s_add_i32 s65, 0, 0x18000
	s_add_i32 s66, 0, 0x1c000
	v_add_u32_e32 v140, s65, v232
	v_add_u32_e32 v156, s66, v232
	ds_read_b128 v[120:123], v140
	ds_read_b128 v[124:127], v140 offset:1024
	ds_read_b128 v[136:139], v140 offset:2048
	ds_read_b128 v[140:143], v140 offset:3072
	ds_read_b128 v[144:147], v156
	ds_read_b128 v[148:151], v156 offset:1024
	ds_read_b128 v[152:155], v156 offset:2048
	ds_read_b128 v[156:159], v156 offset:3072
	s_add_u32 s26, s36, 0xb0000
	s_addc_u32 s27, s37, 0
	s_mov_b32 m0, s46
	v_lshl_add_u64 v[216:217], s[26:27], 0, v[184:185]
	ds_read_b128 v[160:163], v235 offset:32768
	ds_read_b128 v[164:167], v235 offset:33792
	ds_read_b128 v[168:171], v235 offset:34816
	ds_read_b128 v[172:175], v235 offset:35840
	ds_read_b128 v[176:179], v235 offset:36864
	ds_read_b128 v[180:183], v235 offset:37888
	ds_read_b128 v[200:203], v235 offset:38912
	ds_read_b128 v[204:207], v235 offset:39936
	global_load_lds_dwordx4 v[216:217], off
	s_mov_b32 m0, s47
	v_lshl_add_u64 v[216:217], s[26:27], 0, v[188:189]
	global_load_lds_dwordx4 v[216:217], off
	s_waitcnt vmcnt(8)
	s_waitcnt lgkmcnt(0)
	s_barrier
	s_setprio 1
	s_waitcnt lgkmcnt(0)
	v_mfma_f32_16x16x32_bf16 v[132:135], v[120:123], v[160:163], v[132:135]
	v_mfma_f32_16x16x32_bf16 v[128:131], v[136:139], v[160:163], v[128:131]
	v_mfma_f32_16x16x32_bf16 v[108:111], v[120:123], v[168:171], v[108:111]
	v_mfma_f32_16x16x32_bf16 v[104:107], v[136:139], v[168:171], v[104:107]
	v_mfma_f32_16x16x32_bf16 v[92:95], v[120:123], v[176:179], v[92:95]
	v_mfma_f32_16x16x32_bf16 v[88:91], v[136:139], v[176:179], v[88:91]
	v_mfma_f32_16x16x32_bf16 v[76:79], v[120:123], v[200:203], v[76:79]
	v_mfma_f32_16x16x32_bf16 v[72:75], v[136:139], v[200:203], v[72:75]
	v_mfma_f32_16x16x32_bf16 v[132:135], v[124:127], v[164:167], v[132:135]
	v_mfma_f32_16x16x32_bf16 v[128:131], v[140:143], v[164:167], v[128:131]
	v_mfma_f32_16x16x32_bf16 v[108:111], v[124:127], v[172:175], v[108:111]
	v_mfma_f32_16x16x32_bf16 v[104:107], v[140:143], v[172:175], v[104:107]
	v_mfma_f32_16x16x32_bf16 v[92:95], v[124:127], v[180:183], v[92:95]
	v_mfma_f32_16x16x32_bf16 v[88:91], v[140:143], v[180:183], v[88:91]
	v_mfma_f32_16x16x32_bf16 v[76:79], v[124:127], v[204:207], v[76:79]
	v_mfma_f32_16x16x32_bf16 v[72:75], v[140:143], v[204:207], v[72:75]
	s_setprio 0
	s_setprio 1
	v_mfma_f32_16x16x32_bf16 v[116:119], v[144:147], v[160:163], v[116:119]
	v_mfma_f32_16x16x32_bf16 v[112:115], v[152:155], v[160:163], v[112:115]
	v_mfma_f32_16x16x32_bf16 v[100:103], v[144:147], v[168:171], v[100:103]
	v_mfma_f32_16x16x32_bf16 v[96:99], v[152:155], v[168:171], v[96:99]
	v_mfma_f32_16x16x32_bf16 v[84:87], v[144:147], v[176:179], v[84:87]
	v_mfma_f32_16x16x32_bf16 v[80:83], v[152:155], v[176:179], v[80:83]
	v_mfma_f32_16x16x32_bf16 v[68:71], v[144:147], v[200:203], v[68:71]
	v_mfma_f32_16x16x32_bf16 v[64:67], v[152:155], v[200:203], v[64:67]
	v_mfma_f32_16x16x32_bf16 v[116:119], v[148:151], v[164:167], v[116:119]
	v_mfma_f32_16x16x32_bf16 v[112:115], v[156:159], v[164:167], v[112:115]
	v_mfma_f32_16x16x32_bf16 v[100:103], v[148:151], v[172:175], v[100:103]
	v_mfma_f32_16x16x32_bf16 v[96:99], v[156:159], v[172:175], v[96:99]
	s_setprio 2
	s_barrier
	v_mfma_f32_16x16x32_bf16 v[84:87], v[148:151], v[180:183], v[84:87]
	v_mfma_f32_16x16x32_bf16 v[80:83], v[156:159], v[180:183], v[80:83]
	v_mfma_f32_16x16x32_bf16 v[68:71], v[148:151], v[204:207], v[68:71]
	v_mfma_f32_16x16x32_bf16 v[64:67], v[156:159], v[204:207], v[64:67]
	s_setprio 2
	s_add_i32 s26, s65, s43
	v_lshl_add_u64 v[208:209], v[208:209], 0, s[20:21]
	s_mov_b32 m0, s26
	ds_read_b128 v[160:163], v235 offset:49152
	ds_read_b128 v[164:167], v235 offset:50176
	ds_read_b128 v[168:171], v235 offset:51200
	ds_read_b128 v[172:175], v235 offset:52224
	ds_read_b128 v[176:179], v235 offset:53248
	ds_read_b128 v[180:183], v235 offset:54272
	ds_read_b128 v[200:203], v235 offset:55296
	ds_read_b128 v[204:207], v235 offset:56320
	global_load_lds_dwordx4 v[208:209], off
	s_add_i32 m0, s26, 0x2000
	s_add_u32 s26, s30, 0xb0080
	v_lshl_add_u64 v[208:209], v[210:211], 0, s[20:21]
	s_addc_u32 s27, s31, 0
	s_add_i32 s30, s66, s43
	global_load_lds_dwordx4 v[208:209], off
	s_mov_b32 m0, s30
	v_lshl_add_u64 v[208:209], s[26:27], 0, v[186:187]
	global_load_lds_dwordx4 v[208:209], off
	s_add_i32 m0, s30, 0x2000
	v_lshl_add_u64 v[208:209], s[26:27], 0, v[190:191]
	global_load_lds_dwordx4 v[208:209], off
	s_mov_b32 m0, s49
	v_lshl_add_u64 v[208:209], v[212:213], 0, s[20:21]
	global_load_lds_dwordx4 v[208:209], off
	s_mov_b32 m0, s50
	v_lshl_add_u64 v[208:209], v[214:215], 0, s[20:21]
	global_load_lds_dwordx4 v[208:209], off
	s_waitcnt vmcnt(8)
	s_waitcnt lgkmcnt(0)
	s_barrier
	s_setprio 1
	s_waitcnt lgkmcnt(0)
	v_mfma_f32_16x16x32_bf16 v[60:63], v[120:123], v[160:163], v[60:63]
	v_mfma_f32_16x16x32_bf16 v[56:59], v[136:139], v[160:163], v[56:59]
	v_mfma_f32_16x16x32_bf16 v[44:47], v[120:123], v[168:171], v[44:47]
	v_mfma_f32_16x16x32_bf16 v[40:43], v[136:139], v[168:171], v[40:43]
	v_mfma_f32_16x16x32_bf16 v[28:31], v[120:123], v[176:179], v[28:31]
	v_mfma_f32_16x16x32_bf16 v[24:27], v[136:139], v[176:179], v[24:27]
	v_mfma_f32_16x16x32_bf16 v[12:15], v[120:123], v[200:203], v[12:15]
	v_mfma_f32_16x16x32_bf16 v[8:11], v[136:139], v[200:203], v[8:11]
	v_mfma_f32_16x16x32_bf16 v[60:63], v[124:127], v[164:167], v[60:63]
	v_mfma_f32_16x16x32_bf16 v[56:59], v[140:143], v[164:167], v[56:59]
	v_mfma_f32_16x16x32_bf16 v[44:47], v[124:127], v[172:175], v[44:47]
	v_mfma_f32_16x16x32_bf16 v[40:43], v[140:143], v[172:175], v[40:43]
	v_mfma_f32_16x16x32_bf16 v[28:31], v[124:127], v[180:183], v[28:31]
	v_mfma_f32_16x16x32_bf16 v[24:27], v[140:143], v[180:183], v[24:27]
	v_mfma_f32_16x16x32_bf16 v[12:15], v[124:127], v[204:207], v[12:15]
	v_mfma_f32_16x16x32_bf16 v[8:11], v[140:143], v[204:207], v[8:11]
	s_setprio 0
	s_setprio 1
	v_mfma_f32_16x16x32_bf16 v[52:55], v[144:147], v[160:163], v[52:55]
	v_mfma_f32_16x16x32_bf16 v[48:51], v[152:155], v[160:163], v[48:51]
	v_mfma_f32_16x16x32_bf16 v[36:39], v[144:147], v[168:171], v[36:39]
	v_mfma_f32_16x16x32_bf16 v[32:35], v[152:155], v[168:171], v[32:35]
	v_mfma_f32_16x16x32_bf16 v[20:23], v[144:147], v[176:179], v[20:23]
	v_mfma_f32_16x16x32_bf16 v[16:19], v[152:155], v[176:179], v[16:19]
	v_mfma_f32_16x16x32_bf16 v[4:7], v[144:147], v[200:203], v[4:7]
	v_mfma_f32_16x16x32_bf16 v[0:3], v[152:155], v[200:203], v[0:3]
	v_mfma_f32_16x16x32_bf16 v[52:55], v[148:151], v[164:167], v[52:55]
	v_mfma_f32_16x16x32_bf16 v[48:51], v[156:159], v[164:167], v[48:51]
	v_mfma_f32_16x16x32_bf16 v[36:39], v[148:151], v[172:175], v[36:39]
	v_mfma_f32_16x16x32_bf16 v[32:35], v[156:159], v[172:175], v[32:35]
	s_setprio 2
	s_barrier
	v_mfma_f32_16x16x32_bf16 v[20:23], v[148:151], v[180:183], v[20:23]
	v_mfma_f32_16x16x32_bf16 v[16:19], v[156:159], v[180:183], v[16:19]
	v_mfma_f32_16x16x32_bf16 v[4:7], v[148:151], v[204:207], v[4:7]
	v_mfma_f32_16x16x32_bf16 v[0:3], v[156:159], v[204:207], v[0:3]
	s_setprio 2
	s_add_i32 s64, s64, 2
	s_add_u32 s62, s62, 0x100
	s_addc_u32 s63, s63, 0
	s_cmp_gt_u32 s64, 41
	s_mov_b64 s[26:27], s[28:29]
.LBB0_866:
	ds_read_b128 v[120:123], v233
	ds_read_b128 v[124:127], v233 offset:1024
	ds_read_b128 v[136:139], v233 offset:2048
	ds_read_b128 v[140:143], v233 offset:3072
	ds_read_b128 v[144:147], v234
	ds_read_b128 v[148:151], v234 offset:1024
	ds_read_b128 v[152:155], v234 offset:2048
	ds_read_b128 v[156:159], v234 offset:3072
	s_add_u32 s28, s26, 0x100
	s_addc_u32 s29, s27, 0
	s_cmp_eq_u32 s64, 40
	s_cselect_b32 s37, s7, s29
	s_cselect_b32 s36, s6, s28
	s_cselect_b32 s31, s25, s63
	s_cselect_b32 s30, s24, s62
	v_lshl_add_u64 v[208:209], s[26:27], 0, v[192:193]
	s_add_i32 m0, s44, 0xc000
	ds_read_b128 v[160:163], v235
	ds_read_b128 v[164:167], v235 offset:1024
	ds_read_b128 v[168:171], v235 offset:2048
	ds_read_b128 v[172:175], v235 offset:3072
	ds_read_b128 v[176:179], v235 offset:4096
	ds_read_b128 v[180:183], v235 offset:5120
	ds_read_b128 v[200:203], v235 offset:6144
	ds_read_b128 v[204:207], v235 offset:7168
	global_load_lds_dwordx4 v[208:209], off
	s_add_i32 m0, s44, 0xe000
	v_lshl_add_u64 v[208:209], s[26:27], 0, v[194:195]
	global_load_lds_dwordx4 v[208:209], off
	s_waitcnt vmcnt(8)
	s_waitcnt lgkmcnt(0)
	s_barrier
	s_setprio 1
	s_waitcnt lgkmcnt(0)
	v_mfma_f32_16x16x32_bf16 v[132:135], v[120:123], v[160:163], v[132:135]
	v_mfma_f32_16x16x32_bf16 v[128:131], v[136:139], v[160:163], v[128:131]
	v_mfma_f32_16x16x32_bf16 v[108:111], v[120:123], v[168:171], v[108:111]
	v_mfma_f32_16x16x32_bf16 v[104:107], v[136:139], v[168:171], v[104:107]
	v_mfma_f32_16x16x32_bf16 v[92:95], v[120:123], v[176:179], v[92:95]
	v_mfma_f32_16x16x32_bf16 v[88:91], v[136:139], v[176:179], v[88:91]
	v_mfma_f32_16x16x32_bf16 v[76:79], v[120:123], v[200:203], v[76:79]
	v_mfma_f32_16x16x32_bf16 v[72:75], v[136:139], v[200:203], v[72:75]
	v_mfma_f32_16x16x32_bf16 v[132:135], v[124:127], v[164:167], v[132:135]
	v_mfma_f32_16x16x32_bf16 v[128:131], v[140:143], v[164:167], v[128:131]
	v_mfma_f32_16x16x32_bf16 v[108:111], v[124:127], v[172:175], v[108:111]
	v_mfma_f32_16x16x32_bf16 v[104:107], v[140:143], v[172:175], v[104:107]
	v_mfma_f32_16x16x32_bf16 v[92:95], v[124:127], v[180:183], v[92:95]
	v_mfma_f32_16x16x32_bf16 v[88:91], v[140:143], v[180:183], v[88:91]
	v_mfma_f32_16x16x32_bf16 v[76:79], v[124:127], v[204:207], v[76:79]
	v_mfma_f32_16x16x32_bf16 v[72:75], v[140:143], v[204:207], v[72:75]
	s_setprio 0
	s_setprio 1
	v_mfma_f32_16x16x32_bf16 v[116:119], v[144:147], v[160:163], v[116:119]
	v_mfma_f32_16x16x32_bf16 v[112:115], v[152:155], v[160:163], v[112:115]
	v_mfma_f32_16x16x32_bf16 v[100:103], v[144:147], v[168:171], v[100:103]
	v_mfma_f32_16x16x32_bf16 v[96:99], v[152:155], v[168:171], v[96:99]
	v_mfma_f32_16x16x32_bf16 v[84:87], v[144:147], v[176:179], v[84:87]
	v_mfma_f32_16x16x32_bf16 v[80:83], v[152:155], v[176:179], v[80:83]
	v_mfma_f32_16x16x32_bf16 v[68:71], v[144:147], v[200:203], v[68:71]
	v_mfma_f32_16x16x32_bf16 v[64:67], v[152:155], v[200:203], v[64:67]
	v_mfma_f32_16x16x32_bf16 v[116:119], v[148:151], v[164:167], v[116:119]
	v_mfma_f32_16x16x32_bf16 v[112:115], v[156:159], v[164:167], v[112:115]
	v_mfma_f32_16x16x32_bf16 v[100:103], v[148:151], v[172:175], v[100:103]
	v_mfma_f32_16x16x32_bf16 v[96:99], v[156:159], v[172:175], v[96:99]
	s_setprio 2
	s_barrier
	v_mfma_f32_16x16x32_bf16 v[84:87], v[148:151], v[180:183], v[84:87]
	v_mfma_f32_16x16x32_bf16 v[80:83], v[156:159], v[180:183], v[80:83]
	v_mfma_f32_16x16x32_bf16 v[68:71], v[148:151], v[204:207], v[68:71]
	v_mfma_f32_16x16x32_bf16 v[64:67], v[156:159], v[204:207], v[64:67]
	s_setprio 2
	s_add_i32 s26, s56, s43
	v_lshl_add_u64 v[208:209], s[30:31], 0, v[186:187]
	s_mov_b32 m0, s26
	ds_read_b128 v[160:163], v235 offset:16384
	ds_read_b128 v[164:167], v235 offset:17408
	ds_read_b128 v[168:171], v235 offset:18432
	ds_read_b128 v[172:175], v235 offset:19456
	ds_read_b128 v[176:179], v235 offset:20480
	ds_read_b128 v[180:183], v235 offset:21504
	ds_read_b128 v[200:203], v235 offset:22528
	ds_read_b128 v[204:207], v235 offset:23552
	global_load_lds_dwordx4 v[208:209], off
	s_add_i32 m0, s26, 0x2000
	s_add_u32 s26, s30, 0xb0000
	v_lshl_add_u64 v[210:211], s[30:31], 0, v[190:191]
	s_addc_u32 s27, s31, 0
	s_add_i32 s65, s57, s43
	global_load_lds_dwordx4 v[210:211], off
	v_lshl_add_u64 v[212:213], s[26:27], 0, v[186:187]
	s_mov_b32 m0, s65
	v_lshl_add_u64 v[214:215], s[36:37], 0, v[188:189]
	global_load_lds_dwordx4 v[212:213], off
	s_add_i32 m0, s65, 0x2000
	v_lshl_add_u64 v[212:213], s[26:27], 0, v[190:191]
	global_load_lds_dwordx4 v[212:213], off
	s_mov_b32 m0, s44
	v_lshl_add_u64 v[212:213], s[36:37], 0, v[184:185]
	global_load_lds_dwordx4 v[212:213], off
	s_mov_b32 m0, s45
	s_nop 0
	global_load_lds_dwordx4 v[214:215], off
	s_waitcnt vmcnt(8)
	s_waitcnt lgkmcnt(0)
	s_barrier
	s_setprio 1
	s_waitcnt lgkmcnt(0)
	v_mfma_f32_16x16x32_bf16 v[60:63], v[120:123], v[160:163], v[60:63]
	v_mfma_f32_16x16x32_bf16 v[56:59], v[136:139], v[160:163], v[56:59]
	v_mfma_f32_16x16x32_bf16 v[44:47], v[120:123], v[168:171], v[44:47]
	v_mfma_f32_16x16x32_bf16 v[40:43], v[136:139], v[168:171], v[40:43]
	v_mfma_f32_16x16x32_bf16 v[28:31], v[120:123], v[176:179], v[28:31]
	v_mfma_f32_16x16x32_bf16 v[24:27], v[136:139], v[176:179], v[24:27]
	v_mfma_f32_16x16x32_bf16 v[12:15], v[120:123], v[200:203], v[12:15]
	v_mfma_f32_16x16x32_bf16 v[8:11], v[136:139], v[200:203], v[8:11]
	v_mfma_f32_16x16x32_bf16 v[60:63], v[124:127], v[164:167], v[60:63]
	v_mfma_f32_16x16x32_bf16 v[56:59], v[140:143], v[164:167], v[56:59]
	v_mfma_f32_16x16x32_bf16 v[44:47], v[124:127], v[172:175], v[44:47]
	v_mfma_f32_16x16x32_bf16 v[40:43], v[140:143], v[172:175], v[40:43]
	v_mfma_f32_16x16x32_bf16 v[28:31], v[124:127], v[180:183], v[28:31]
	v_mfma_f32_16x16x32_bf16 v[24:27], v[140:143], v[180:183], v[24:27]
	v_mfma_f32_16x16x32_bf16 v[12:15], v[124:127], v[204:207], v[12:15]
	v_mfma_f32_16x16x32_bf16 v[8:11], v[140:143], v[204:207], v[8:11]
	s_setprio 0
	s_setprio 1
	v_mfma_f32_16x16x32_bf16 v[52:55], v[144:147], v[160:163], v[52:55]
	v_mfma_f32_16x16x32_bf16 v[48:51], v[152:155], v[160:163], v[48:51]
	v_mfma_f32_16x16x32_bf16 v[36:39], v[144:147], v[168:171], v[36:39]
	v_mfma_f32_16x16x32_bf16 v[32:35], v[152:155], v[168:171], v[32:35]
	v_mfma_f32_16x16x32_bf16 v[20:23], v[144:147], v[176:179], v[20:23]
	v_mfma_f32_16x16x32_bf16 v[16:19], v[152:155], v[176:179], v[16:19]
	v_mfma_f32_16x16x32_bf16 v[4:7], v[144:147], v[200:203], v[4:7]
	v_mfma_f32_16x16x32_bf16 v[0:3], v[152:155], v[200:203], v[0:3]
	v_mfma_f32_16x16x32_bf16 v[52:55], v[148:151], v[164:167], v[52:55]
	v_mfma_f32_16x16x32_bf16 v[48:51], v[156:159], v[164:167], v[48:51]
	v_mfma_f32_16x16x32_bf16 v[36:39], v[148:151], v[172:175], v[36:39]
	v_mfma_f32_16x16x32_bf16 v[32:35], v[156:159], v[172:175], v[32:35]
	s_setprio 2
	s_barrier
	v_mfma_f32_16x16x32_bf16 v[20:23], v[148:151], v[180:183], v[20:23]
	v_mfma_f32_16x16x32_bf16 v[16:19], v[156:159], v[180:183], v[16:19]
	v_mfma_f32_16x16x32_bf16 v[4:7], v[148:151], v[204:207], v[4:7]
	v_mfma_f32_16x16x32_bf16 v[0:3], v[156:159], v[204:207], v[0:3]
	s_setprio 2
	s_add_i32 s65, 0, 0x18000
	s_add_i32 s66, 0, 0x1c000
	v_add_u32_e32 v140, s65, v232
	v_add_u32_e32 v156, s66, v232
	ds_read_b128 v[120:123], v140
	ds_read_b128 v[124:127], v140 offset:1024
	ds_read_b128 v[136:139], v140 offset:2048
	ds_read_b128 v[140:143], v140 offset:3072
	ds_read_b128 v[144:147], v156
	ds_read_b128 v[148:151], v156 offset:1024
	ds_read_b128 v[152:155], v156 offset:2048
	ds_read_b128 v[156:159], v156 offset:3072
	s_add_u32 s26, s36, 0xb0000
	s_addc_u32 s27, s37, 0
	s_mov_b32 m0, s46
	v_lshl_add_u64 v[216:217], s[26:27], 0, v[184:185]
	ds_read_b128 v[160:163], v235 offset:32768
	ds_read_b128 v[164:167], v235 offset:33792
	ds_read_b128 v[168:171], v235 offset:34816
	ds_read_b128 v[172:175], v235 offset:35840
	ds_read_b128 v[176:179], v235 offset:36864
	ds_read_b128 v[180:183], v235 offset:37888
	ds_read_b128 v[200:203], v235 offset:38912
	ds_read_b128 v[204:207], v235 offset:39936
	global_load_lds_dwordx4 v[216:217], off
	s_mov_b32 m0, s47
	v_lshl_add_u64 v[216:217], s[26:27], 0, v[188:189]
	global_load_lds_dwordx4 v[216:217], off
	s_waitcnt vmcnt(8)
	s_waitcnt lgkmcnt(0)
	s_barrier
	s_setprio 1
	s_waitcnt lgkmcnt(0)
	v_mfma_f32_16x16x32_bf16 v[132:135], v[120:123], v[160:163], v[132:135]
	v_mfma_f32_16x16x32_bf16 v[128:131], v[136:139], v[160:163], v[128:131]
	v_mfma_f32_16x16x32_bf16 v[108:111], v[120:123], v[168:171], v[108:111]
	v_mfma_f32_16x16x32_bf16 v[104:107], v[136:139], v[168:171], v[104:107]
	v_mfma_f32_16x16x32_bf16 v[92:95], v[120:123], v[176:179], v[92:95]
	v_mfma_f32_16x16x32_bf16 v[88:91], v[136:139], v[176:179], v[88:91]
	v_mfma_f32_16x16x32_bf16 v[76:79], v[120:123], v[200:203], v[76:79]
	v_mfma_f32_16x16x32_bf16 v[72:75], v[136:139], v[200:203], v[72:75]
	v_mfma_f32_16x16x32_bf16 v[132:135], v[124:127], v[164:167], v[132:135]
	v_mfma_f32_16x16x32_bf16 v[128:131], v[140:143], v[164:167], v[128:131]
	v_mfma_f32_16x16x32_bf16 v[108:111], v[124:127], v[172:175], v[108:111]
	v_mfma_f32_16x16x32_bf16 v[104:107], v[140:143], v[172:175], v[104:107]
	v_mfma_f32_16x16x32_bf16 v[92:95], v[124:127], v[180:183], v[92:95]
	v_mfma_f32_16x16x32_bf16 v[88:91], v[140:143], v[180:183], v[88:91]
	v_mfma_f32_16x16x32_bf16 v[76:79], v[124:127], v[204:207], v[76:79]
	v_mfma_f32_16x16x32_bf16 v[72:75], v[140:143], v[204:207], v[72:75]
	s_setprio 0
	s_setprio 1
	v_mfma_f32_16x16x32_bf16 v[116:119], v[144:147], v[160:163], v[116:119]
	v_mfma_f32_16x16x32_bf16 v[112:115], v[152:155], v[160:163], v[112:115]
	v_mfma_f32_16x16x32_bf16 v[100:103], v[144:147], v[168:171], v[100:103]
	v_mfma_f32_16x16x32_bf16 v[96:99], v[152:155], v[168:171], v[96:99]
	v_mfma_f32_16x16x32_bf16 v[84:87], v[144:147], v[176:179], v[84:87]
	v_mfma_f32_16x16x32_bf16 v[80:83], v[152:155], v[176:179], v[80:83]
	v_mfma_f32_16x16x32_bf16 v[68:71], v[144:147], v[200:203], v[68:71]
	v_mfma_f32_16x16x32_bf16 v[64:67], v[152:155], v[200:203], v[64:67]
	v_mfma_f32_16x16x32_bf16 v[116:119], v[148:151], v[164:167], v[116:119]
	v_mfma_f32_16x16x32_bf16 v[112:115], v[156:159], v[164:167], v[112:115]
	v_mfma_f32_16x16x32_bf16 v[100:103], v[148:151], v[172:175], v[100:103]
	v_mfma_f32_16x16x32_bf16 v[96:99], v[156:159], v[172:175], v[96:99]
	s_setprio 2
	s_barrier
	v_mfma_f32_16x16x32_bf16 v[84:87], v[148:151], v[180:183], v[84:87]
	v_mfma_f32_16x16x32_bf16 v[80:83], v[156:159], v[180:183], v[80:83]
	v_mfma_f32_16x16x32_bf16 v[68:71], v[148:151], v[204:207], v[68:71]
	v_mfma_f32_16x16x32_bf16 v[64:67], v[156:159], v[204:207], v[64:67]
	s_setprio 2
	s_add_i32 s26, s65, s43
	v_lshl_add_u64 v[208:209], v[208:209], 0, s[20:21]
	s_mov_b32 m0, s26
	ds_read_b128 v[160:163], v235 offset:49152
	ds_read_b128 v[164:167], v235 offset:50176
	ds_read_b128 v[168:171], v235 offset:51200
	ds_read_b128 v[172:175], v235 offset:52224
	ds_read_b128 v[176:179], v235 offset:53248
	ds_read_b128 v[180:183], v235 offset:54272
	ds_read_b128 v[200:203], v235 offset:55296
	ds_read_b128 v[204:207], v235 offset:56320
	global_load_lds_dwordx4 v[208:209], off
	s_add_i32 m0, s26, 0x2000
	s_add_u32 s26, s30, 0xb0080
	v_lshl_add_u64 v[208:209], v[210:211], 0, s[20:21]
	s_addc_u32 s27, s31, 0
	s_add_i32 s30, s66, s43
	global_load_lds_dwordx4 v[208:209], off
	s_mov_b32 m0, s30
	v_lshl_add_u64 v[208:209], s[26:27], 0, v[186:187]
	global_load_lds_dwordx4 v[208:209], off
	s_add_i32 m0, s30, 0x2000
	v_lshl_add_u64 v[208:209], s[26:27], 0, v[190:191]
	global_load_lds_dwordx4 v[208:209], off
	s_mov_b32 m0, s49
	v_lshl_add_u64 v[208:209], v[212:213], 0, s[20:21]
	global_load_lds_dwordx4 v[208:209], off
	s_mov_b32 m0, s50
	v_lshl_add_u64 v[208:209], v[214:215], 0, s[20:21]
	global_load_lds_dwordx4 v[208:209], off
	s_waitcnt vmcnt(8)
	s_waitcnt lgkmcnt(0)
	s_barrier
	s_setprio 1
	s_waitcnt lgkmcnt(0)
	v_mfma_f32_16x16x32_bf16 v[60:63], v[120:123], v[160:163], v[60:63]
	v_mfma_f32_16x16x32_bf16 v[56:59], v[136:139], v[160:163], v[56:59]
	v_mfma_f32_16x16x32_bf16 v[44:47], v[120:123], v[168:171], v[44:47]
	v_mfma_f32_16x16x32_bf16 v[40:43], v[136:139], v[168:171], v[40:43]
	v_mfma_f32_16x16x32_bf16 v[28:31], v[120:123], v[176:179], v[28:31]
	v_mfma_f32_16x16x32_bf16 v[24:27], v[136:139], v[176:179], v[24:27]
	v_mfma_f32_16x16x32_bf16 v[12:15], v[120:123], v[200:203], v[12:15]
	v_mfma_f32_16x16x32_bf16 v[8:11], v[136:139], v[200:203], v[8:11]
	v_mfma_f32_16x16x32_bf16 v[60:63], v[124:127], v[164:167], v[60:63]
	v_mfma_f32_16x16x32_bf16 v[56:59], v[140:143], v[164:167], v[56:59]
	v_mfma_f32_16x16x32_bf16 v[44:47], v[124:127], v[172:175], v[44:47]
	v_mfma_f32_16x16x32_bf16 v[40:43], v[140:143], v[172:175], v[40:43]
	v_mfma_f32_16x16x32_bf16 v[28:31], v[124:127], v[180:183], v[28:31]
	v_mfma_f32_16x16x32_bf16 v[24:27], v[140:143], v[180:183], v[24:27]
	v_mfma_f32_16x16x32_bf16 v[12:15], v[124:127], v[204:207], v[12:15]
	v_mfma_f32_16x16x32_bf16 v[8:11], v[140:143], v[204:207], v[8:11]
	s_setprio 0
	s_setprio 1
	v_mfma_f32_16x16x32_bf16 v[52:55], v[144:147], v[160:163], v[52:55]
	v_mfma_f32_16x16x32_bf16 v[48:51], v[152:155], v[160:163], v[48:51]
	v_mfma_f32_16x16x32_bf16 v[36:39], v[144:147], v[168:171], v[36:39]
	v_mfma_f32_16x16x32_bf16 v[32:35], v[152:155], v[168:171], v[32:35]
	v_mfma_f32_16x16x32_bf16 v[20:23], v[144:147], v[176:179], v[20:23]
	v_mfma_f32_16x16x32_bf16 v[16:19], v[152:155], v[176:179], v[16:19]
	v_mfma_f32_16x16x32_bf16 v[4:7], v[144:147], v[200:203], v[4:7]
	v_mfma_f32_16x16x32_bf16 v[0:3], v[152:155], v[200:203], v[0:3]
	v_mfma_f32_16x16x32_bf16 v[52:55], v[148:151], v[164:167], v[52:55]
	v_mfma_f32_16x16x32_bf16 v[48:51], v[156:159], v[164:167], v[48:51]
	v_mfma_f32_16x16x32_bf16 v[36:39], v[148:151], v[172:175], v[36:39]
	v_mfma_f32_16x16x32_bf16 v[32:35], v[156:159], v[172:175], v[32:35]
	s_setprio 2
	s_barrier
	v_mfma_f32_16x16x32_bf16 v[20:23], v[148:151], v[180:183], v[20:23]
	v_mfma_f32_16x16x32_bf16 v[16:19], v[156:159], v[180:183], v[16:19]
	v_mfma_f32_16x16x32_bf16 v[4:7], v[148:151], v[204:207], v[4:7]
	v_mfma_f32_16x16x32_bf16 v[0:3], v[156:159], v[204:207], v[0:3]
	s_setprio 0
	s_add_i32 s64, s64, 2
	s_add_u32 s62, s62, 0x100
	s_addc_u32 s63, s63, 0
	s_cmp_gt_u32 s64, 41
	s_mov_b64 s[26:27], s[28:29]
	s_cbranch_scc0 .LBB0_866

.LBB0_951:
	s_ashr_i32 s27, s26, 31
	s_lshl_b64 s[30:31], s[26:27], 19
	s_add_u32 s30, s47, s30
	s_addc_u32 s31, s48, s31
	s_and_b64 s[36:37], s[4:5], exec
	s_cselect_b32 s27, s31, s7
	s_cselect_b32 s39, s30, s6
	s_ashr_i32 s29, s28, 31
	s_lshl_b64 s[36:37], s[28:29], 19
	s_add_u32 s36, s49, s36
	s_addc_u32 s37, s50, s37
	s_and_b64 s[44:45], s[4:5], exec
	s_cselect_b32 s29, s37, s41
	s_cselect_b32 s43, s36, s40
	s_add_u32 s6, s6, 0x40080
	s_addc_u32 s7, s7, 0
	s_add_u32 s71, s40, 0x100
	s_addc_u32 s72, s41, 0
	s_mov_b32 s73, -2
	ds_read_b128 v[144:147], v179
	ds_read_b128 v[148:151], v179 offset:1024
	ds_read_b128 v[152:155], v179 offset:2048
	ds_read_b128 v[156:159], v179 offset:3072
	ds_read_b128 v[160:163], v180
	ds_read_b128 v[164:167], v180 offset:1024
	ds_read_b128 v[168:171], v180 offset:2048
	ds_read_b128 v[172:175], v180 offset:3072
	s_add_u32 s40, s6, 0xfffc0080
	s_addc_u32 s41, s7, -1
	s_cmp_eq_u32 s73, 12
	s_cselect_b32 s45, s27, s41
	s_cselect_b32 s44, s39, s40
	s_cselect_b32 s41, s29, s72
	s_cselect_b32 s40, s43, s71
	v_lshl_add_u64 v[176:177], s[6:7], 0, v[136:137]
	s_add_i32 m0, s54, 0xc000
	ds_read_b128 v[184:187], v181
	ds_read_b128 v[188:191], v181 offset:1024
	ds_read_b128 v[192:195], v181 offset:2048
	ds_read_b128 v[196:199], v181 offset:3072
	ds_read_b128 v[200:203], v181 offset:4096
	ds_read_b128 v[204:207], v181 offset:5120
	ds_read_b128 v[208:211], v181 offset:6144
	ds_read_b128 v[212:215], v181 offset:7168
	global_load_lds_dwordx4 v[176:177], off
	s_add_i32 m0, s54, 0xe000
	v_lshl_add_u64 v[176:177], s[6:7], 0, v[138:139]
	global_load_lds_dwordx4 v[176:177], off
	s_waitcnt vmcnt(8)
	s_waitcnt lgkmcnt(0)
	s_barrier
	s_setprio 1
	s_waitcnt lgkmcnt(0)
	v_mfma_f32_16x16x32_bf16 v[124:127], v[144:147], v[184:187], 0
	v_mfma_f32_16x16x32_bf16 v[120:123], v[152:155], v[184:187], 0
	v_mfma_f32_16x16x32_bf16 v[108:111], v[144:147], v[192:195], 0
	v_mfma_f32_16x16x32_bf16 v[104:107], v[152:155], v[192:195], 0
	v_mfma_f32_16x16x32_bf16 v[92:95], v[144:147], v[200:203], 0
	v_mfma_f32_16x16x32_bf16 v[88:91], v[152:155], v[200:203], 0
	v_mfma_f32_16x16x32_bf16 v[76:79], v[144:147], v[208:211], 0
	v_mfma_f32_16x16x32_bf16 v[72:75], v[152:155], v[208:211], 0
	v_mfma_f32_16x16x32_bf16 v[124:127], v[148:151], v[188:191], v[124:127]
	v_mfma_f32_16x16x32_bf16 v[120:123], v[156:159], v[188:191], v[120:123]
	v_mfma_f32_16x16x32_bf16 v[108:111], v[148:151], v[196:199], v[108:111]
	v_mfma_f32_16x16x32_bf16 v[104:107], v[156:159], v[196:199], v[104:107]
	v_mfma_f32_16x16x32_bf16 v[92:95], v[148:151], v[204:207], v[92:95]
	v_mfma_f32_16x16x32_bf16 v[88:91], v[156:159], v[204:207], v[88:91]
	v_mfma_f32_16x16x32_bf16 v[76:79], v[148:151], v[212:215], v[76:79]
	v_mfma_f32_16x16x32_bf16 v[72:75], v[156:159], v[212:215], v[72:75]
	s_setprio 0
	s_setprio 1
	v_mfma_f32_16x16x32_bf16 v[116:119], v[160:163], v[184:187], 0
	v_mfma_f32_16x16x32_bf16 v[112:115], v[168:171], v[184:187], 0
	v_mfma_f32_16x16x32_bf16 v[100:103], v[160:163], v[192:195], 0
	v_mfma_f32_16x16x32_bf16 v[96:99], v[168:171], v[192:195], 0
	v_mfma_f32_16x16x32_bf16 v[84:87], v[160:163], v[200:203], 0
	v_mfma_f32_16x16x32_bf16 v[80:83], v[168:171], v[200:203], 0
	v_mfma_f32_16x16x32_bf16 v[68:71], v[160:163], v[208:211], 0
	v_mfma_f32_16x16x32_bf16 v[64:67], v[168:171], v[208:211], 0
	v_mfma_f32_16x16x32_bf16 v[116:119], v[164:167], v[188:191], v[116:119]
	v_mfma_f32_16x16x32_bf16 v[112:115], v[172:175], v[188:191], v[112:115]
	v_mfma_f32_16x16x32_bf16 v[100:103], v[164:167], v[196:199], v[100:103]
	v_mfma_f32_16x16x32_bf16 v[96:99], v[172:175], v[196:199], v[96:99]
	s_setprio 2
	s_barrier
	v_mfma_f32_16x16x32_bf16 v[84:87], v[164:167], v[204:207], v[84:87]
	v_mfma_f32_16x16x32_bf16 v[80:83], v[172:175], v[204:207], v[80:83]
	v_mfma_f32_16x16x32_bf16 v[68:71], v[164:167], v[212:215], v[68:71]
	v_mfma_f32_16x16x32_bf16 v[64:67], v[172:175], v[212:215], v[64:67]
	s_setprio 2
	s_add_i32 s74, s69, s51
	v_lshl_add_u64 v[176:177], s[40:41], 0, v[130:131]
	s_mov_b32 m0, s74
	ds_read_b128 v[184:187], v181 offset:16384
	ds_read_b128 v[188:191], v181 offset:17408
	ds_read_b128 v[192:195], v181 offset:18432
	ds_read_b128 v[196:199], v181 offset:19456
	ds_read_b128 v[200:203], v181 offset:20480
	ds_read_b128 v[204:207], v181 offset:21504
	ds_read_b128 v[208:211], v181 offset:22528
	ds_read_b128 v[212:215], v181 offset:23552
	global_load_lds_dwordx4 v[176:177], off
	s_add_i32 m0, s74, 0x2000
	s_add_u32 s74, s40, 0x40000
	v_lshl_add_u64 v[216:217], s[40:41], 0, v[134:135]
	s_addc_u32 s75, s41, 0
	s_add_i32 s76, s70, s51
	global_load_lds_dwordx4 v[216:217], off
	v_lshl_add_u64 v[218:219], s[74:75], 0, v[130:131]
	s_mov_b32 m0, s76
	v_lshl_add_u64 v[220:221], s[44:45], 0, v[132:133]
	global_load_lds_dwordx4 v[218:219], off
	s_add_i32 m0, s76, 0x2000
	v_lshl_add_u64 v[218:219], s[74:75], 0, v[134:135]
	global_load_lds_dwordx4 v[218:219], off
	s_mov_b32 m0, s54
	v_lshl_add_u64 v[218:219], s[44:45], 0, v[128:129]
	global_load_lds_dwordx4 v[218:219], off
	s_mov_b32 m0, s55
	s_nop 0
	global_load_lds_dwordx4 v[220:221], off
	s_waitcnt vmcnt(8)
	s_waitcnt lgkmcnt(0)
	s_barrier
	s_setprio 1
	s_waitcnt lgkmcnt(0)
	v_mfma_f32_16x16x32_bf16 v[60:63], v[144:147], v[184:187], 0
	v_mfma_f32_16x16x32_bf16 v[56:59], v[152:155], v[184:187], 0
	v_mfma_f32_16x16x32_bf16 v[44:47], v[144:147], v[192:195], 0
	v_mfma_f32_16x16x32_bf16 v[40:43], v[152:155], v[192:195], 0
	v_mfma_f32_16x16x32_bf16 v[28:31], v[144:147], v[200:203], 0
	v_mfma_f32_16x16x32_bf16 v[24:27], v[152:155], v[200:203], 0
	v_mfma_f32_16x16x32_bf16 v[12:15], v[144:147], v[208:211], 0
	v_mfma_f32_16x16x32_bf16 v[8:11], v[152:155], v[208:211], 0
	v_mfma_f32_16x16x32_bf16 v[60:63], v[148:151], v[188:191], v[60:63]
	v_mfma_f32_16x16x32_bf16 v[56:59], v[156:159], v[188:191], v[56:59]
	v_mfma_f32_16x16x32_bf16 v[44:47], v[148:151], v[196:199], v[44:47]
	v_mfma_f32_16x16x32_bf16 v[40:43], v[156:159], v[196:199], v[40:43]
	v_mfma_f32_16x16x32_bf16 v[28:31], v[148:151], v[204:207], v[28:31]
	v_mfma_f32_16x16x32_bf16 v[24:27], v[156:159], v[204:207], v[24:27]
	v_mfma_f32_16x16x32_bf16 v[12:15], v[148:151], v[212:215], v[12:15]
	v_mfma_f32_16x16x32_bf16 v[8:11], v[156:159], v[212:215], v[8:11]
	s_setprio 0
	s_setprio 1
	v_mfma_f32_16x16x32_bf16 v[52:55], v[160:163], v[184:187], 0
	v_mfma_f32_16x16x32_bf16 v[48:51], v[168:171], v[184:187], 0
	v_mfma_f32_16x16x32_bf16 v[36:39], v[160:163], v[192:195], 0
	v_mfma_f32_16x16x32_bf16 v[32:35], v[168:171], v[192:195], 0
	v_mfma_f32_16x16x32_bf16 v[20:23], v[160:163], v[200:203], 0
	v_mfma_f32_16x16x32_bf16 v[16:19], v[168:171], v[200:203], 0
	v_mfma_f32_16x16x32_bf16 v[4:7], v[160:163], v[208:211], 0
	v_mfma_f32_16x16x32_bf16 v[0:3], v[168:171], v[208:211], 0
	v_mfma_f32_16x16x32_bf16 v[52:55], v[164:167], v[188:191], v[52:55]
	v_mfma_f32_16x16x32_bf16 v[48:51], v[172:175], v[188:191], v[48:51]
	v_mfma_f32_16x16x32_bf16 v[36:39], v[164:167], v[196:199], v[36:39]
	v_mfma_f32_16x16x32_bf16 v[32:35], v[172:175], v[196:199], v[32:35]
	s_setprio 2
	s_barrier
	v_mfma_f32_16x16x32_bf16 v[20:23], v[164:167], v[204:207], v[20:23]
	v_mfma_f32_16x16x32_bf16 v[16:19], v[172:175], v[204:207], v[16:19]
	v_mfma_f32_16x16x32_bf16 v[4:7], v[164:167], v[212:215], v[4:7]
	v_mfma_f32_16x16x32_bf16 v[0:3], v[172:175], v[212:215], v[0:3]
	s_setprio 2
	s_add_i32 s74, 0, 0x18000
	s_add_i32 s75, 0, 0x1c000
	v_add_u32_e32 v156, s74, v178
	v_add_u32_e32 v172, s75, v178
	ds_read_b128 v[144:147], v156
	ds_read_b128 v[148:151], v156 offset:1024
	ds_read_b128 v[152:155], v156 offset:2048
	ds_read_b128 v[156:159], v156 offset:3072
	ds_read_b128 v[160:163], v172
	ds_read_b128 v[164:167], v172 offset:1024
	ds_read_b128 v[168:171], v172 offset:2048
	ds_read_b128 v[172:175], v172 offset:3072
	s_add_u32 s44, s44, 0x40000
	s_addc_u32 s45, s45, 0
	s_mov_b32 m0, s56
	v_lshl_add_u64 v[222:223], s[44:45], 0, v[128:129]
	ds_read_b128 v[184:187], v181 offset:32768
	ds_read_b128 v[188:191], v181 offset:33792
	ds_read_b128 v[192:195], v181 offset:34816
	ds_read_b128 v[196:199], v181 offset:35840
	ds_read_b128 v[200:203], v181 offset:36864
	ds_read_b128 v[204:207], v181 offset:37888
	ds_read_b128 v[208:211], v181 offset:38912
	ds_read_b128 v[212:215], v181 offset:39936
	global_load_lds_dwordx4 v[222:223], off
	s_mov_b32 m0, s57
	v_lshl_add_u64 v[222:223], s[44:45], 0, v[132:133]
	global_load_lds_dwordx4 v[222:223], off
	s_waitcnt vmcnt(8)
	s_waitcnt lgkmcnt(0)
	s_barrier
	s_setprio 1
	s_waitcnt lgkmcnt(0)
	v_mfma_f32_16x16x32_bf16 v[124:127], v[144:147], v[184:187], v[124:127]
	v_mfma_f32_16x16x32_bf16 v[120:123], v[152:155], v[184:187], v[120:123]
	v_mfma_f32_16x16x32_bf16 v[108:111], v[144:147], v[192:195], v[108:111]
	v_mfma_f32_16x16x32_bf16 v[104:107], v[152:155], v[192:195], v[104:107]
	v_mfma_f32_16x16x32_bf16 v[92:95], v[144:147], v[200:203], v[92:95]
	v_mfma_f32_16x16x32_bf16 v[88:91], v[152:155], v[200:203], v[88:91]
	v_mfma_f32_16x16x32_bf16 v[76:79], v[144:147], v[208:211], v[76:79]
	v_mfma_f32_16x16x32_bf16 v[72:75], v[152:155], v[208:211], v[72:75]
	v_mfma_f32_16x16x32_bf16 v[124:127], v[148:151], v[188:191], v[124:127]
	v_mfma_f32_16x16x32_bf16 v[120:123], v[156:159], v[188:191], v[120:123]
	v_mfma_f32_16x16x32_bf16 v[108:111], v[148:151], v[196:199], v[108:111]
	v_mfma_f32_16x16x32_bf16 v[104:107], v[156:159], v[196:199], v[104:107]
	v_mfma_f32_16x16x32_bf16 v[92:95], v[148:151], v[204:207], v[92:95]
	v_mfma_f32_16x16x32_bf16 v[88:91], v[156:159], v[204:207], v[88:91]
	v_mfma_f32_16x16x32_bf16 v[76:79], v[148:151], v[212:215], v[76:79]
	v_mfma_f32_16x16x32_bf16 v[72:75], v[156:159], v[212:215], v[72:75]
	s_setprio 0
	s_setprio 1
	v_mfma_f32_16x16x32_bf16 v[116:119], v[160:163], v[184:187], v[116:119]
	v_mfma_f32_16x16x32_bf16 v[112:115], v[168:171], v[184:187], v[112:115]
	v_mfma_f32_16x16x32_bf16 v[100:103], v[160:163], v[192:195], v[100:103]
	v_mfma_f32_16x16x32_bf16 v[96:99], v[168:171], v[192:195], v[96:99]
	v_mfma_f32_16x16x32_bf16 v[84:87], v[160:163], v[200:203], v[84:87]
	v_mfma_f32_16x16x32_bf16 v[80:83], v[168:171], v[200:203], v[80:83]
	v_mfma_f32_16x16x32_bf16 v[68:71], v[160:163], v[208:211], v[68:71]
	v_mfma_f32_16x16x32_bf16 v[64:67], v[168:171], v[208:211], v[64:67]
	v_mfma_f32_16x16x32_bf16 v[116:119], v[164:167], v[188:191], v[116:119]
	v_mfma_f32_16x16x32_bf16 v[112:115], v[172:175], v[188:191], v[112:115]
	v_mfma_f32_16x16x32_bf16 v[100:103], v[164:167], v[196:199], v[100:103]
	v_mfma_f32_16x16x32_bf16 v[96:99], v[172:175], v[196:199], v[96:99]
	s_setprio 2
	s_barrier
	v_mfma_f32_16x16x32_bf16 v[84:87], v[164:167], v[204:207], v[84:87]
	v_mfma_f32_16x16x32_bf16 v[80:83], v[172:175], v[204:207], v[80:83]
	v_mfma_f32_16x16x32_bf16 v[68:71], v[164:167], v[212:215], v[68:71]
	v_mfma_f32_16x16x32_bf16 v[64:67], v[172:175], v[212:215], v[64:67]
	s_setprio 2
	s_add_i32 s44, s74, s51
	v_lshl_add_u64 v[176:177], v[176:177], 0, s[22:23]
	s_mov_b32 m0, s44
	ds_read_b128 v[184:187], v181 offset:49152
	ds_read_b128 v[188:191], v181 offset:50176
	ds_read_b128 v[192:195], v181 offset:51200
	ds_read_b128 v[196:199], v181 offset:52224
	ds_read_b128 v[200:203], v181 offset:53248
	ds_read_b128 v[204:207], v181 offset:54272
	ds_read_b128 v[208:211], v181 offset:55296
	ds_read_b128 v[212:215], v181 offset:56320
	global_load_lds_dwordx4 v[176:177], off
	s_add_i32 m0, s44, 0x2000
	s_add_u32 s40, s40, 0x40080
	v_lshl_add_u64 v[176:177], v[216:217], 0, s[22:23]
	s_addc_u32 s41, s41, 0
	s_add_i32 s44, s75, s51
	global_load_lds_dwordx4 v[176:177], off
	s_mov_b32 m0, s44
	v_lshl_add_u64 v[176:177], s[40:41], 0, v[130:131]
	global_load_lds_dwordx4 v[176:177], off
	s_add_i32 m0, s44, 0x2000
	v_lshl_add_u64 v[176:177], s[40:41], 0, v[134:135]
	global_load_lds_dwordx4 v[176:177], off
	s_mov_b32 m0, s64
	v_lshl_add_u64 v[176:177], v[218:219], 0, s[22:23]
	global_load_lds_dwordx4 v[176:177], off
	s_mov_b32 m0, s65
	v_lshl_add_u64 v[176:177], v[220:221], 0, s[22:23]
	global_load_lds_dwordx4 v[176:177], off
	s_waitcnt vmcnt(8)
	s_waitcnt lgkmcnt(0)
	s_barrier
	s_setprio 1
	s_waitcnt lgkmcnt(0)
	v_mfma_f32_16x16x32_bf16 v[60:63], v[144:147], v[184:187], v[60:63]
	v_mfma_f32_16x16x32_bf16 v[56:59], v[152:155], v[184:187], v[56:59]
	v_mfma_f32_16x16x32_bf16 v[44:47], v[144:147], v[192:195], v[44:47]
	v_mfma_f32_16x16x32_bf16 v[40:43], v[152:155], v[192:195], v[40:43]
	v_mfma_f32_16x16x32_bf16 v[28:31], v[144:147], v[200:203], v[28:31]
	v_mfma_f32_16x16x32_bf16 v[24:27], v[152:155], v[200:203], v[24:27]
	v_mfma_f32_16x16x32_bf16 v[12:15], v[144:147], v[208:211], v[12:15]
	v_mfma_f32_16x16x32_bf16 v[8:11], v[152:155], v[208:211], v[8:11]
	v_mfma_f32_16x16x32_bf16 v[60:63], v[148:151], v[188:191], v[60:63]
	v_mfma_f32_16x16x32_bf16 v[56:59], v[156:159], v[188:191], v[56:59]
	v_mfma_f32_16x16x32_bf16 v[44:47], v[148:151], v[196:199], v[44:47]
	v_mfma_f32_16x16x32_bf16 v[40:43], v[156:159], v[196:199], v[40:43]
	v_mfma_f32_16x16x32_bf16 v[28:31], v[148:151], v[204:207], v[28:31]
	v_mfma_f32_16x16x32_bf16 v[24:27], v[156:159], v[204:207], v[24:27]
	v_mfma_f32_16x16x32_bf16 v[12:15], v[148:151], v[212:215], v[12:15]
	v_mfma_f32_16x16x32_bf16 v[8:11], v[156:159], v[212:215], v[8:11]
	s_setprio 0
	s_setprio 1
	v_mfma_f32_16x16x32_bf16 v[52:55], v[160:163], v[184:187], v[52:55]
	v_mfma_f32_16x16x32_bf16 v[48:51], v[168:171], v[184:187], v[48:51]
	v_mfma_f32_16x16x32_bf16 v[36:39], v[160:163], v[192:195], v[36:39]
	v_mfma_f32_16x16x32_bf16 v[32:35], v[168:171], v[192:195], v[32:35]
	v_mfma_f32_16x16x32_bf16 v[20:23], v[160:163], v[200:203], v[20:23]
	v_mfma_f32_16x16x32_bf16 v[16:19], v[168:171], v[200:203], v[16:19]
	v_mfma_f32_16x16x32_bf16 v[4:7], v[160:163], v[208:211], v[4:7]
	v_mfma_f32_16x16x32_bf16 v[0:3], v[168:171], v[208:211], v[0:3]
	v_mfma_f32_16x16x32_bf16 v[52:55], v[164:167], v[188:191], v[52:55]
	v_mfma_f32_16x16x32_bf16 v[48:51], v[172:175], v[188:191], v[48:51]
	v_mfma_f32_16x16x32_bf16 v[36:39], v[164:167], v[196:199], v[36:39]
	v_mfma_f32_16x16x32_bf16 v[32:35], v[172:175], v[196:199], v[32:35]
	s_setprio 2
	s_barrier
	v_mfma_f32_16x16x32_bf16 v[20:23], v[164:167], v[204:207], v[20:23]
	v_mfma_f32_16x16x32_bf16 v[16:19], v[172:175], v[204:207], v[16:19]
	v_mfma_f32_16x16x32_bf16 v[4:7], v[164:167], v[212:215], v[4:7]
	v_mfma_f32_16x16x32_bf16 v[0:3], v[172:175], v[212:215], v[0:3]
	s_setprio 2
	s_add_i32 s73, s73, 2
	s_add_u32 s6, s6, 0x100
	s_addc_u32 s7, s7, 0
	s_add_u32 s71, s71, 0x100
	s_addc_u32 s72, s72, 0
	s_cmp_gt_u32 s73, 13
.LBB0_952:
	ds_read_b128 v[144:147], v179
	ds_read_b128 v[148:151], v179 offset:1024
	ds_read_b128 v[152:155], v179 offset:2048
	ds_read_b128 v[156:159], v179 offset:3072
	ds_read_b128 v[160:163], v180
	ds_read_b128 v[164:167], v180 offset:1024
	ds_read_b128 v[168:171], v180 offset:2048
	ds_read_b128 v[172:175], v180 offset:3072
	s_add_u32 s40, s6, 0xfffc0080
	s_addc_u32 s41, s7, -1
	s_cmp_eq_u32 s73, 12
	s_cselect_b32 s45, s27, s41
	s_cselect_b32 s44, s39, s40
	s_cselect_b32 s41, s29, s72
	s_cselect_b32 s40, s43, s71
	v_lshl_add_u64 v[176:177], s[6:7], 0, v[136:137]
	s_add_i32 m0, s54, 0xc000
	ds_read_b128 v[184:187], v181
	ds_read_b128 v[188:191], v181 offset:1024
	ds_read_b128 v[192:195], v181 offset:2048
	ds_read_b128 v[196:199], v181 offset:3072
	ds_read_b128 v[200:203], v181 offset:4096
	ds_read_b128 v[204:207], v181 offset:5120
	ds_read_b128 v[208:211], v181 offset:6144
	ds_read_b128 v[212:215], v181 offset:7168
	global_load_lds_dwordx4 v[176:177], off
	s_add_i32 m0, s54, 0xe000
	v_lshl_add_u64 v[176:177], s[6:7], 0, v[138:139]
	global_load_lds_dwordx4 v[176:177], off
	s_waitcnt vmcnt(8)
	s_waitcnt lgkmcnt(0)
	s_barrier
	s_setprio 1
	s_waitcnt lgkmcnt(0)
	v_mfma_f32_16x16x32_bf16 v[124:127], v[144:147], v[184:187], v[124:127]
	v_mfma_f32_16x16x32_bf16 v[120:123], v[152:155], v[184:187], v[120:123]
	v_mfma_f32_16x16x32_bf16 v[108:111], v[144:147], v[192:195], v[108:111]
	v_mfma_f32_16x16x32_bf16 v[104:107], v[152:155], v[192:195], v[104:107]
	v_mfma_f32_16x16x32_bf16 v[92:95], v[144:147], v[200:203], v[92:95]
	v_mfma_f32_16x16x32_bf16 v[88:91], v[152:155], v[200:203], v[88:91]
	v_mfma_f32_16x16x32_bf16 v[76:79], v[144:147], v[208:211], v[76:79]
	v_mfma_f32_16x16x32_bf16 v[72:75], v[152:155], v[208:211], v[72:75]
	v_mfma_f32_16x16x32_bf16 v[124:127], v[148:151], v[188:191], v[124:127]
	v_mfma_f32_16x16x32_bf16 v[120:123], v[156:159], v[188:191], v[120:123]
	v_mfma_f32_16x16x32_bf16 v[108:111], v[148:151], v[196:199], v[108:111]
	v_mfma_f32_16x16x32_bf16 v[104:107], v[156:159], v[196:199], v[104:107]
	v_mfma_f32_16x16x32_bf16 v[92:95], v[148:151], v[204:207], v[92:95]
	v_mfma_f32_16x16x32_bf16 v[88:91], v[156:159], v[204:207], v[88:91]
	v_mfma_f32_16x16x32_bf16 v[76:79], v[148:151], v[212:215], v[76:79]
	v_mfma_f32_16x16x32_bf16 v[72:75], v[156:159], v[212:215], v[72:75]
	s_setprio 0
	s_setprio 1
	v_mfma_f32_16x16x32_bf16 v[116:119], v[160:163], v[184:187], v[116:119]
	v_mfma_f32_16x16x32_bf16 v[112:115], v[168:171], v[184:187], v[112:115]
	v_mfma_f32_16x16x32_bf16 v[100:103], v[160:163], v[192:195], v[100:103]
	v_mfma_f32_16x16x32_bf16 v[96:99], v[168:171], v[192:195], v[96:99]
	v_mfma_f32_16x16x32_bf16 v[84:87], v[160:163], v[200:203], v[84:87]
	v_mfma_f32_16x16x32_bf16 v[80:83], v[168:171], v[200:203], v[80:83]
	v_mfma_f32_16x16x32_bf16 v[68:71], v[160:163], v[208:211], v[68:71]
	v_mfma_f32_16x16x32_bf16 v[64:67], v[168:171], v[208:211], v[64:67]
	v_mfma_f32_16x16x32_bf16 v[116:119], v[164:167], v[188:191], v[116:119]
	v_mfma_f32_16x16x32_bf16 v[112:115], v[172:175], v[188:191], v[112:115]
	v_mfma_f32_16x16x32_bf16 v[100:103], v[164:167], v[196:199], v[100:103]
	v_mfma_f32_16x16x32_bf16 v[96:99], v[172:175], v[196:199], v[96:99]
	s_setprio 2
	s_barrier
	v_mfma_f32_16x16x32_bf16 v[84:87], v[164:167], v[204:207], v[84:87]
	v_mfma_f32_16x16x32_bf16 v[80:83], v[172:175], v[204:207], v[80:83]
	v_mfma_f32_16x16x32_bf16 v[68:71], v[164:167], v[212:215], v[68:71]
	v_mfma_f32_16x16x32_bf16 v[64:67], v[172:175], v[212:215], v[64:67]
	s_setprio 2
	s_add_i32 s74, s69, s51
	v_lshl_add_u64 v[176:177], s[40:41], 0, v[130:131]
	s_mov_b32 m0, s74
	ds_read_b128 v[184:187], v181 offset:16384
	ds_read_b128 v[188:191], v181 offset:17408
	ds_read_b128 v[192:195], v181 offset:18432
	ds_read_b128 v[196:199], v181 offset:19456
	ds_read_b128 v[200:203], v181 offset:20480
	ds_read_b128 v[204:207], v181 offset:21504
	ds_read_b128 v[208:211], v181 offset:22528
	ds_read_b128 v[212:215], v181 offset:23552
	global_load_lds_dwordx4 v[176:177], off
	s_add_i32 m0, s74, 0x2000
	s_add_u32 s74, s40, 0x40000
	v_lshl_add_u64 v[216:217], s[40:41], 0, v[134:135]
	s_addc_u32 s75, s41, 0
	s_add_i32 s76, s70, s51
	global_load_lds_dwordx4 v[216:217], off
	v_lshl_add_u64 v[218:219], s[74:75], 0, v[130:131]
	s_mov_b32 m0, s76
	v_lshl_add_u64 v[220:221], s[44:45], 0, v[132:133]
	global_load_lds_dwordx4 v[218:219], off
	s_add_i32 m0, s76, 0x2000
	v_lshl_add_u64 v[218:219], s[74:75], 0, v[134:135]
	global_load_lds_dwordx4 v[218:219], off
	s_mov_b32 m0, s54
	v_lshl_add_u64 v[218:219], s[44:45], 0, v[128:129]
	global_load_lds_dwordx4 v[218:219], off
	s_mov_b32 m0, s55
	s_nop 0
	global_load_lds_dwordx4 v[220:221], off
	s_waitcnt vmcnt(8)
	s_waitcnt lgkmcnt(0)
	s_barrier
	s_setprio 1
	s_waitcnt lgkmcnt(0)
	v_mfma_f32_16x16x32_bf16 v[60:63], v[144:147], v[184:187], v[60:63]
	v_mfma_f32_16x16x32_bf16 v[56:59], v[152:155], v[184:187], v[56:59]
	v_mfma_f32_16x16x32_bf16 v[44:47], v[144:147], v[192:195], v[44:47]
	v_mfma_f32_16x16x32_bf16 v[40:43], v[152:155], v[192:195], v[40:43]
	v_mfma_f32_16x16x32_bf16 v[28:31], v[144:147], v[200:203], v[28:31]
	v_mfma_f32_16x16x32_bf16 v[24:27], v[152:155], v[200:203], v[24:27]
	v_mfma_f32_16x16x32_bf16 v[12:15], v[144:147], v[208:211], v[12:15]
	v_mfma_f32_16x16x32_bf16 v[8:11], v[152:155], v[208:211], v[8:11]
	v_mfma_f32_16x16x32_bf16 v[60:63], v[148:151], v[188:191], v[60:63]
	v_mfma_f32_16x16x32_bf16 v[56:59], v[156:159], v[188:191], v[56:59]
	v_mfma_f32_16x16x32_bf16 v[44:47], v[148:151], v[196:199], v[44:47]
	v_mfma_f32_16x16x32_bf16 v[40:43], v[156:159], v[196:199], v[40:43]
	v_mfma_f32_16x16x32_bf16 v[28:31], v[148:151], v[204:207], v[28:31]
	v_mfma_f32_16x16x32_bf16 v[24:27], v[156:159], v[204:207], v[24:27]
	v_mfma_f32_16x16x32_bf16 v[12:15], v[148:151], v[212:215], v[12:15]
	v_mfma_f32_16x16x32_bf16 v[8:11], v[156:159], v[212:215], v[8:11]
	s_setprio 0
	s_setprio 1
	v_mfma_f32_16x16x32_bf16 v[52:55], v[160:163], v[184:187], v[52:55]
	v_mfma_f32_16x16x32_bf16 v[48:51], v[168:171], v[184:187], v[48:51]
	v_mfma_f32_16x16x32_bf16 v[36:39], v[160:163], v[192:195], v[36:39]
	v_mfma_f32_16x16x32_bf16 v[32:35], v[168:171], v[192:195], v[32:35]
	v_mfma_f32_16x16x32_bf16 v[20:23], v[160:163], v[200:203], v[20:23]
	v_mfma_f32_16x16x32_bf16 v[16:19], v[168:171], v[200:203], v[16:19]
	v_mfma_f32_16x16x32_bf16 v[4:7], v[160:163], v[208:211], v[4:7]
	v_mfma_f32_16x16x32_bf16 v[0:3], v[168:171], v[208:211], v[0:3]
	v_mfma_f32_16x16x32_bf16 v[52:55], v[164:167], v[188:191], v[52:55]
	v_mfma_f32_16x16x32_bf16 v[48:51], v[172:175], v[188:191], v[48:51]
	v_mfma_f32_16x16x32_bf16 v[36:39], v[164:167], v[196:199], v[36:39]
	v_mfma_f32_16x16x32_bf16 v[32:35], v[172:175], v[196:199], v[32:35]
	s_setprio 2
	s_barrier
	v_mfma_f32_16x16x32_bf16 v[20:23], v[164:167], v[204:207], v[20:23]
	v_mfma_f32_16x16x32_bf16 v[16:19], v[172:175], v[204:207], v[16:19]
	v_mfma_f32_16x16x32_bf16 v[4:7], v[164:167], v[212:215], v[4:7]
	v_mfma_f32_16x16x32_bf16 v[0:3], v[172:175], v[212:215], v[0:3]
	s_setprio 2
	s_add_i32 s74, 0, 0x18000
	s_add_i32 s75, 0, 0x1c000
	v_add_u32_e32 v156, s74, v178
	v_add_u32_e32 v172, s75, v178
	ds_read_b128 v[144:147], v156
	ds_read_b128 v[148:151], v156 offset:1024
	ds_read_b128 v[152:155], v156 offset:2048
	ds_read_b128 v[156:159], v156 offset:3072
	ds_read_b128 v[160:163], v172
	ds_read_b128 v[164:167], v172 offset:1024
	ds_read_b128 v[168:171], v172 offset:2048
	ds_read_b128 v[172:175], v172 offset:3072
	s_add_u32 s44, s44, 0x40000
	s_addc_u32 s45, s45, 0
	s_mov_b32 m0, s56
	v_lshl_add_u64 v[222:223], s[44:45], 0, v[128:129]
	ds_read_b128 v[184:187], v181 offset:32768
	ds_read_b128 v[188:191], v181 offset:33792
	ds_read_b128 v[192:195], v181 offset:34816
	ds_read_b128 v[196:199], v181 offset:35840
	ds_read_b128 v[200:203], v181 offset:36864
	ds_read_b128 v[204:207], v181 offset:37888
	ds_read_b128 v[208:211], v181 offset:38912
	ds_read_b128 v[212:215], v181 offset:39936
	global_load_lds_dwordx4 v[222:223], off
	s_mov_b32 m0, s57
	v_lshl_add_u64 v[222:223], s[44:45], 0, v[132:133]
	global_load_lds_dwordx4 v[222:223], off
	s_waitcnt vmcnt(8)
	s_waitcnt lgkmcnt(0)
	s_barrier
	s_setprio 1
	s_waitcnt lgkmcnt(0)
	v_mfma_f32_16x16x32_bf16 v[124:127], v[144:147], v[184:187], v[124:127]
	v_mfma_f32_16x16x32_bf16 v[120:123], v[152:155], v[184:187], v[120:123]
	v_mfma_f32_16x16x32_bf16 v[108:111], v[144:147], v[192:195], v[108:111]
	v_mfma_f32_16x16x32_bf16 v[104:107], v[152:155], v[192:195], v[104:107]
	v_mfma_f32_16x16x32_bf16 v[92:95], v[144:147], v[200:203], v[92:95]
	v_mfma_f32_16x16x32_bf16 v[88:91], v[152:155], v[200:203], v[88:91]
	v_mfma_f32_16x16x32_bf16 v[76:79], v[144:147], v[208:211], v[76:79]
	v_mfma_f32_16x16x32_bf16 v[72:75], v[152:155], v[208:211], v[72:75]
	v_mfma_f32_16x16x32_bf16 v[124:127], v[148:151], v[188:191], v[124:127]
	v_mfma_f32_16x16x32_bf16 v[120:123], v[156:159], v[188:191], v[120:123]
	v_mfma_f32_16x16x32_bf16 v[108:111], v[148:151], v[196:199], v[108:111]
	v_mfma_f32_16x16x32_bf16 v[104:107], v[156:159], v[196:199], v[104:107]
	v_mfma_f32_16x16x32_bf16 v[92:95], v[148:151], v[204:207], v[92:95]
	v_mfma_f32_16x16x32_bf16 v[88:91], v[156:159], v[204:207], v[88:91]
	v_mfma_f32_16x16x32_bf16 v[76:79], v[148:151], v[212:215], v[76:79]
	v_mfma_f32_16x16x32_bf16 v[72:75], v[156:159], v[212:215], v[72:75]
	s_setprio 0
	s_setprio 1
	v_mfma_f32_16x16x32_bf16 v[116:119], v[160:163], v[184:187], v[116:119]
	v_mfma_f32_16x16x32_bf16 v[112:115], v[168:171], v[184:187], v[112:115]
	v_mfma_f32_16x16x32_bf16 v[100:103], v[160:163], v[192:195], v[100:103]
	v_mfma_f32_16x16x32_bf16 v[96:99], v[168:171], v[192:195], v[96:99]
	v_mfma_f32_16x16x32_bf16 v[84:87], v[160:163], v[200:203], v[84:87]
	v_mfma_f32_16x16x32_bf16 v[80:83], v[168:171], v[200:203], v[80:83]
	v_mfma_f32_16x16x32_bf16 v[68:71], v[160:163], v[208:211], v[68:71]
	v_mfma_f32_16x16x32_bf16 v[64:67], v[168:171], v[208:211], v[64:67]
	v_mfma_f32_16x16x32_bf16 v[116:119], v[164:167], v[188:191], v[116:119]
	v_mfma_f32_16x16x32_bf16 v[112:115], v[172:175], v[188:191], v[112:115]
	v_mfma_f32_16x16x32_bf16 v[100:103], v[164:167], v[196:199], v[100:103]
	v_mfma_f32_16x16x32_bf16 v[96:99], v[172:175], v[196:199], v[96:99]
	s_setprio 2
	s_barrier
	v_mfma_f32_16x16x32_bf16 v[84:87], v[164:167], v[204:207], v[84:87]
	v_mfma_f32_16x16x32_bf16 v[80:83], v[172:175], v[204:207], v[80:83]
	v_mfma_f32_16x16x32_bf16 v[68:71], v[164:167], v[212:215], v[68:71]
	v_mfma_f32_16x16x32_bf16 v[64:67], v[172:175], v[212:215], v[64:67]
	s_setprio 2
	s_add_i32 s44, s74, s51
	v_lshl_add_u64 v[176:177], v[176:177], 0, s[22:23]
	s_mov_b32 m0, s44
	ds_read_b128 v[184:187], v181 offset:49152
	ds_read_b128 v[188:191], v181 offset:50176
	ds_read_b128 v[192:195], v181 offset:51200
	ds_read_b128 v[196:199], v181 offset:52224
	ds_read_b128 v[200:203], v181 offset:53248
	ds_read_b128 v[204:207], v181 offset:54272
	ds_read_b128 v[208:211], v181 offset:55296
	ds_read_b128 v[212:215], v181 offset:56320
	global_load_lds_dwordx4 v[176:177], off
	s_add_i32 m0, s44, 0x2000
	s_add_u32 s40, s40, 0x40080
	v_lshl_add_u64 v[176:177], v[216:217], 0, s[22:23]
	s_addc_u32 s41, s41, 0
	s_add_i32 s44, s75, s51
	global_load_lds_dwordx4 v[176:177], off
	s_mov_b32 m0, s44
	v_lshl_add_u64 v[176:177], s[40:41], 0, v[130:131]
	global_load_lds_dwordx4 v[176:177], off
	s_add_i32 m0, s44, 0x2000
	v_lshl_add_u64 v[176:177], s[40:41], 0, v[134:135]
	global_load_lds_dwordx4 v[176:177], off
	s_mov_b32 m0, s64
	v_lshl_add_u64 v[176:177], v[218:219], 0, s[22:23]
	global_load_lds_dwordx4 v[176:177], off
	s_mov_b32 m0, s65
	v_lshl_add_u64 v[176:177], v[220:221], 0, s[22:23]
	global_load_lds_dwordx4 v[176:177], off
	s_waitcnt vmcnt(8)
	s_waitcnt lgkmcnt(0)
	s_barrier
	s_setprio 1
	s_waitcnt lgkmcnt(0)
	v_mfma_f32_16x16x32_bf16 v[60:63], v[144:147], v[184:187], v[60:63]
	v_mfma_f32_16x16x32_bf16 v[56:59], v[152:155], v[184:187], v[56:59]
	v_mfma_f32_16x16x32_bf16 v[44:47], v[144:147], v[192:195], v[44:47]
	v_mfma_f32_16x16x32_bf16 v[40:43], v[152:155], v[192:195], v[40:43]
	v_mfma_f32_16x16x32_bf16 v[28:31], v[144:147], v[200:203], v[28:31]
	v_mfma_f32_16x16x32_bf16 v[24:27], v[152:155], v[200:203], v[24:27]
	v_mfma_f32_16x16x32_bf16 v[12:15], v[144:147], v[208:211], v[12:15]
	v_mfma_f32_16x16x32_bf16 v[8:11], v[152:155], v[208:211], v[8:11]
	v_mfma_f32_16x16x32_bf16 v[60:63], v[148:151], v[188:191], v[60:63]
	v_mfma_f32_16x16x32_bf16 v[56:59], v[156:159], v[188:191], v[56:59]
	v_mfma_f32_16x16x32_bf16 v[44:47], v[148:151], v[196:199], v[44:47]
	v_mfma_f32_16x16x32_bf16 v[40:43], v[156:159], v[196:199], v[40:43]
	v_mfma_f32_16x16x32_bf16 v[28:31], v[148:151], v[204:207], v[28:31]
	v_mfma_f32_16x16x32_bf16 v[24:27], v[156:159], v[204:207], v[24:27]
	v_mfma_f32_16x16x32_bf16 v[12:15], v[148:151], v[212:215], v[12:15]
	v_mfma_f32_16x16x32_bf16 v[8:11], v[156:159], v[212:215], v[8:11]
	s_setprio 0
	s_setprio 1
	v_mfma_f32_16x16x32_bf16 v[52:55], v[160:163], v[184:187], v[52:55]
	v_mfma_f32_16x16x32_bf16 v[48:51], v[168:171], v[184:187], v[48:51]
	v_mfma_f32_16x16x32_bf16 v[36:39], v[160:163], v[192:195], v[36:39]
	v_mfma_f32_16x16x32_bf16 v[32:35], v[168:171], v[192:195], v[32:35]
	v_mfma_f32_16x16x32_bf16 v[20:23], v[160:163], v[200:203], v[20:23]
	v_mfma_f32_16x16x32_bf16 v[16:19], v[168:171], v[200:203], v[16:19]
	v_mfma_f32_16x16x32_bf16 v[4:7], v[160:163], v[208:211], v[4:7]
	v_mfma_f32_16x16x32_bf16 v[0:3], v[168:171], v[208:211], v[0:3]
	v_mfma_f32_16x16x32_bf16 v[52:55], v[164:167], v[188:191], v[52:55]
	v_mfma_f32_16x16x32_bf16 v[48:51], v[172:175], v[188:191], v[48:51]
	v_mfma_f32_16x16x32_bf16 v[36:39], v[164:167], v[196:199], v[36:39]
	v_mfma_f32_16x16x32_bf16 v[32:35], v[172:175], v[196:199], v[32:35]
	s_setprio 2
	s_barrier
	v_mfma_f32_16x16x32_bf16 v[20:23], v[164:167], v[204:207], v[20:23]
	v_mfma_f32_16x16x32_bf16 v[16:19], v[172:175], v[204:207], v[16:19]
	v_mfma_f32_16x16x32_bf16 v[4:7], v[164:167], v[212:215], v[4:7]
	v_mfma_f32_16x16x32_bf16 v[0:3], v[172:175], v[212:215], v[0:3]
	s_setprio 0
	s_add_i32 s73, s73, 2
	s_add_u32 s6, s6, 0x100
	s_addc_u32 s7, s7, 0
	s_add_u32 s71, s71, 0x100
	s_addc_u32 s72, s72, 0
	s_cmp_gt_u32 s73, 13
	s_cbranch_scc0 .LBB0_952

.LBB0_1145:
	s_ashr_i32 s23, s22, 31
	s_lshl_b64 s[26:27], s[22:23], 19
	s_add_u32 s26, s45, s26
	s_addc_u32 s27, s46, s27
	s_and_b64 s[28:29], s[4:5], exec
	s_cselect_b32 s23, s27, s39
	s_cselect_b32 s31, s26, s38
	s_ashr_i32 s25, s24, 31
	s_lshl_b64 s[28:29], s[24:25], 19
	s_add_u32 s28, s47, s28
	s_addc_u32 s29, s48, s29
	s_and_b64 s[42:43], s[4:5], exec
	s_cselect_b32 s25, s29, s41
	s_cselect_b32 s37, s28, s40
	s_add_u32 s38, s38, 0x40080
	s_addc_u32 s39, s39, 0
	s_add_u32 s64, s40, 0x100
	s_addc_u32 s65, s41, 0
	s_mov_b32 s66, -2
	ds_read_b128 v[120:123], v233
	ds_read_b128 v[132:135], v233 offset:1024
	ds_read_b128 v[136:139], v233 offset:2048
	ds_read_b128 v[140:143], v233 offset:3072
	ds_read_b128 v[144:147], v234
	ds_read_b128 v[148:151], v234 offset:1024
	ds_read_b128 v[152:155], v234 offset:2048
	ds_read_b128 v[156:159], v234 offset:3072
	s_add_u32 s40, s38, 0xfffc0080
	s_addc_u32 s41, s39, -1
	s_cmp_eq_u32 s66, 12
	s_cselect_b32 s43, s23, s41
	s_cselect_b32 s42, s31, s40
	s_cselect_b32 s41, s25, s65
	s_cselect_b32 s40, s37, s64
	v_lshl_add_u64 v[208:209], s[38:39], 0, v[192:193]
	s_add_i32 m0, s50, 0xc000
	ds_read_b128 v[160:163], v235
	ds_read_b128 v[164:167], v235 offset:1024
	ds_read_b128 v[168:171], v235 offset:2048
	ds_read_b128 v[172:175], v235 offset:3072
	ds_read_b128 v[176:179], v235 offset:4096
	ds_read_b128 v[180:183], v235 offset:5120
	ds_read_b128 v[200:203], v235 offset:6144
	ds_read_b128 v[204:207], v235 offset:7168
	global_load_lds_dwordx4 v[208:209], off
	s_add_i32 m0, s50, 0xe000
	v_lshl_add_u64 v[208:209], s[38:39], 0, v[194:195]
	global_load_lds_dwordx4 v[208:209], off
	s_waitcnt vmcnt(8)
	s_waitcnt lgkmcnt(0)
	s_barrier
	s_setprio 1
	s_waitcnt lgkmcnt(0)
	v_mfma_f32_16x16x32_bf16 v[128:131], v[120:123], v[160:163], 0
	v_mfma_f32_16x16x32_bf16 v[124:127], v[136:139], v[160:163], 0
	v_mfma_f32_16x16x32_bf16 v[108:111], v[120:123], v[168:171], 0
	v_mfma_f32_16x16x32_bf16 v[104:107], v[136:139], v[168:171], 0
	v_mfma_f32_16x16x32_bf16 v[92:95], v[120:123], v[176:179], 0
	v_mfma_f32_16x16x32_bf16 v[88:91], v[136:139], v[176:179], 0
	v_mfma_f32_16x16x32_bf16 v[76:79], v[120:123], v[200:203], 0
	v_mfma_f32_16x16x32_bf16 v[72:75], v[136:139], v[200:203], 0
	v_mfma_f32_16x16x32_bf16 v[128:131], v[132:135], v[164:167], v[128:131]
	v_mfma_f32_16x16x32_bf16 v[124:127], v[140:143], v[164:167], v[124:127]
	v_mfma_f32_16x16x32_bf16 v[108:111], v[132:135], v[172:175], v[108:111]
	v_mfma_f32_16x16x32_bf16 v[104:107], v[140:143], v[172:175], v[104:107]
	v_mfma_f32_16x16x32_bf16 v[92:95], v[132:135], v[180:183], v[92:95]
	v_mfma_f32_16x16x32_bf16 v[88:91], v[140:143], v[180:183], v[88:91]
	v_mfma_f32_16x16x32_bf16 v[76:79], v[132:135], v[204:207], v[76:79]
	v_mfma_f32_16x16x32_bf16 v[72:75], v[140:143], v[204:207], v[72:75]
	s_setprio 0
	s_setprio 1
	v_mfma_f32_16x16x32_bf16 v[116:119], v[144:147], v[160:163], 0
	v_mfma_f32_16x16x32_bf16 v[112:115], v[152:155], v[160:163], 0
	v_mfma_f32_16x16x32_bf16 v[100:103], v[144:147], v[168:171], 0
	v_mfma_f32_16x16x32_bf16 v[96:99], v[152:155], v[168:171], 0
	v_mfma_f32_16x16x32_bf16 v[84:87], v[144:147], v[176:179], 0
	v_mfma_f32_16x16x32_bf16 v[80:83], v[152:155], v[176:179], 0
	v_mfma_f32_16x16x32_bf16 v[68:71], v[144:147], v[200:203], 0
	v_mfma_f32_16x16x32_bf16 v[64:67], v[152:155], v[200:203], 0
	v_mfma_f32_16x16x32_bf16 v[116:119], v[148:151], v[164:167], v[116:119]
	v_mfma_f32_16x16x32_bf16 v[112:115], v[156:159], v[164:167], v[112:115]
	v_mfma_f32_16x16x32_bf16 v[100:103], v[148:151], v[172:175], v[100:103]
	v_mfma_f32_16x16x32_bf16 v[96:99], v[156:159], v[172:175], v[96:99]
	s_setprio 2
	s_barrier
	v_mfma_f32_16x16x32_bf16 v[84:87], v[148:151], v[180:183], v[84:87]
	v_mfma_f32_16x16x32_bf16 v[80:83], v[156:159], v[180:183], v[80:83]
	v_mfma_f32_16x16x32_bf16 v[68:71], v[148:151], v[204:207], v[68:71]
	v_mfma_f32_16x16x32_bf16 v[64:67], v[156:159], v[204:207], v[64:67]
	s_setprio 2
	s_add_i32 s67, s62, s49
	v_lshl_add_u64 v[208:209], s[40:41], 0, v[186:187]
	s_mov_b32 m0, s67
	ds_read_b128 v[160:163], v235 offset:16384
	ds_read_b128 v[164:167], v235 offset:17408
	ds_read_b128 v[168:171], v235 offset:18432
	ds_read_b128 v[172:175], v235 offset:19456
	ds_read_b128 v[176:179], v235 offset:20480
	ds_read_b128 v[180:183], v235 offset:21504
	ds_read_b128 v[200:203], v235 offset:22528
	ds_read_b128 v[204:207], v235 offset:23552
	global_load_lds_dwordx4 v[208:209], off
	s_add_i32 m0, s67, 0x2000
	s_add_u32 s68, s40, 0x40000
	v_lshl_add_u64 v[210:211], s[40:41], 0, v[190:191]
	s_addc_u32 s69, s41, 0
	s_add_i32 s67, s63, s49
	global_load_lds_dwordx4 v[210:211], off
	v_lshl_add_u64 v[212:213], s[68:69], 0, v[186:187]
	s_mov_b32 m0, s67
	v_lshl_add_u64 v[214:215], s[42:43], 0, v[188:189]
	global_load_lds_dwordx4 v[212:213], off
	s_add_i32 m0, s67, 0x2000
	v_lshl_add_u64 v[212:213], s[68:69], 0, v[190:191]
	global_load_lds_dwordx4 v[212:213], off
	s_mov_b32 m0, s50
	v_lshl_add_u64 v[212:213], s[42:43], 0, v[184:185]
	global_load_lds_dwordx4 v[212:213], off
	s_mov_b32 m0, s51
	s_nop 0
	global_load_lds_dwordx4 v[214:215], off
	s_waitcnt vmcnt(8)
	s_waitcnt lgkmcnt(0)
	s_barrier
	s_setprio 1
	s_waitcnt lgkmcnt(0)
	v_mfma_f32_16x16x32_bf16 v[60:63], v[120:123], v[160:163], 0
	v_mfma_f32_16x16x32_bf16 v[56:59], v[136:139], v[160:163], 0
	v_mfma_f32_16x16x32_bf16 v[44:47], v[120:123], v[168:171], 0
	v_mfma_f32_16x16x32_bf16 v[40:43], v[136:139], v[168:171], 0
	v_mfma_f32_16x16x32_bf16 v[28:31], v[120:123], v[176:179], 0
	v_mfma_f32_16x16x32_bf16 v[24:27], v[136:139], v[176:179], 0
	v_mfma_f32_16x16x32_bf16 v[12:15], v[120:123], v[200:203], 0
	v_mfma_f32_16x16x32_bf16 v[8:11], v[136:139], v[200:203], 0
	v_mfma_f32_16x16x32_bf16 v[60:63], v[132:135], v[164:167], v[60:63]
	v_mfma_f32_16x16x32_bf16 v[56:59], v[140:143], v[164:167], v[56:59]
	v_mfma_f32_16x16x32_bf16 v[44:47], v[132:135], v[172:175], v[44:47]
	v_mfma_f32_16x16x32_bf16 v[40:43], v[140:143], v[172:175], v[40:43]
	v_mfma_f32_16x16x32_bf16 v[28:31], v[132:135], v[180:183], v[28:31]
	v_mfma_f32_16x16x32_bf16 v[24:27], v[140:143], v[180:183], v[24:27]
	v_mfma_f32_16x16x32_bf16 v[12:15], v[132:135], v[204:207], v[12:15]
	v_mfma_f32_16x16x32_bf16 v[8:11], v[140:143], v[204:207], v[8:11]
	s_setprio 0
	s_setprio 1
	v_mfma_f32_16x16x32_bf16 v[52:55], v[144:147], v[160:163], 0
	v_mfma_f32_16x16x32_bf16 v[48:51], v[152:155], v[160:163], 0
	v_mfma_f32_16x16x32_bf16 v[36:39], v[144:147], v[168:171], 0
	v_mfma_f32_16x16x32_bf16 v[32:35], v[152:155], v[168:171], 0
	v_mfma_f32_16x16x32_bf16 v[20:23], v[144:147], v[176:179], 0
	v_mfma_f32_16x16x32_bf16 v[16:19], v[152:155], v[176:179], 0
	v_mfma_f32_16x16x32_bf16 v[4:7], v[144:147], v[200:203], 0
	v_mfma_f32_16x16x32_bf16 v[0:3], v[152:155], v[200:203], 0
	v_mfma_f32_16x16x32_bf16 v[52:55], v[148:151], v[164:167], v[52:55]
	v_mfma_f32_16x16x32_bf16 v[48:51], v[156:159], v[164:167], v[48:51]
	v_mfma_f32_16x16x32_bf16 v[36:39], v[148:151], v[172:175], v[36:39]
	v_mfma_f32_16x16x32_bf16 v[32:35], v[156:159], v[172:175], v[32:35]
	s_setprio 2
	s_barrier
	v_mfma_f32_16x16x32_bf16 v[20:23], v[148:151], v[180:183], v[20:23]
	v_mfma_f32_16x16x32_bf16 v[16:19], v[156:159], v[180:183], v[16:19]
	v_mfma_f32_16x16x32_bf16 v[4:7], v[148:151], v[204:207], v[4:7]
	v_mfma_f32_16x16x32_bf16 v[0:3], v[156:159], v[204:207], v[0:3]
	s_setprio 2
	s_add_i32 s67, 0, 0x18000
	s_add_i32 s68, 0, 0x1c000
	v_add_u32_e32 v140, s67, v232
	v_add_u32_e32 v156, s68, v232
	ds_read_b128 v[120:123], v140
	ds_read_b128 v[132:135], v140 offset:1024
	ds_read_b128 v[136:139], v140 offset:2048
	ds_read_b128 v[140:143], v140 offset:3072
	ds_read_b128 v[144:147], v156
	ds_read_b128 v[148:151], v156 offset:1024
	ds_read_b128 v[152:155], v156 offset:2048
	ds_read_b128 v[156:159], v156 offset:3072
	s_add_u32 s42, s42, 0x40000
	s_addc_u32 s43, s43, 0
	s_mov_b32 m0, s54
	v_lshl_add_u64 v[216:217], s[42:43], 0, v[184:185]
	ds_read_b128 v[160:163], v235 offset:32768
	ds_read_b128 v[164:167], v235 offset:33792
	ds_read_b128 v[168:171], v235 offset:34816
	ds_read_b128 v[172:175], v235 offset:35840
	ds_read_b128 v[176:179], v235 offset:36864
	ds_read_b128 v[180:183], v235 offset:37888
	ds_read_b128 v[200:203], v235 offset:38912
	ds_read_b128 v[204:207], v235 offset:39936
	global_load_lds_dwordx4 v[216:217], off
	s_mov_b32 m0, s55
	v_lshl_add_u64 v[216:217], s[42:43], 0, v[188:189]
	global_load_lds_dwordx4 v[216:217], off
	s_waitcnt vmcnt(8)
	s_waitcnt lgkmcnt(0)
	s_barrier
	s_setprio 1
	s_waitcnt lgkmcnt(0)
	v_mfma_f32_16x16x32_bf16 v[128:131], v[120:123], v[160:163], v[128:131]
	v_mfma_f32_16x16x32_bf16 v[124:127], v[136:139], v[160:163], v[124:127]
	v_mfma_f32_16x16x32_bf16 v[108:111], v[120:123], v[168:171], v[108:111]
	v_mfma_f32_16x16x32_bf16 v[104:107], v[136:139], v[168:171], v[104:107]
	v_mfma_f32_16x16x32_bf16 v[92:95], v[120:123], v[176:179], v[92:95]
	v_mfma_f32_16x16x32_bf16 v[88:91], v[136:139], v[176:179], v[88:91]
	v_mfma_f32_16x16x32_bf16 v[76:79], v[120:123], v[200:203], v[76:79]
	v_mfma_f32_16x16x32_bf16 v[72:75], v[136:139], v[200:203], v[72:75]
	v_mfma_f32_16x16x32_bf16 v[128:131], v[132:135], v[164:167], v[128:131]
	v_mfma_f32_16x16x32_bf16 v[124:127], v[140:143], v[164:167], v[124:127]
	v_mfma_f32_16x16x32_bf16 v[108:111], v[132:135], v[172:175], v[108:111]
	v_mfma_f32_16x16x32_bf16 v[104:107], v[140:143], v[172:175], v[104:107]
	v_mfma_f32_16x16x32_bf16 v[92:95], v[132:135], v[180:183], v[92:95]
	v_mfma_f32_16x16x32_bf16 v[88:91], v[140:143], v[180:183], v[88:91]
	v_mfma_f32_16x16x32_bf16 v[76:79], v[132:135], v[204:207], v[76:79]
	v_mfma_f32_16x16x32_bf16 v[72:75], v[140:143], v[204:207], v[72:75]
	s_setprio 0
	s_setprio 1
	v_mfma_f32_16x16x32_bf16 v[116:119], v[144:147], v[160:163], v[116:119]
	v_mfma_f32_16x16x32_bf16 v[112:115], v[152:155], v[160:163], v[112:115]
	v_mfma_f32_16x16x32_bf16 v[100:103], v[144:147], v[168:171], v[100:103]
	v_mfma_f32_16x16x32_bf16 v[96:99], v[152:155], v[168:171], v[96:99]
	v_mfma_f32_16x16x32_bf16 v[84:87], v[144:147], v[176:179], v[84:87]
	v_mfma_f32_16x16x32_bf16 v[80:83], v[152:155], v[176:179], v[80:83]
	v_mfma_f32_16x16x32_bf16 v[68:71], v[144:147], v[200:203], v[68:71]
	v_mfma_f32_16x16x32_bf16 v[64:67], v[152:155], v[200:203], v[64:67]
	v_mfma_f32_16x16x32_bf16 v[116:119], v[148:151], v[164:167], v[116:119]
	v_mfma_f32_16x16x32_bf16 v[112:115], v[156:159], v[164:167], v[112:115]
	v_mfma_f32_16x16x32_bf16 v[100:103], v[148:151], v[172:175], v[100:103]
	v_mfma_f32_16x16x32_bf16 v[96:99], v[156:159], v[172:175], v[96:99]
	s_setprio 2
	s_barrier
	v_mfma_f32_16x16x32_bf16 v[84:87], v[148:151], v[180:183], v[84:87]
	v_mfma_f32_16x16x32_bf16 v[80:83], v[156:159], v[180:183], v[80:83]
	v_mfma_f32_16x16x32_bf16 v[68:71], v[148:151], v[204:207], v[68:71]
	v_mfma_f32_16x16x32_bf16 v[64:67], v[156:159], v[204:207], v[64:67]
	s_setprio 2
	s_add_i32 s42, s67, s49
	v_lshl_add_u64 v[208:209], v[208:209], 0, s[18:19]
	s_mov_b32 m0, s42
	ds_read_b128 v[160:163], v235 offset:49152
	ds_read_b128 v[164:167], v235 offset:50176
	ds_read_b128 v[168:171], v235 offset:51200
	ds_read_b128 v[172:175], v235 offset:52224
	ds_read_b128 v[176:179], v235 offset:53248
	ds_read_b128 v[180:183], v235 offset:54272
	ds_read_b128 v[200:203], v235 offset:55296
	ds_read_b128 v[204:207], v235 offset:56320
	global_load_lds_dwordx4 v[208:209], off
	s_add_i32 m0, s42, 0x2000
	s_add_u32 s40, s40, 0x40080
	v_lshl_add_u64 v[208:209], v[210:211], 0, s[18:19]
	s_addc_u32 s41, s41, 0
	s_add_i32 s42, s68, s49
	global_load_lds_dwordx4 v[208:209], off
	s_mov_b32 m0, s42
	v_lshl_add_u64 v[208:209], s[40:41], 0, v[186:187]
	global_load_lds_dwordx4 v[208:209], off
	s_add_i32 m0, s42, 0x2000
	v_lshl_add_u64 v[208:209], s[40:41], 0, v[190:191]
	global_load_lds_dwordx4 v[208:209], off
	s_mov_b32 m0, s57
	v_lshl_add_u64 v[208:209], v[212:213], 0, s[18:19]
	global_load_lds_dwordx4 v[208:209], off
	s_mov_b32 m0, s58
	v_lshl_add_u64 v[208:209], v[214:215], 0, s[18:19]
	global_load_lds_dwordx4 v[208:209], off
	s_waitcnt vmcnt(8)
	s_waitcnt lgkmcnt(0)
	s_barrier
	s_setprio 1
	s_waitcnt lgkmcnt(0)
	v_mfma_f32_16x16x32_bf16 v[60:63], v[120:123], v[160:163], v[60:63]
	v_mfma_f32_16x16x32_bf16 v[56:59], v[136:139], v[160:163], v[56:59]
	v_mfma_f32_16x16x32_bf16 v[44:47], v[120:123], v[168:171], v[44:47]
	v_mfma_f32_16x16x32_bf16 v[40:43], v[136:139], v[168:171], v[40:43]
	v_mfma_f32_16x16x32_bf16 v[28:31], v[120:123], v[176:179], v[28:31]
	v_mfma_f32_16x16x32_bf16 v[24:27], v[136:139], v[176:179], v[24:27]
	v_mfma_f32_16x16x32_bf16 v[12:15], v[120:123], v[200:203], v[12:15]
	v_mfma_f32_16x16x32_bf16 v[8:11], v[136:139], v[200:203], v[8:11]
	v_mfma_f32_16x16x32_bf16 v[60:63], v[132:135], v[164:167], v[60:63]
	v_mfma_f32_16x16x32_bf16 v[56:59], v[140:143], v[164:167], v[56:59]
	v_mfma_f32_16x16x32_bf16 v[44:47], v[132:135], v[172:175], v[44:47]
	v_mfma_f32_16x16x32_bf16 v[40:43], v[140:143], v[172:175], v[40:43]
	v_mfma_f32_16x16x32_bf16 v[28:31], v[132:135], v[180:183], v[28:31]
	v_mfma_f32_16x16x32_bf16 v[24:27], v[140:143], v[180:183], v[24:27]
	v_mfma_f32_16x16x32_bf16 v[12:15], v[132:135], v[204:207], v[12:15]
	v_mfma_f32_16x16x32_bf16 v[8:11], v[140:143], v[204:207], v[8:11]
	s_setprio 0
	s_setprio 1
	v_mfma_f32_16x16x32_bf16 v[52:55], v[144:147], v[160:163], v[52:55]
	v_mfma_f32_16x16x32_bf16 v[48:51], v[152:155], v[160:163], v[48:51]
	v_mfma_f32_16x16x32_bf16 v[36:39], v[144:147], v[168:171], v[36:39]
	v_mfma_f32_16x16x32_bf16 v[32:35], v[152:155], v[168:171], v[32:35]
	v_mfma_f32_16x16x32_bf16 v[20:23], v[144:147], v[176:179], v[20:23]
	v_mfma_f32_16x16x32_bf16 v[16:19], v[152:155], v[176:179], v[16:19]
	v_mfma_f32_16x16x32_bf16 v[4:7], v[144:147], v[200:203], v[4:7]
	v_mfma_f32_16x16x32_bf16 v[0:3], v[152:155], v[200:203], v[0:3]
	v_mfma_f32_16x16x32_bf16 v[52:55], v[148:151], v[164:167], v[52:55]
	v_mfma_f32_16x16x32_bf16 v[48:51], v[156:159], v[164:167], v[48:51]
	v_mfma_f32_16x16x32_bf16 v[36:39], v[148:151], v[172:175], v[36:39]
	v_mfma_f32_16x16x32_bf16 v[32:35], v[156:159], v[172:175], v[32:35]
	s_setprio 2
	s_barrier
	v_mfma_f32_16x16x32_bf16 v[20:23], v[148:151], v[180:183], v[20:23]
	v_mfma_f32_16x16x32_bf16 v[16:19], v[156:159], v[180:183], v[16:19]
	v_mfma_f32_16x16x32_bf16 v[4:7], v[148:151], v[204:207], v[4:7]
	v_mfma_f32_16x16x32_bf16 v[0:3], v[156:159], v[204:207], v[0:3]
	s_setprio 2
	s_add_i32 s66, s66, 2
	s_add_u32 s38, s38, 0x100
	s_addc_u32 s39, s39, 0
	s_add_u32 s64, s64, 0x100
	s_addc_u32 s65, s65, 0
	s_cmp_gt_u32 s66, 13
.LBB0_1146:
	ds_read_b128 v[120:123], v233
	ds_read_b128 v[132:135], v233 offset:1024
	ds_read_b128 v[136:139], v233 offset:2048
	ds_read_b128 v[140:143], v233 offset:3072
	ds_read_b128 v[144:147], v234
	ds_read_b128 v[148:151], v234 offset:1024
	ds_read_b128 v[152:155], v234 offset:2048
	ds_read_b128 v[156:159], v234 offset:3072
	s_add_u32 s40, s38, 0xfffc0080
	s_addc_u32 s41, s39, -1
	s_cmp_eq_u32 s66, 12
	s_cselect_b32 s43, s23, s41
	s_cselect_b32 s42, s31, s40
	s_cselect_b32 s41, s25, s65
	s_cselect_b32 s40, s37, s64
	v_lshl_add_u64 v[208:209], s[38:39], 0, v[192:193]
	s_add_i32 m0, s50, 0xc000
	ds_read_b128 v[160:163], v235
	ds_read_b128 v[164:167], v235 offset:1024
	ds_read_b128 v[168:171], v235 offset:2048
	ds_read_b128 v[172:175], v235 offset:3072
	ds_read_b128 v[176:179], v235 offset:4096
	ds_read_b128 v[180:183], v235 offset:5120
	ds_read_b128 v[200:203], v235 offset:6144
	ds_read_b128 v[204:207], v235 offset:7168
	global_load_lds_dwordx4 v[208:209], off
	s_add_i32 m0, s50, 0xe000
	v_lshl_add_u64 v[208:209], s[38:39], 0, v[194:195]
	global_load_lds_dwordx4 v[208:209], off
	s_waitcnt vmcnt(8)
	s_waitcnt lgkmcnt(0)
	s_barrier
	s_setprio 1
	s_waitcnt lgkmcnt(0)
	v_mfma_f32_16x16x32_bf16 v[128:131], v[120:123], v[160:163], v[128:131]
	v_mfma_f32_16x16x32_bf16 v[124:127], v[136:139], v[160:163], v[124:127]
	v_mfma_f32_16x16x32_bf16 v[108:111], v[120:123], v[168:171], v[108:111]
	v_mfma_f32_16x16x32_bf16 v[104:107], v[136:139], v[168:171], v[104:107]
	v_mfma_f32_16x16x32_bf16 v[92:95], v[120:123], v[176:179], v[92:95]
	v_mfma_f32_16x16x32_bf16 v[88:91], v[136:139], v[176:179], v[88:91]
	v_mfma_f32_16x16x32_bf16 v[76:79], v[120:123], v[200:203], v[76:79]
	v_mfma_f32_16x16x32_bf16 v[72:75], v[136:139], v[200:203], v[72:75]
	v_mfma_f32_16x16x32_bf16 v[128:131], v[132:135], v[164:167], v[128:131]
	v_mfma_f32_16x16x32_bf16 v[124:127], v[140:143], v[164:167], v[124:127]
	v_mfma_f32_16x16x32_bf16 v[108:111], v[132:135], v[172:175], v[108:111]
	v_mfma_f32_16x16x32_bf16 v[104:107], v[140:143], v[172:175], v[104:107]
	v_mfma_f32_16x16x32_bf16 v[92:95], v[132:135], v[180:183], v[92:95]
	v_mfma_f32_16x16x32_bf16 v[88:91], v[140:143], v[180:183], v[88:91]
	v_mfma_f32_16x16x32_bf16 v[76:79], v[132:135], v[204:207], v[76:79]
	v_mfma_f32_16x16x32_bf16 v[72:75], v[140:143], v[204:207], v[72:75]
	s_setprio 0
	s_setprio 1
	v_mfma_f32_16x16x32_bf16 v[116:119], v[144:147], v[160:163], v[116:119]
	v_mfma_f32_16x16x32_bf16 v[112:115], v[152:155], v[160:163], v[112:115]
	v_mfma_f32_16x16x32_bf16 v[100:103], v[144:147], v[168:171], v[100:103]
	v_mfma_f32_16x16x32_bf16 v[96:99], v[152:155], v[168:171], v[96:99]
	v_mfma_f32_16x16x32_bf16 v[84:87], v[144:147], v[176:179], v[84:87]
	v_mfma_f32_16x16x32_bf16 v[80:83], v[152:155], v[176:179], v[80:83]
	v_mfma_f32_16x16x32_bf16 v[68:71], v[144:147], v[200:203], v[68:71]
	v_mfma_f32_16x16x32_bf16 v[64:67], v[152:155], v[200:203], v[64:67]
	v_mfma_f32_16x16x32_bf16 v[116:119], v[148:151], v[164:167], v[116:119]
	v_mfma_f32_16x16x32_bf16 v[112:115], v[156:159], v[164:167], v[112:115]
	v_mfma_f32_16x16x32_bf16 v[100:103], v[148:151], v[172:175], v[100:103]
	v_mfma_f32_16x16x32_bf16 v[96:99], v[156:159], v[172:175], v[96:99]
	s_setprio 2
	s_barrier
	v_mfma_f32_16x16x32_bf16 v[84:87], v[148:151], v[180:183], v[84:87]
	v_mfma_f32_16x16x32_bf16 v[80:83], v[156:159], v[180:183], v[80:83]
	v_mfma_f32_16x16x32_bf16 v[68:71], v[148:151], v[204:207], v[68:71]
	v_mfma_f32_16x16x32_bf16 v[64:67], v[156:159], v[204:207], v[64:67]
	s_setprio 2
	s_add_i32 s67, s62, s49
	v_lshl_add_u64 v[208:209], s[40:41], 0, v[186:187]
	s_mov_b32 m0, s67
	ds_read_b128 v[160:163], v235 offset:16384
	ds_read_b128 v[164:167], v235 offset:17408
	ds_read_b128 v[168:171], v235 offset:18432
	ds_read_b128 v[172:175], v235 offset:19456
	ds_read_b128 v[176:179], v235 offset:20480
	ds_read_b128 v[180:183], v235 offset:21504
	ds_read_b128 v[200:203], v235 offset:22528
	ds_read_b128 v[204:207], v235 offset:23552
	global_load_lds_dwordx4 v[208:209], off
	s_add_i32 m0, s67, 0x2000
	s_add_u32 s68, s40, 0x40000
	v_lshl_add_u64 v[210:211], s[40:41], 0, v[190:191]
	s_addc_u32 s69, s41, 0
	s_add_i32 s67, s63, s49
	global_load_lds_dwordx4 v[210:211], off
	v_lshl_add_u64 v[212:213], s[68:69], 0, v[186:187]
	s_mov_b32 m0, s67
	v_lshl_add_u64 v[214:215], s[42:43], 0, v[188:189]
	global_load_lds_dwordx4 v[212:213], off
	s_add_i32 m0, s67, 0x2000
	v_lshl_add_u64 v[212:213], s[68:69], 0, v[190:191]
	global_load_lds_dwordx4 v[212:213], off
	s_mov_b32 m0, s50
	v_lshl_add_u64 v[212:213], s[42:43], 0, v[184:185]
	global_load_lds_dwordx4 v[212:213], off
	s_mov_b32 m0, s51
	s_nop 0
	global_load_lds_dwordx4 v[214:215], off
	s_waitcnt vmcnt(8)
	s_waitcnt lgkmcnt(0)
	s_barrier
	s_setprio 1
	s_waitcnt lgkmcnt(0)
	v_mfma_f32_16x16x32_bf16 v[60:63], v[120:123], v[160:163], v[60:63]
	v_mfma_f32_16x16x32_bf16 v[56:59], v[136:139], v[160:163], v[56:59]
	v_mfma_f32_16x16x32_bf16 v[44:47], v[120:123], v[168:171], v[44:47]
	v_mfma_f32_16x16x32_bf16 v[40:43], v[136:139], v[168:171], v[40:43]
	v_mfma_f32_16x16x32_bf16 v[28:31], v[120:123], v[176:179], v[28:31]
	v_mfma_f32_16x16x32_bf16 v[24:27], v[136:139], v[176:179], v[24:27]
	v_mfma_f32_16x16x32_bf16 v[12:15], v[120:123], v[200:203], v[12:15]
	v_mfma_f32_16x16x32_bf16 v[8:11], v[136:139], v[200:203], v[8:11]
	v_mfma_f32_16x16x32_bf16 v[60:63], v[132:135], v[164:167], v[60:63]
	v_mfma_f32_16x16x32_bf16 v[56:59], v[140:143], v[164:167], v[56:59]
	v_mfma_f32_16x16x32_bf16 v[44:47], v[132:135], v[172:175], v[44:47]
	v_mfma_f32_16x16x32_bf16 v[40:43], v[140:143], v[172:175], v[40:43]
	v_mfma_f32_16x16x32_bf16 v[28:31], v[132:135], v[180:183], v[28:31]
	v_mfma_f32_16x16x32_bf16 v[24:27], v[140:143], v[180:183], v[24:27]
	v_mfma_f32_16x16x32_bf16 v[12:15], v[132:135], v[204:207], v[12:15]
	v_mfma_f32_16x16x32_bf16 v[8:11], v[140:143], v[204:207], v[8:11]
	s_setprio 0
	s_setprio 1
	v_mfma_f32_16x16x32_bf16 v[52:55], v[144:147], v[160:163], v[52:55]
	v_mfma_f32_16x16x32_bf16 v[48:51], v[152:155], v[160:163], v[48:51]
	v_mfma_f32_16x16x32_bf16 v[36:39], v[144:147], v[168:171], v[36:39]
	v_mfma_f32_16x16x32_bf16 v[32:35], v[152:155], v[168:171], v[32:35]
	v_mfma_f32_16x16x32_bf16 v[20:23], v[144:147], v[176:179], v[20:23]
	v_mfma_f32_16x16x32_bf16 v[16:19], v[152:155], v[176:179], v[16:19]
	v_mfma_f32_16x16x32_bf16 v[4:7], v[144:147], v[200:203], v[4:7]
	v_mfma_f32_16x16x32_bf16 v[0:3], v[152:155], v[200:203], v[0:3]
	v_mfma_f32_16x16x32_bf16 v[52:55], v[148:151], v[164:167], v[52:55]
	v_mfma_f32_16x16x32_bf16 v[48:51], v[156:159], v[164:167], v[48:51]
	v_mfma_f32_16x16x32_bf16 v[36:39], v[148:151], v[172:175], v[36:39]
	v_mfma_f32_16x16x32_bf16 v[32:35], v[156:159], v[172:175], v[32:35]
	s_setprio 2
	s_barrier
	v_mfma_f32_16x16x32_bf16 v[20:23], v[148:151], v[180:183], v[20:23]
	v_mfma_f32_16x16x32_bf16 v[16:19], v[156:159], v[180:183], v[16:19]
	v_mfma_f32_16x16x32_bf16 v[4:7], v[148:151], v[204:207], v[4:7]
	v_mfma_f32_16x16x32_bf16 v[0:3], v[156:159], v[204:207], v[0:3]
	s_setprio 2
	s_add_i32 s67, 0, 0x18000
	s_add_i32 s68, 0, 0x1c000
	v_add_u32_e32 v140, s67, v232
	v_add_u32_e32 v156, s68, v232
	ds_read_b128 v[120:123], v140
	ds_read_b128 v[132:135], v140 offset:1024
	ds_read_b128 v[136:139], v140 offset:2048
	ds_read_b128 v[140:143], v140 offset:3072
	ds_read_b128 v[144:147], v156
	ds_read_b128 v[148:151], v156 offset:1024
	ds_read_b128 v[152:155], v156 offset:2048
	ds_read_b128 v[156:159], v156 offset:3072
	s_add_u32 s42, s42, 0x40000
	s_addc_u32 s43, s43, 0
	s_mov_b32 m0, s54
	v_lshl_add_u64 v[216:217], s[42:43], 0, v[184:185]
	ds_read_b128 v[160:163], v235 offset:32768
	ds_read_b128 v[164:167], v235 offset:33792
	ds_read_b128 v[168:171], v235 offset:34816
	ds_read_b128 v[172:175], v235 offset:35840
	ds_read_b128 v[176:179], v235 offset:36864
	ds_read_b128 v[180:183], v235 offset:37888
	ds_read_b128 v[200:203], v235 offset:38912
	ds_read_b128 v[204:207], v235 offset:39936
	global_load_lds_dwordx4 v[216:217], off
	s_mov_b32 m0, s55
	v_lshl_add_u64 v[216:217], s[42:43], 0, v[188:189]
	global_load_lds_dwordx4 v[216:217], off
	s_waitcnt vmcnt(8)
	s_waitcnt lgkmcnt(0)
	s_barrier
	s_setprio 1
	s_waitcnt lgkmcnt(0)
	v_mfma_f32_16x16x32_bf16 v[128:131], v[120:123], v[160:163], v[128:131]
	v_mfma_f32_16x16x32_bf16 v[124:127], v[136:139], v[160:163], v[124:127]
	v_mfma_f32_16x16x32_bf16 v[108:111], v[120:123], v[168:171], v[108:111]
	v_mfma_f32_16x16x32_bf16 v[104:107], v[136:139], v[168:171], v[104:107]
	v_mfma_f32_16x16x32_bf16 v[92:95], v[120:123], v[176:179], v[92:95]
	v_mfma_f32_16x16x32_bf16 v[88:91], v[136:139], v[176:179], v[88:91]
	v_mfma_f32_16x16x32_bf16 v[76:79], v[120:123], v[200:203], v[76:79]
	v_mfma_f32_16x16x32_bf16 v[72:75], v[136:139], v[200:203], v[72:75]
	v_mfma_f32_16x16x32_bf16 v[128:131], v[132:135], v[164:167], v[128:131]
	v_mfma_f32_16x16x32_bf16 v[124:127], v[140:143], v[164:167], v[124:127]
	v_mfma_f32_16x16x32_bf16 v[108:111], v[132:135], v[172:175], v[108:111]
	v_mfma_f32_16x16x32_bf16 v[104:107], v[140:143], v[172:175], v[104:107]
	v_mfma_f32_16x16x32_bf16 v[92:95], v[132:135], v[180:183], v[92:95]
	v_mfma_f32_16x16x32_bf16 v[88:91], v[140:143], v[180:183], v[88:91]
	v_mfma_f32_16x16x32_bf16 v[76:79], v[132:135], v[204:207], v[76:79]
	v_mfma_f32_16x16x32_bf16 v[72:75], v[140:143], v[204:207], v[72:75]
	s_setprio 0
	s_setprio 1
	v_mfma_f32_16x16x32_bf16 v[116:119], v[144:147], v[160:163], v[116:119]
	v_mfma_f32_16x16x32_bf16 v[112:115], v[152:155], v[160:163], v[112:115]
	v_mfma_f32_16x16x32_bf16 v[100:103], v[144:147], v[168:171], v[100:103]
	v_mfma_f32_16x16x32_bf16 v[96:99], v[152:155], v[168:171], v[96:99]
	v_mfma_f32_16x16x32_bf16 v[84:87], v[144:147], v[176:179], v[84:87]
	v_mfma_f32_16x16x32_bf16 v[80:83], v[152:155], v[176:179], v[80:83]
	v_mfma_f32_16x16x32_bf16 v[68:71], v[144:147], v[200:203], v[68:71]
	v_mfma_f32_16x16x32_bf16 v[64:67], v[152:155], v[200:203], v[64:67]
	v_mfma_f32_16x16x32_bf16 v[116:119], v[148:151], v[164:167], v[116:119]
	v_mfma_f32_16x16x32_bf16 v[112:115], v[156:159], v[164:167], v[112:115]
	v_mfma_f32_16x16x32_bf16 v[100:103], v[148:151], v[172:175], v[100:103]
	v_mfma_f32_16x16x32_bf16 v[96:99], v[156:159], v[172:175], v[96:99]
	s_setprio 2
	s_barrier
	v_mfma_f32_16x16x32_bf16 v[84:87], v[148:151], v[180:183], v[84:87]
	v_mfma_f32_16x16x32_bf16 v[80:83], v[156:159], v[180:183], v[80:83]
	v_mfma_f32_16x16x32_bf16 v[68:71], v[148:151], v[204:207], v[68:71]
	v_mfma_f32_16x16x32_bf16 v[64:67], v[156:159], v[204:207], v[64:67]
	s_setprio 2
	s_add_i32 s42, s67, s49
	v_lshl_add_u64 v[208:209], v[208:209], 0, s[18:19]
	s_mov_b32 m0, s42
	ds_read_b128 v[160:163], v235 offset:49152
	ds_read_b128 v[164:167], v235 offset:50176
	ds_read_b128 v[168:171], v235 offset:51200
	ds_read_b128 v[172:175], v235 offset:52224
	ds_read_b128 v[176:179], v235 offset:53248
	ds_read_b128 v[180:183], v235 offset:54272
	ds_read_b128 v[200:203], v235 offset:55296
	ds_read_b128 v[204:207], v235 offset:56320
	global_load_lds_dwordx4 v[208:209], off
	s_add_i32 m0, s42, 0x2000
	s_add_u32 s40, s40, 0x40080
	v_lshl_add_u64 v[208:209], v[210:211], 0, s[18:19]
	s_addc_u32 s41, s41, 0
	s_add_i32 s42, s68, s49
	global_load_lds_dwordx4 v[208:209], off
	s_mov_b32 m0, s42
	v_lshl_add_u64 v[208:209], s[40:41], 0, v[186:187]
	global_load_lds_dwordx4 v[208:209], off
	s_add_i32 m0, s42, 0x2000
	v_lshl_add_u64 v[208:209], s[40:41], 0, v[190:191]
	global_load_lds_dwordx4 v[208:209], off
	s_mov_b32 m0, s57
	v_lshl_add_u64 v[208:209], v[212:213], 0, s[18:19]
	global_load_lds_dwordx4 v[208:209], off
	s_mov_b32 m0, s58
	v_lshl_add_u64 v[208:209], v[214:215], 0, s[18:19]
	global_load_lds_dwordx4 v[208:209], off
	s_waitcnt vmcnt(8)
	s_waitcnt lgkmcnt(0)
	s_barrier
	s_setprio 1
	s_waitcnt lgkmcnt(0)
	v_mfma_f32_16x16x32_bf16 v[60:63], v[120:123], v[160:163], v[60:63]
	v_mfma_f32_16x16x32_bf16 v[56:59], v[136:139], v[160:163], v[56:59]
	v_mfma_f32_16x16x32_bf16 v[44:47], v[120:123], v[168:171], v[44:47]
	v_mfma_f32_16x16x32_bf16 v[40:43], v[136:139], v[168:171], v[40:43]
	v_mfma_f32_16x16x32_bf16 v[28:31], v[120:123], v[176:179], v[28:31]
	v_mfma_f32_16x16x32_bf16 v[24:27], v[136:139], v[176:179], v[24:27]
	v_mfma_f32_16x16x32_bf16 v[12:15], v[120:123], v[200:203], v[12:15]
	v_mfma_f32_16x16x32_bf16 v[8:11], v[136:139], v[200:203], v[8:11]
	v_mfma_f32_16x16x32_bf16 v[60:63], v[132:135], v[164:167], v[60:63]
	v_mfma_f32_16x16x32_bf16 v[56:59], v[140:143], v[164:167], v[56:59]
	v_mfma_f32_16x16x32_bf16 v[44:47], v[132:135], v[172:175], v[44:47]
	v_mfma_f32_16x16x32_bf16 v[40:43], v[140:143], v[172:175], v[40:43]
	v_mfma_f32_16x16x32_bf16 v[28:31], v[132:135], v[180:183], v[28:31]
	v_mfma_f32_16x16x32_bf16 v[24:27], v[140:143], v[180:183], v[24:27]
	v_mfma_f32_16x16x32_bf16 v[12:15], v[132:135], v[204:207], v[12:15]
	v_mfma_f32_16x16x32_bf16 v[8:11], v[140:143], v[204:207], v[8:11]
	s_setprio 0
	s_setprio 1
	v_mfma_f32_16x16x32_bf16 v[52:55], v[144:147], v[160:163], v[52:55]
	v_mfma_f32_16x16x32_bf16 v[48:51], v[152:155], v[160:163], v[48:51]
	v_mfma_f32_16x16x32_bf16 v[36:39], v[144:147], v[168:171], v[36:39]
	v_mfma_f32_16x16x32_bf16 v[32:35], v[152:155], v[168:171], v[32:35]
	v_mfma_f32_16x16x32_bf16 v[20:23], v[144:147], v[176:179], v[20:23]
	v_mfma_f32_16x16x32_bf16 v[16:19], v[152:155], v[176:179], v[16:19]
	v_mfma_f32_16x16x32_bf16 v[4:7], v[144:147], v[200:203], v[4:7]
	v_mfma_f32_16x16x32_bf16 v[0:3], v[152:155], v[200:203], v[0:3]
	v_mfma_f32_16x16x32_bf16 v[52:55], v[148:151], v[164:167], v[52:55]
	v_mfma_f32_16x16x32_bf16 v[48:51], v[156:159], v[164:167], v[48:51]
	v_mfma_f32_16x16x32_bf16 v[36:39], v[148:151], v[172:175], v[36:39]
	v_mfma_f32_16x16x32_bf16 v[32:35], v[156:159], v[172:175], v[32:35]
	s_setprio 2
	s_barrier
	v_mfma_f32_16x16x32_bf16 v[20:23], v[148:151], v[180:183], v[20:23]
	v_mfma_f32_16x16x32_bf16 v[16:19], v[156:159], v[180:183], v[16:19]
	v_mfma_f32_16x16x32_bf16 v[4:7], v[148:151], v[204:207], v[4:7]
	v_mfma_f32_16x16x32_bf16 v[0:3], v[156:159], v[204:207], v[0:3]
	s_setprio 0
	s_add_i32 s66, s66, 2
	s_add_u32 s38, s38, 0x100
	s_addc_u32 s39, s39, 0
	s_add_u32 s64, s64, 0x100
	s_addc_u32 s65, s65, 0
	s_cmp_gt_u32 s66, 13
	s_cbranch_scc0 .LBB0_1146

.LBB0_1309:
	s_add_u32 s51, s26, 0x100
	s_addc_u32 s52, s27, 0
	s_mov_b32 s53, -2
	ds_read_b128 v[128:131], v197
	ds_read_b128 v[132:135], v197 offset:1024
	ds_read_b128 v[136:139], v197 offset:2048
	ds_read_b128 v[140:143], v197 offset:3072
	ds_read_b128 v[144:147], v198
	ds_read_b128 v[148:151], v198 offset:1024
	ds_read_b128 v[152:155], v198 offset:2048
	ds_read_b128 v[156:159], v198 offset:3072
	s_add_u32 s4, s24, 0x100
	s_addc_u32 s5, s25, 0
	s_cmp_eq_u32 s53, 40
	s_cselect_b32 s29, s21, s5
	s_cselect_b32 s28, s20, s4
	s_cselect_b32 s27, s23, s52
	s_cselect_b32 s26, s22, s51
	v_lshl_add_u64 v[212:213], s[24:25], 0, v[172:173]
	s_add_i32 m0, s36, 0xc000
	ds_read_b128 v[160:163], v199
	ds_read_b128 v[180:183], v199 offset:1024
	ds_read_b128 v[184:187], v199 offset:2048
	ds_read_b128 v[188:191], v199 offset:3072
	ds_read_b128 v[192:195], v199 offset:4096
	ds_read_b128 v[200:203], v199 offset:5120
	ds_read_b128 v[204:207], v199 offset:6144
	ds_read_b128 v[208:211], v199 offset:7168
	global_load_lds_dwordx4 v[212:213], off
	s_add_i32 m0, s36, 0xe000
	v_lshl_add_u64 v[212:213], s[24:25], 0, v[174:175]
	global_load_lds_dwordx4 v[212:213], off
	s_waitcnt vmcnt(8)
	s_waitcnt lgkmcnt(0)
	s_barrier
	s_setprio 1
	s_waitcnt lgkmcnt(0)
	v_mfma_f32_16x16x32_bf16 v[124:127], v[128:131], v[160:163], 0
	v_mfma_f32_16x16x32_bf16 v[120:123], v[136:139], v[160:163], 0
	v_mfma_f32_16x16x32_bf16 v[116:119], v[128:131], v[184:187], 0
	v_mfma_f32_16x16x32_bf16 v[108:111], v[136:139], v[184:187], 0
	v_mfma_f32_16x16x32_bf16 v[88:91], v[128:131], v[192:195], 0
	v_mfma_f32_16x16x32_bf16 v[100:103], v[136:139], v[192:195], 0
	v_mfma_f32_16x16x32_bf16 v[72:75], v[128:131], v[204:207], 0
	v_mfma_f32_16x16x32_bf16 v[76:79], v[136:139], v[204:207], 0
	v_mfma_f32_16x16x32_bf16 v[124:127], v[132:135], v[180:183], v[124:127]
	v_mfma_f32_16x16x32_bf16 v[120:123], v[140:143], v[180:183], v[120:123]
	v_mfma_f32_16x16x32_bf16 v[116:119], v[132:135], v[188:191], v[116:119]
	v_mfma_f32_16x16x32_bf16 v[108:111], v[140:143], v[188:191], v[108:111]
	v_mfma_f32_16x16x32_bf16 v[88:91], v[132:135], v[200:203], v[88:91]
	v_mfma_f32_16x16x32_bf16 v[100:103], v[140:143], v[200:203], v[100:103]
	v_mfma_f32_16x16x32_bf16 v[72:75], v[132:135], v[208:211], v[72:75]
	v_mfma_f32_16x16x32_bf16 v[76:79], v[140:143], v[208:211], v[76:79]
	s_setprio 0
	s_setprio 1
	v_mfma_f32_16x16x32_bf16 v[112:115], v[144:147], v[160:163], 0
	v_mfma_f32_16x16x32_bf16 v[104:107], v[152:155], v[160:163], 0
	v_mfma_f32_16x16x32_bf16 v[96:99], v[144:147], v[184:187], 0
	v_mfma_f32_16x16x32_bf16 v[92:95], v[152:155], v[184:187], 0
	v_mfma_f32_16x16x32_bf16 v[80:83], v[144:147], v[192:195], 0
	v_mfma_f32_16x16x32_bf16 v[84:87], v[152:155], v[192:195], 0
	v_mfma_f32_16x16x32_bf16 v[64:67], v[144:147], v[204:207], 0
	v_mfma_f32_16x16x32_bf16 v[68:71], v[152:155], v[204:207], 0
	v_mfma_f32_16x16x32_bf16 v[112:115], v[148:151], v[180:183], v[112:115]
	v_mfma_f32_16x16x32_bf16 v[104:107], v[156:159], v[180:183], v[104:107]
	v_mfma_f32_16x16x32_bf16 v[96:99], v[148:151], v[188:191], v[96:99]
	v_mfma_f32_16x16x32_bf16 v[92:95], v[156:159], v[188:191], v[92:95]
	s_setprio 2
	s_barrier
	v_mfma_f32_16x16x32_bf16 v[80:83], v[148:151], v[200:203], v[80:83]
	v_mfma_f32_16x16x32_bf16 v[84:87], v[156:159], v[200:203], v[84:87]
	v_mfma_f32_16x16x32_bf16 v[64:67], v[148:151], v[208:211], v[64:67]
	v_mfma_f32_16x16x32_bf16 v[68:71], v[156:159], v[208:211], v[68:71]
	s_setprio 2
	s_add_i32 s24, s45, s35
	v_lshl_add_u64 v[212:213], s[26:27], 0, v[166:167]
	s_mov_b32 m0, s24
	ds_read_b128 v[160:163], v199 offset:16384
	ds_read_b128 v[180:183], v199 offset:17408
	ds_read_b128 v[184:187], v199 offset:18432
	ds_read_b128 v[188:191], v199 offset:19456
	ds_read_b128 v[192:195], v199 offset:20480
	ds_read_b128 v[200:203], v199 offset:21504
	ds_read_b128 v[204:207], v199 offset:22528
	ds_read_b128 v[208:211], v199 offset:23552
	global_load_lds_dwordx4 v[212:213], off
	s_add_i32 m0, s24, 0x2000
	s_add_u32 s24, s26, 0xb0000
	v_lshl_add_u64 v[214:215], s[26:27], 0, v[170:171]
	s_addc_u32 s25, s27, 0
	s_add_i32 s54, s46, s35
	global_load_lds_dwordx4 v[214:215], off
	v_lshl_add_u64 v[216:217], s[24:25], 0, v[166:167]
	s_mov_b32 m0, s54
	v_lshl_add_u64 v[218:219], s[28:29], 0, v[168:169]
	global_load_lds_dwordx4 v[216:217], off
	s_add_i32 m0, s54, 0x2000
	v_lshl_add_u64 v[216:217], s[24:25], 0, v[170:171]
	global_load_lds_dwordx4 v[216:217], off
	s_mov_b32 m0, s36
	v_lshl_add_u64 v[216:217], s[28:29], 0, v[164:165]
	global_load_lds_dwordx4 v[216:217], off
	s_mov_b32 m0, s37
	s_nop 0
	global_load_lds_dwordx4 v[218:219], off
	s_waitcnt vmcnt(8)
	s_waitcnt lgkmcnt(0)
	s_barrier
	s_setprio 1
	s_waitcnt lgkmcnt(0)
	v_mfma_f32_16x16x32_bf16 v[56:59], v[128:131], v[160:163], 0
	v_mfma_f32_16x16x32_bf16 v[60:63], v[136:139], v[160:163], 0
	v_mfma_f32_16x16x32_bf16 v[40:43], v[128:131], v[184:187], 0
	v_mfma_f32_16x16x32_bf16 v[44:47], v[136:139], v[184:187], 0
	v_mfma_f32_16x16x32_bf16 v[24:27], v[128:131], v[192:195], 0
	v_mfma_f32_16x16x32_bf16 v[28:31], v[136:139], v[192:195], 0
	v_mfma_f32_16x16x32_bf16 v[8:11], v[128:131], v[204:207], 0
	v_mfma_f32_16x16x32_bf16 v[12:15], v[136:139], v[204:207], 0
	v_mfma_f32_16x16x32_bf16 v[56:59], v[132:135], v[180:183], v[56:59]
	v_mfma_f32_16x16x32_bf16 v[60:63], v[140:143], v[180:183], v[60:63]
	v_mfma_f32_16x16x32_bf16 v[40:43], v[132:135], v[188:191], v[40:43]
	v_mfma_f32_16x16x32_bf16 v[44:47], v[140:143], v[188:191], v[44:47]
	v_mfma_f32_16x16x32_bf16 v[24:27], v[132:135], v[200:203], v[24:27]
	v_mfma_f32_16x16x32_bf16 v[28:31], v[140:143], v[200:203], v[28:31]
	v_mfma_f32_16x16x32_bf16 v[8:11], v[132:135], v[208:211], v[8:11]
	v_mfma_f32_16x16x32_bf16 v[12:15], v[140:143], v[208:211], v[12:15]
	s_setprio 0
	s_setprio 1
	v_mfma_f32_16x16x32_bf16 v[48:51], v[144:147], v[160:163], 0
	v_mfma_f32_16x16x32_bf16 v[52:55], v[152:155], v[160:163], 0
	v_mfma_f32_16x16x32_bf16 v[32:35], v[144:147], v[184:187], 0
	v_mfma_f32_16x16x32_bf16 v[36:39], v[152:155], v[184:187], 0
	v_mfma_f32_16x16x32_bf16 v[16:19], v[144:147], v[192:195], 0
	v_mfma_f32_16x16x32_bf16 v[20:23], v[152:155], v[192:195], 0
	v_mfma_f32_16x16x32_bf16 v[0:3], v[144:147], v[204:207], 0
	v_mfma_f32_16x16x32_bf16 v[4:7], v[152:155], v[204:207], 0
	v_mfma_f32_16x16x32_bf16 v[48:51], v[148:151], v[180:183], v[48:51]
	v_mfma_f32_16x16x32_bf16 v[52:55], v[156:159], v[180:183], v[52:55]
	v_mfma_f32_16x16x32_bf16 v[32:35], v[148:151], v[188:191], v[32:35]
	v_mfma_f32_16x16x32_bf16 v[36:39], v[156:159], v[188:191], v[36:39]
	s_setprio 2
	s_barrier
	v_mfma_f32_16x16x32_bf16 v[16:19], v[148:151], v[200:203], v[16:19]
	v_mfma_f32_16x16x32_bf16 v[20:23], v[156:159], v[200:203], v[20:23]
	v_mfma_f32_16x16x32_bf16 v[0:3], v[148:151], v[208:211], v[0:3]
	v_mfma_f32_16x16x32_bf16 v[4:7], v[156:159], v[208:211], v[4:7]
	s_setprio 2
	s_add_i32 s54, 0, 0x18000
	s_add_i32 s55, 0, 0x1c000
	v_add_u32_e32 v140, s54, v196
	v_add_u32_e32 v156, s55, v196
	ds_read_b128 v[128:131], v140
	ds_read_b128 v[132:135], v140 offset:1024
	ds_read_b128 v[136:139], v140 offset:2048
	ds_read_b128 v[140:143], v140 offset:3072
	ds_read_b128 v[144:147], v156
	ds_read_b128 v[148:151], v156 offset:1024
	ds_read_b128 v[152:155], v156 offset:2048
	ds_read_b128 v[156:159], v156 offset:3072
	s_add_u32 s24, s28, 0xb0000
	s_addc_u32 s25, s29, 0
	s_mov_b32 m0, s38
	v_lshl_add_u64 v[220:221], s[24:25], 0, v[164:165]
	ds_read_b128 v[160:163], v199 offset:32768
	ds_read_b128 v[180:183], v199 offset:33792
	ds_read_b128 v[184:187], v199 offset:34816
	ds_read_b128 v[188:191], v199 offset:35840
	ds_read_b128 v[192:195], v199 offset:36864
	ds_read_b128 v[200:203], v199 offset:37888
	ds_read_b128 v[204:207], v199 offset:38912
	ds_read_b128 v[208:211], v199 offset:39936
	global_load_lds_dwordx4 v[220:221], off
	s_mov_b32 m0, s39
	v_lshl_add_u64 v[220:221], s[24:25], 0, v[168:169]
	global_load_lds_dwordx4 v[220:221], off
	s_waitcnt vmcnt(8)
	s_waitcnt lgkmcnt(0)
	s_barrier
	s_setprio 1
	s_waitcnt lgkmcnt(0)
	v_mfma_f32_16x16x32_bf16 v[124:127], v[128:131], v[160:163], v[124:127]
	v_mfma_f32_16x16x32_bf16 v[120:123], v[136:139], v[160:163], v[120:123]
	v_mfma_f32_16x16x32_bf16 v[116:119], v[128:131], v[184:187], v[116:119]
	v_mfma_f32_16x16x32_bf16 v[108:111], v[136:139], v[184:187], v[108:111]
	v_mfma_f32_16x16x32_bf16 v[88:91], v[128:131], v[192:195], v[88:91]
	v_mfma_f32_16x16x32_bf16 v[100:103], v[136:139], v[192:195], v[100:103]
	v_mfma_f32_16x16x32_bf16 v[72:75], v[128:131], v[204:207], v[72:75]
	v_mfma_f32_16x16x32_bf16 v[76:79], v[136:139], v[204:207], v[76:79]
	v_mfma_f32_16x16x32_bf16 v[124:127], v[132:135], v[180:183], v[124:127]
	v_mfma_f32_16x16x32_bf16 v[120:123], v[140:143], v[180:183], v[120:123]
	v_mfma_f32_16x16x32_bf16 v[116:119], v[132:135], v[188:191], v[116:119]
	v_mfma_f32_16x16x32_bf16 v[108:111], v[140:143], v[188:191], v[108:111]
	v_mfma_f32_16x16x32_bf16 v[88:91], v[132:135], v[200:203], v[88:91]
	v_mfma_f32_16x16x32_bf16 v[100:103], v[140:143], v[200:203], v[100:103]
	v_mfma_f32_16x16x32_bf16 v[72:75], v[132:135], v[208:211], v[72:75]
	v_mfma_f32_16x16x32_bf16 v[76:79], v[140:143], v[208:211], v[76:79]
	s_setprio 0
	s_setprio 1
	v_mfma_f32_16x16x32_bf16 v[112:115], v[144:147], v[160:163], v[112:115]
	v_mfma_f32_16x16x32_bf16 v[104:107], v[152:155], v[160:163], v[104:107]
	v_mfma_f32_16x16x32_bf16 v[96:99], v[144:147], v[184:187], v[96:99]
	v_mfma_f32_16x16x32_bf16 v[92:95], v[152:155], v[184:187], v[92:95]
	v_mfma_f32_16x16x32_bf16 v[80:83], v[144:147], v[192:195], v[80:83]
	v_mfma_f32_16x16x32_bf16 v[84:87], v[152:155], v[192:195], v[84:87]
	v_mfma_f32_16x16x32_bf16 v[64:67], v[144:147], v[204:207], v[64:67]
	v_mfma_f32_16x16x32_bf16 v[68:71], v[152:155], v[204:207], v[68:71]
	v_mfma_f32_16x16x32_bf16 v[112:115], v[148:151], v[180:183], v[112:115]
	v_mfma_f32_16x16x32_bf16 v[104:107], v[156:159], v[180:183], v[104:107]
	v_mfma_f32_16x16x32_bf16 v[96:99], v[148:151], v[188:191], v[96:99]
	v_mfma_f32_16x16x32_bf16 v[92:95], v[156:159], v[188:191], v[92:95]
	s_setprio 2
	s_barrier
	v_mfma_f32_16x16x32_bf16 v[80:83], v[148:151], v[200:203], v[80:83]
	v_mfma_f32_16x16x32_bf16 v[84:87], v[156:159], v[200:203], v[84:87]
	v_mfma_f32_16x16x32_bf16 v[64:67], v[148:151], v[208:211], v[64:67]
	v_mfma_f32_16x16x32_bf16 v[68:71], v[156:159], v[208:211], v[68:71]
	s_setprio 2
	s_add_i32 s24, s54, s35
	v_lshl_add_u64 v[212:213], v[212:213], 0, s[16:17]
	s_mov_b32 m0, s24
	ds_read_b128 v[160:163], v199 offset:49152
	ds_read_b128 v[180:183], v199 offset:50176
	ds_read_b128 v[184:187], v199 offset:51200
	ds_read_b128 v[188:191], v199 offset:52224
	ds_read_b128 v[192:195], v199 offset:53248
	ds_read_b128 v[200:203], v199 offset:54272
	ds_read_b128 v[204:207], v199 offset:55296
	ds_read_b128 v[208:211], v199 offset:56320
	global_load_lds_dwordx4 v[212:213], off
	s_add_i32 m0, s24, 0x2000
	s_add_u32 s24, s26, 0xb0080
	v_lshl_add_u64 v[212:213], v[214:215], 0, s[16:17]
	s_addc_u32 s25, s27, 0
	s_add_i32 s26, s55, s35
	global_load_lds_dwordx4 v[212:213], off
	s_mov_b32 m0, s26
	v_lshl_add_u64 v[212:213], s[24:25], 0, v[166:167]
	global_load_lds_dwordx4 v[212:213], off
	s_add_i32 m0, s26, 0x2000
	v_lshl_add_u64 v[212:213], s[24:25], 0, v[170:171]
	global_load_lds_dwordx4 v[212:213], off
	s_mov_b32 m0, s41
	v_lshl_add_u64 v[212:213], v[216:217], 0, s[16:17]
	global_load_lds_dwordx4 v[212:213], off
	s_mov_b32 m0, s42
	v_lshl_add_u64 v[212:213], v[218:219], 0, s[16:17]
	global_load_lds_dwordx4 v[212:213], off
	s_waitcnt vmcnt(8)
	s_waitcnt lgkmcnt(0)
	s_barrier
	s_setprio 1
	s_waitcnt lgkmcnt(0)
	v_mfma_f32_16x16x32_bf16 v[56:59], v[128:131], v[160:163], v[56:59]
	v_mfma_f32_16x16x32_bf16 v[60:63], v[136:139], v[160:163], v[60:63]
	v_mfma_f32_16x16x32_bf16 v[40:43], v[128:131], v[184:187], v[40:43]
	v_mfma_f32_16x16x32_bf16 v[44:47], v[136:139], v[184:187], v[44:47]
	v_mfma_f32_16x16x32_bf16 v[24:27], v[128:131], v[192:195], v[24:27]
	v_mfma_f32_16x16x32_bf16 v[28:31], v[136:139], v[192:195], v[28:31]
	v_mfma_f32_16x16x32_bf16 v[8:11], v[128:131], v[204:207], v[8:11]
	v_mfma_f32_16x16x32_bf16 v[12:15], v[136:139], v[204:207], v[12:15]
	v_mfma_f32_16x16x32_bf16 v[56:59], v[132:135], v[180:183], v[56:59]
	v_mfma_f32_16x16x32_bf16 v[60:63], v[140:143], v[180:183], v[60:63]
	v_mfma_f32_16x16x32_bf16 v[40:43], v[132:135], v[188:191], v[40:43]
	v_mfma_f32_16x16x32_bf16 v[44:47], v[140:143], v[188:191], v[44:47]
	v_mfma_f32_16x16x32_bf16 v[24:27], v[132:135], v[200:203], v[24:27]
	v_mfma_f32_16x16x32_bf16 v[28:31], v[140:143], v[200:203], v[28:31]
	v_mfma_f32_16x16x32_bf16 v[8:11], v[132:135], v[208:211], v[8:11]
	v_mfma_f32_16x16x32_bf16 v[12:15], v[140:143], v[208:211], v[12:15]
	s_setprio 0
	s_setprio 1
	v_mfma_f32_16x16x32_bf16 v[48:51], v[144:147], v[160:163], v[48:51]
	v_mfma_f32_16x16x32_bf16 v[52:55], v[152:155], v[160:163], v[52:55]
	v_mfma_f32_16x16x32_bf16 v[32:35], v[144:147], v[184:187], v[32:35]
	v_mfma_f32_16x16x32_bf16 v[36:39], v[152:155], v[184:187], v[36:39]
	v_mfma_f32_16x16x32_bf16 v[16:19], v[144:147], v[192:195], v[16:19]
	v_mfma_f32_16x16x32_bf16 v[20:23], v[152:155], v[192:195], v[20:23]
	v_mfma_f32_16x16x32_bf16 v[0:3], v[144:147], v[204:207], v[0:3]
	v_mfma_f32_16x16x32_bf16 v[4:7], v[152:155], v[204:207], v[4:7]
	v_mfma_f32_16x16x32_bf16 v[48:51], v[148:151], v[180:183], v[48:51]
	v_mfma_f32_16x16x32_bf16 v[52:55], v[156:159], v[180:183], v[52:55]
	v_mfma_f32_16x16x32_bf16 v[32:35], v[148:151], v[188:191], v[32:35]
	v_mfma_f32_16x16x32_bf16 v[36:39], v[156:159], v[188:191], v[36:39]
	s_setprio 2
	s_barrier
	v_mfma_f32_16x16x32_bf16 v[16:19], v[148:151], v[200:203], v[16:19]
	v_mfma_f32_16x16x32_bf16 v[20:23], v[156:159], v[200:203], v[20:23]
	v_mfma_f32_16x16x32_bf16 v[0:3], v[148:151], v[208:211], v[0:3]
	v_mfma_f32_16x16x32_bf16 v[4:7], v[156:159], v[208:211], v[4:7]
	s_setprio 2
	s_add_i32 s53, s53, 2
	s_add_u32 s51, s51, 0x100
	s_addc_u32 s52, s52, 0
	s_cmp_gt_u32 s53, 41
	s_mov_b64 s[24:25], s[4:5]
.LBB0_1310:
	ds_read_b128 v[128:131], v197
	ds_read_b128 v[132:135], v197 offset:1024
	ds_read_b128 v[136:139], v197 offset:2048
	ds_read_b128 v[140:143], v197 offset:3072
	ds_read_b128 v[144:147], v198
	ds_read_b128 v[148:151], v198 offset:1024
	ds_read_b128 v[152:155], v198 offset:2048
	ds_read_b128 v[156:159], v198 offset:3072
	s_add_u32 s4, s24, 0x100
	s_addc_u32 s5, s25, 0
	s_cmp_eq_u32 s53, 40
	s_cselect_b32 s29, s21, s5
	s_cselect_b32 s28, s20, s4
	s_cselect_b32 s27, s23, s52
	s_cselect_b32 s26, s22, s51
	v_lshl_add_u64 v[212:213], s[24:25], 0, v[172:173]
	s_add_i32 m0, s36, 0xc000
	ds_read_b128 v[160:163], v199
	ds_read_b128 v[180:183], v199 offset:1024
	ds_read_b128 v[184:187], v199 offset:2048
	ds_read_b128 v[188:191], v199 offset:3072
	ds_read_b128 v[192:195], v199 offset:4096
	ds_read_b128 v[200:203], v199 offset:5120
	ds_read_b128 v[204:207], v199 offset:6144
	ds_read_b128 v[208:211], v199 offset:7168
	global_load_lds_dwordx4 v[212:213], off
	s_add_i32 m0, s36, 0xe000
	v_lshl_add_u64 v[212:213], s[24:25], 0, v[174:175]
	global_load_lds_dwordx4 v[212:213], off
	s_waitcnt vmcnt(8)
	s_waitcnt lgkmcnt(0)
	s_barrier
	s_setprio 1
	s_waitcnt lgkmcnt(0)
	v_mfma_f32_16x16x32_bf16 v[124:127], v[128:131], v[160:163], v[124:127]
	v_mfma_f32_16x16x32_bf16 v[120:123], v[136:139], v[160:163], v[120:123]
	v_mfma_f32_16x16x32_bf16 v[116:119], v[128:131], v[184:187], v[116:119]
	v_mfma_f32_16x16x32_bf16 v[108:111], v[136:139], v[184:187], v[108:111]
	v_mfma_f32_16x16x32_bf16 v[88:91], v[128:131], v[192:195], v[88:91]
	v_mfma_f32_16x16x32_bf16 v[100:103], v[136:139], v[192:195], v[100:103]
	v_mfma_f32_16x16x32_bf16 v[72:75], v[128:131], v[204:207], v[72:75]
	v_mfma_f32_16x16x32_bf16 v[76:79], v[136:139], v[204:207], v[76:79]
	v_mfma_f32_16x16x32_bf16 v[124:127], v[132:135], v[180:183], v[124:127]
	v_mfma_f32_16x16x32_bf16 v[120:123], v[140:143], v[180:183], v[120:123]
	v_mfma_f32_16x16x32_bf16 v[116:119], v[132:135], v[188:191], v[116:119]
	v_mfma_f32_16x16x32_bf16 v[108:111], v[140:143], v[188:191], v[108:111]
	v_mfma_f32_16x16x32_bf16 v[88:91], v[132:135], v[200:203], v[88:91]
	v_mfma_f32_16x16x32_bf16 v[100:103], v[140:143], v[200:203], v[100:103]
	v_mfma_f32_16x16x32_bf16 v[72:75], v[132:135], v[208:211], v[72:75]
	v_mfma_f32_16x16x32_bf16 v[76:79], v[140:143], v[208:211], v[76:79]
	s_setprio 0
	s_setprio 1
	v_mfma_f32_16x16x32_bf16 v[112:115], v[144:147], v[160:163], v[112:115]
	v_mfma_f32_16x16x32_bf16 v[104:107], v[152:155], v[160:163], v[104:107]
	v_mfma_f32_16x16x32_bf16 v[96:99], v[144:147], v[184:187], v[96:99]
	v_mfma_f32_16x16x32_bf16 v[92:95], v[152:155], v[184:187], v[92:95]
	v_mfma_f32_16x16x32_bf16 v[80:83], v[144:147], v[192:195], v[80:83]
	v_mfma_f32_16x16x32_bf16 v[84:87], v[152:155], v[192:195], v[84:87]
	v_mfma_f32_16x16x32_bf16 v[64:67], v[144:147], v[204:207], v[64:67]
	v_mfma_f32_16x16x32_bf16 v[68:71], v[152:155], v[204:207], v[68:71]
	v_mfma_f32_16x16x32_bf16 v[112:115], v[148:151], v[180:183], v[112:115]
	v_mfma_f32_16x16x32_bf16 v[104:107], v[156:159], v[180:183], v[104:107]
	v_mfma_f32_16x16x32_bf16 v[96:99], v[148:151], v[188:191], v[96:99]
	v_mfma_f32_16x16x32_bf16 v[92:95], v[156:159], v[188:191], v[92:95]
	s_setprio 2
	s_barrier
	v_mfma_f32_16x16x32_bf16 v[80:83], v[148:151], v[200:203], v[80:83]
	v_mfma_f32_16x16x32_bf16 v[84:87], v[156:159], v[200:203], v[84:87]
	v_mfma_f32_16x16x32_bf16 v[64:67], v[148:151], v[208:211], v[64:67]
	v_mfma_f32_16x16x32_bf16 v[68:71], v[156:159], v[208:211], v[68:71]
	s_setprio 2
	s_add_i32 s24, s45, s35
	v_lshl_add_u64 v[212:213], s[26:27], 0, v[166:167]
	s_mov_b32 m0, s24
	ds_read_b128 v[160:163], v199 offset:16384
	ds_read_b128 v[180:183], v199 offset:17408
	ds_read_b128 v[184:187], v199 offset:18432
	ds_read_b128 v[188:191], v199 offset:19456
	ds_read_b128 v[192:195], v199 offset:20480
	ds_read_b128 v[200:203], v199 offset:21504
	ds_read_b128 v[204:207], v199 offset:22528
	ds_read_b128 v[208:211], v199 offset:23552
	global_load_lds_dwordx4 v[212:213], off
	s_add_i32 m0, s24, 0x2000
	s_add_u32 s24, s26, 0xb0000
	v_lshl_add_u64 v[214:215], s[26:27], 0, v[170:171]
	s_addc_u32 s25, s27, 0
	s_add_i32 s54, s46, s35
	global_load_lds_dwordx4 v[214:215], off
	v_lshl_add_u64 v[216:217], s[24:25], 0, v[166:167]
	s_mov_b32 m0, s54
	v_lshl_add_u64 v[218:219], s[28:29], 0, v[168:169]
	global_load_lds_dwordx4 v[216:217], off
	s_add_i32 m0, s54, 0x2000
	v_lshl_add_u64 v[216:217], s[24:25], 0, v[170:171]
	global_load_lds_dwordx4 v[216:217], off
	s_mov_b32 m0, s36
	v_lshl_add_u64 v[216:217], s[28:29], 0, v[164:165]
	global_load_lds_dwordx4 v[216:217], off
	s_mov_b32 m0, s37
	s_nop 0
	global_load_lds_dwordx4 v[218:219], off
	s_waitcnt vmcnt(8)
	s_waitcnt lgkmcnt(0)
	s_barrier
	s_setprio 1
	s_waitcnt lgkmcnt(0)
	v_mfma_f32_16x16x32_bf16 v[56:59], v[128:131], v[160:163], v[56:59]
	v_mfma_f32_16x16x32_bf16 v[60:63], v[136:139], v[160:163], v[60:63]
	v_mfma_f32_16x16x32_bf16 v[40:43], v[128:131], v[184:187], v[40:43]
	v_mfma_f32_16x16x32_bf16 v[44:47], v[136:139], v[184:187], v[44:47]
	v_mfma_f32_16x16x32_bf16 v[24:27], v[128:131], v[192:195], v[24:27]
	v_mfma_f32_16x16x32_bf16 v[28:31], v[136:139], v[192:195], v[28:31]
	v_mfma_f32_16x16x32_bf16 v[8:11], v[128:131], v[204:207], v[8:11]
	v_mfma_f32_16x16x32_bf16 v[12:15], v[136:139], v[204:207], v[12:15]
	v_mfma_f32_16x16x32_bf16 v[56:59], v[132:135], v[180:183], v[56:59]
	v_mfma_f32_16x16x32_bf16 v[60:63], v[140:143], v[180:183], v[60:63]
	v_mfma_f32_16x16x32_bf16 v[40:43], v[132:135], v[188:191], v[40:43]
	v_mfma_f32_16x16x32_bf16 v[44:47], v[140:143], v[188:191], v[44:47]
	v_mfma_f32_16x16x32_bf16 v[24:27], v[132:135], v[200:203], v[24:27]
	v_mfma_f32_16x16x32_bf16 v[28:31], v[140:143], v[200:203], v[28:31]
	v_mfma_f32_16x16x32_bf16 v[8:11], v[132:135], v[208:211], v[8:11]
	v_mfma_f32_16x16x32_bf16 v[12:15], v[140:143], v[208:211], v[12:15]
	s_setprio 0
	s_setprio 1
	v_mfma_f32_16x16x32_bf16 v[48:51], v[144:147], v[160:163], v[48:51]
	v_mfma_f32_16x16x32_bf16 v[52:55], v[152:155], v[160:163], v[52:55]
	v_mfma_f32_16x16x32_bf16 v[32:35], v[144:147], v[184:187], v[32:35]
	v_mfma_f32_16x16x32_bf16 v[36:39], v[152:155], v[184:187], v[36:39]
	v_mfma_f32_16x16x32_bf16 v[16:19], v[144:147], v[192:195], v[16:19]
	v_mfma_f32_16x16x32_bf16 v[20:23], v[152:155], v[192:195], v[20:23]
	v_mfma_f32_16x16x32_bf16 v[0:3], v[144:147], v[204:207], v[0:3]
	v_mfma_f32_16x16x32_bf16 v[4:7], v[152:155], v[204:207], v[4:7]
	v_mfma_f32_16x16x32_bf16 v[48:51], v[148:151], v[180:183], v[48:51]
	v_mfma_f32_16x16x32_bf16 v[52:55], v[156:159], v[180:183], v[52:55]
	v_mfma_f32_16x16x32_bf16 v[32:35], v[148:151], v[188:191], v[32:35]
	v_mfma_f32_16x16x32_bf16 v[36:39], v[156:159], v[188:191], v[36:39]
	s_setprio 2
	s_barrier
	v_mfma_f32_16x16x32_bf16 v[16:19], v[148:151], v[200:203], v[16:19]
	v_mfma_f32_16x16x32_bf16 v[20:23], v[156:159], v[200:203], v[20:23]
	v_mfma_f32_16x16x32_bf16 v[0:3], v[148:151], v[208:211], v[0:3]
	v_mfma_f32_16x16x32_bf16 v[4:7], v[156:159], v[208:211], v[4:7]
	s_setprio 2
	s_add_i32 s54, 0, 0x18000
	s_add_i32 s55, 0, 0x1c000
	v_add_u32_e32 v140, s54, v196
	v_add_u32_e32 v156, s55, v196
	ds_read_b128 v[128:131], v140
	ds_read_b128 v[132:135], v140 offset:1024
	ds_read_b128 v[136:139], v140 offset:2048
	ds_read_b128 v[140:143], v140 offset:3072
	ds_read_b128 v[144:147], v156
	ds_read_b128 v[148:151], v156 offset:1024
	ds_read_b128 v[152:155], v156 offset:2048
	ds_read_b128 v[156:159], v156 offset:3072
	s_add_u32 s24, s28, 0xb0000
	s_addc_u32 s25, s29, 0
	s_mov_b32 m0, s38
	v_lshl_add_u64 v[220:221], s[24:25], 0, v[164:165]
	ds_read_b128 v[160:163], v199 offset:32768
	ds_read_b128 v[180:183], v199 offset:33792
	ds_read_b128 v[184:187], v199 offset:34816
	ds_read_b128 v[188:191], v199 offset:35840
	ds_read_b128 v[192:195], v199 offset:36864
	ds_read_b128 v[200:203], v199 offset:37888
	ds_read_b128 v[204:207], v199 offset:38912
	ds_read_b128 v[208:211], v199 offset:39936
	global_load_lds_dwordx4 v[220:221], off
	s_mov_b32 m0, s39
	v_lshl_add_u64 v[220:221], s[24:25], 0, v[168:169]
	global_load_lds_dwordx4 v[220:221], off
	s_waitcnt vmcnt(8)
	s_waitcnt lgkmcnt(0)
	s_barrier
	s_setprio 1
	s_waitcnt lgkmcnt(0)
	v_mfma_f32_16x16x32_bf16 v[124:127], v[128:131], v[160:163], v[124:127]
	v_mfma_f32_16x16x32_bf16 v[120:123], v[136:139], v[160:163], v[120:123]
	v_mfma_f32_16x16x32_bf16 v[116:119], v[128:131], v[184:187], v[116:119]
	v_mfma_f32_16x16x32_bf16 v[108:111], v[136:139], v[184:187], v[108:111]
	v_mfma_f32_16x16x32_bf16 v[88:91], v[128:131], v[192:195], v[88:91]
	v_mfma_f32_16x16x32_bf16 v[100:103], v[136:139], v[192:195], v[100:103]
	v_mfma_f32_16x16x32_bf16 v[72:75], v[128:131], v[204:207], v[72:75]
	v_mfma_f32_16x16x32_bf16 v[76:79], v[136:139], v[204:207], v[76:79]
	v_mfma_f32_16x16x32_bf16 v[124:127], v[132:135], v[180:183], v[124:127]
	v_mfma_f32_16x16x32_bf16 v[120:123], v[140:143], v[180:183], v[120:123]
	v_mfma_f32_16x16x32_bf16 v[116:119], v[132:135], v[188:191], v[116:119]
	v_mfma_f32_16x16x32_bf16 v[108:111], v[140:143], v[188:191], v[108:111]
	v_mfma_f32_16x16x32_bf16 v[88:91], v[132:135], v[200:203], v[88:91]
	v_mfma_f32_16x16x32_bf16 v[100:103], v[140:143], v[200:203], v[100:103]
	v_mfma_f32_16x16x32_bf16 v[72:75], v[132:135], v[208:211], v[72:75]
	v_mfma_f32_16x16x32_bf16 v[76:79], v[140:143], v[208:211], v[76:79]
	s_setprio 0
	s_setprio 1
	v_mfma_f32_16x16x32_bf16 v[112:115], v[144:147], v[160:163], v[112:115]
	v_mfma_f32_16x16x32_bf16 v[104:107], v[152:155], v[160:163], v[104:107]
	v_mfma_f32_16x16x32_bf16 v[96:99], v[144:147], v[184:187], v[96:99]
	v_mfma_f32_16x16x32_bf16 v[92:95], v[152:155], v[184:187], v[92:95]
	v_mfma_f32_16x16x32_bf16 v[80:83], v[144:147], v[192:195], v[80:83]
	v_mfma_f32_16x16x32_bf16 v[84:87], v[152:155], v[192:195], v[84:87]
	v_mfma_f32_16x16x32_bf16 v[64:67], v[144:147], v[204:207], v[64:67]
	v_mfma_f32_16x16x32_bf16 v[68:71], v[152:155], v[204:207], v[68:71]
	v_mfma_f32_16x16x32_bf16 v[112:115], v[148:151], v[180:183], v[112:115]
	v_mfma_f32_16x16x32_bf16 v[104:107], v[156:159], v[180:183], v[104:107]
	v_mfma_f32_16x16x32_bf16 v[96:99], v[148:151], v[188:191], v[96:99]
	v_mfma_f32_16x16x32_bf16 v[92:95], v[156:159], v[188:191], v[92:95]
	s_setprio 2
	s_barrier
	v_mfma_f32_16x16x32_bf16 v[80:83], v[148:151], v[200:203], v[80:83]
	v_mfma_f32_16x16x32_bf16 v[84:87], v[156:159], v[200:203], v[84:87]
	v_mfma_f32_16x16x32_bf16 v[64:67], v[148:151], v[208:211], v[64:67]
	v_mfma_f32_16x16x32_bf16 v[68:71], v[156:159], v[208:211], v[68:71]
	s_setprio 2
	s_add_i32 s24, s54, s35
	v_lshl_add_u64 v[212:213], v[212:213], 0, s[16:17]
	s_mov_b32 m0, s24
	ds_read_b128 v[160:163], v199 offset:49152
	ds_read_b128 v[180:183], v199 offset:50176
	ds_read_b128 v[184:187], v199 offset:51200
	ds_read_b128 v[188:191], v199 offset:52224
	ds_read_b128 v[192:195], v199 offset:53248
	ds_read_b128 v[200:203], v199 offset:54272
	ds_read_b128 v[204:207], v199 offset:55296
	ds_read_b128 v[208:211], v199 offset:56320
	global_load_lds_dwordx4 v[212:213], off
	s_add_i32 m0, s24, 0x2000
	s_add_u32 s24, s26, 0xb0080
	v_lshl_add_u64 v[212:213], v[214:215], 0, s[16:17]
	s_addc_u32 s25, s27, 0
	s_add_i32 s26, s55, s35
	global_load_lds_dwordx4 v[212:213], off
	s_mov_b32 m0, s26
	v_lshl_add_u64 v[212:213], s[24:25], 0, v[166:167]
	global_load_lds_dwordx4 v[212:213], off
	s_add_i32 m0, s26, 0x2000
	v_lshl_add_u64 v[212:213], s[24:25], 0, v[170:171]
	global_load_lds_dwordx4 v[212:213], off
	s_mov_b32 m0, s41
	v_lshl_add_u64 v[212:213], v[216:217], 0, s[16:17]
	global_load_lds_dwordx4 v[212:213], off
	s_mov_b32 m0, s42
	v_lshl_add_u64 v[212:213], v[218:219], 0, s[16:17]
	global_load_lds_dwordx4 v[212:213], off
	s_waitcnt vmcnt(8)
	s_waitcnt lgkmcnt(0)
	s_barrier
	s_setprio 1
	s_waitcnt lgkmcnt(0)
	v_mfma_f32_16x16x32_bf16 v[56:59], v[128:131], v[160:163], v[56:59]
	v_mfma_f32_16x16x32_bf16 v[60:63], v[136:139], v[160:163], v[60:63]
	v_mfma_f32_16x16x32_bf16 v[40:43], v[128:131], v[184:187], v[40:43]
	v_mfma_f32_16x16x32_bf16 v[44:47], v[136:139], v[184:187], v[44:47]
	v_mfma_f32_16x16x32_bf16 v[24:27], v[128:131], v[192:195], v[24:27]
	v_mfma_f32_16x16x32_bf16 v[28:31], v[136:139], v[192:195], v[28:31]
	v_mfma_f32_16x16x32_bf16 v[8:11], v[128:131], v[204:207], v[8:11]
	v_mfma_f32_16x16x32_bf16 v[12:15], v[136:139], v[204:207], v[12:15]
	v_mfma_f32_16x16x32_bf16 v[56:59], v[132:135], v[180:183], v[56:59]
	v_mfma_f32_16x16x32_bf16 v[60:63], v[140:143], v[180:183], v[60:63]
	v_mfma_f32_16x16x32_bf16 v[40:43], v[132:135], v[188:191], v[40:43]
	v_mfma_f32_16x16x32_bf16 v[44:47], v[140:143], v[188:191], v[44:47]
	v_mfma_f32_16x16x32_bf16 v[24:27], v[132:135], v[200:203], v[24:27]
	v_mfma_f32_16x16x32_bf16 v[28:31], v[140:143], v[200:203], v[28:31]
	v_mfma_f32_16x16x32_bf16 v[8:11], v[132:135], v[208:211], v[8:11]
	v_mfma_f32_16x16x32_bf16 v[12:15], v[140:143], v[208:211], v[12:15]
	s_setprio 0
	s_setprio 1
	v_mfma_f32_16x16x32_bf16 v[48:51], v[144:147], v[160:163], v[48:51]
	v_mfma_f32_16x16x32_bf16 v[52:55], v[152:155], v[160:163], v[52:55]
	v_mfma_f32_16x16x32_bf16 v[32:35], v[144:147], v[184:187], v[32:35]
	v_mfma_f32_16x16x32_bf16 v[36:39], v[152:155], v[184:187], v[36:39]
	v_mfma_f32_16x16x32_bf16 v[16:19], v[144:147], v[192:195], v[16:19]
	v_mfma_f32_16x16x32_bf16 v[20:23], v[152:155], v[192:195], v[20:23]
	v_mfma_f32_16x16x32_bf16 v[0:3], v[144:147], v[204:207], v[0:3]
	v_mfma_f32_16x16x32_bf16 v[4:7], v[152:155], v[204:207], v[4:7]
	v_mfma_f32_16x16x32_bf16 v[48:51], v[148:151], v[180:183], v[48:51]
	v_mfma_f32_16x16x32_bf16 v[52:55], v[156:159], v[180:183], v[52:55]
	v_mfma_f32_16x16x32_bf16 v[32:35], v[148:151], v[188:191], v[32:35]
	v_mfma_f32_16x16x32_bf16 v[36:39], v[156:159], v[188:191], v[36:39]
	s_setprio 2
	s_barrier
	v_mfma_f32_16x16x32_bf16 v[16:19], v[148:151], v[200:203], v[16:19]
	v_mfma_f32_16x16x32_bf16 v[20:23], v[156:159], v[200:203], v[20:23]
	v_mfma_f32_16x16x32_bf16 v[0:3], v[148:151], v[208:211], v[0:3]
	v_mfma_f32_16x16x32_bf16 v[4:7], v[156:159], v[208:211], v[4:7]
	s_setprio 0
	s_add_i32 s53, s53, 2
	s_add_u32 s51, s51, 0x100
	s_addc_u32 s52, s52, 0
	s_cmp_gt_u32 s53, 41
	s_mov_b64 s[24:25], s[4:5]
	s_cbranch_scc0 .LBB0_1310
